# row passes: loop-invariant gain vectors read from LDS (filled once per wave) so in-row waits no longer include the row's global stores
# speedup vs baseline: 1.0205x; 1.0197x over previous
; DI unsigned pk2(float lo, float hi) { return f2bf(lo) | (f2bf(hi) << 16); }
; template <int MODE, bool FIRST, bool LAST>
; DI void phase_rowpass(const float* xin, const bf16_t* M, const float* gpost, float* outf, bf16_t* HB, bf16_t* XN, const float* gnext, int gw, int NGW, int lane) {
;     int row = gw; if (row >= T_) return;
;     HRow<FIRST> hc; u32x2 mw[8];
;     { const u32x2* mr = (const u32x2*)(M + (size_t)row * D_) + lane;
; #pragma unroll
;       for (int j = 0; j < 8; ++j) { if constexpr (FIRST) hc.f[j] = ((const f32x4*)(xin + (size_t)row * D_) + lane)[64 * j]; else hc.f[j] = ((const u32x2*)(HB + (size_t)row * D_) + lane)[64 * j]; mw[j] = mr[64 * j]; } }
;     ...
;         for (int j = 0; j < 8; ++j) { const f32x4 gv = ((const f32x4*)gpost)[lane + 64 * j]; hv[j] = hv[j] + mv[j] * rs * gv;
;             if constexpr (LAST) ((f32x4*)(outf + (size_t)row * D_) + lane)[64 * j] = hv[j];
;             else { u32x2 w; w.x = pk2(hv[j][0], hv[j][1]); w.y = pk2(hv[j][2], hv[j][3]); ((u32x2*)(HB + (size_t)row * D_) + lane)[64 * j] = w; }
;             s2 += (hv[j][0] * hv[j][0] + hv[j][1] * hv[j][1]) + (hv[j][2] * hv[j][2] + hv[j][3] * hv[j][3]); }
;         if (MODE == 1) { const float r2 = rsqrtf(wave_sum(s2) * (1.f / D_) + EPS); u32x2* o = (u32x2*)(XN + (size_t)row * D_) + lane;
; #pragma unroll
;             for (int j = 0; j < 8; ++j) { const f32x4 gv = ((const f32x4*)gnext)[lane + 64 * j]; u32x2 w; w.x = pk2(hv[j][0] * r2 * gv[0], hv[j][1] * r2 * gv[1]); w.y = pk2(hv[j][2] * r2 * gv[2], hv[j][3] * r2 * gv[3]); o[64 * j] = w; } }
.LBB0_432:
	s_cmp_lt_i32 s62, 5
	s_cselect_b64 s[8:9], -1, 0
	s_and_b64 s[6:7], s[8:9], s[6:7]
	s_andn2_b64 vcc, exec, s[6:7]
	s_cbranch_vccnz .LBB0_438
	v_mov_b32_e32 v2, v1
	s_lshl_b32 s3, s2, 3
	v_readfirstlane_b32 s8, v2
	s_ashr_i32 s8, s8, 6
	s_add_i32 s12, s8, s3
	s_mov_b64 s[16:17], s[0:1]
	s_cmpk_gt_i32 s12, 0x3fff
	s_cbranch_scc1 .LBB0_438
	s_load_dwordx2 s[18:19], s[16:17], 0xc8
	s_load_dwordx2 s[20:21], s[16:17], 0x0
	s_load_dwordx4 s[8:11], s[16:17], 0x18
	s_ashr_i32 s13, s12, 31
	s_lshl_b32 s14, s74, 3
	s_lshl_b64 s[16:17], s[12:13], 12
	v_and_b32_e32 v6, 63, v2
	s_waitcnt lgkmcnt(0)
	s_add_u32 s16, s18, s16
	v_lshlrev_b32_e32 v66, 3, v6
	v_mov_b32_e32 v67, 0
	s_addc_u32 s17, s19, s17
	v_lshl_add_u64 v[2:3], s[16:17], 0, v[66:67]
	s_mov_b64 s[22:23], 0x14dcc000
	v_lshl_add_u64 v[4:5], v[2:3], 0, s[22:23]
	s_lshl_b64 s[22:23], s[12:13], 13
	s_add_u32 s22, s20, s22
	s_mov_b32 s3, 0x14dcc000
	s_addc_u32 s23, s21, s23
	v_lshlrev_b32_e32 v6, 4, v6
	v_mov_b32_e32 v7, v67
	v_add_co_u32_e32 v2, vcc, s3, v2
	v_lshl_add_u64 v[8:9], s[22:23], 0, v[6:7]
	s_nop 0
	v_addc_co_u32_e32 v3, vcc, 0, v3, vcc
	s_movk_i32 s3, 0x1000
	v_add_co_u32_e32 v8, vcc, s3, v8
	global_load_dwordx4 v[62:65], v6, s[22:23]
	global_load_dwordx4 v[58:61], v6, s[22:23] offset:1024
	global_load_dwordx4 v[54:57], v6, s[22:23] offset:2048
	global_load_dwordx4 v[50:53], v6, s[22:23] offset:3072
	v_addc_co_u32_e32 v9, vcc, 0, v9, vcc
	global_load_dwordx2 v[120:121], v[4:5], off offset:512
	global_load_dwordx2 v[118:119], v[4:5], off offset:1024
	global_load_dwordx2 v[114:115], v[4:5], off offset:1536
	global_load_dwordx2 v[112:113], v[4:5], off offset:2048
	global_load_dwordx4 v[46:49], v[8:9], off
	global_load_dwordx4 v[42:45], v[8:9], off offset:1024
	global_load_dwordx4 v[38:41], v[8:9], off offset:2048
	global_load_dwordx4 v[34:37], v[8:9], off offset:3072
	global_load_dwordx2 v[124:125], v[2:3], off
	global_load_dwordx2 v[110:111], v[4:5], off offset:2560
	global_load_dwordx2 v[108:109], v[4:5], off offset:3072
	global_load_dwordx2 v[106:107], v[4:5], off offset:3584
	v_mbcnt_lo_u32_b32 v2, -1, 0
	v_mbcnt_hi_u32_b32 v2, -1, v2
	v_and_b32_e32 v3, 64, v2
	v_add_u32_e32 v3, 64, v3
	v_xor_b32_e32 v4, 1, v2
	v_cmp_lt_i32_e32 vcc, v4, v3
	s_add_i32 s22, s12, s14
	v_mov_b32_e32 v5, v67
	v_cndmask_b32_e32 v4, v2, v4, vcc
	v_lshlrev_b32_e32 v136, 2, v4
	v_xor_b32_e32 v4, 2, v2
	v_cmp_lt_i32_e32 vcc, v4, v3
	v_or_b32_e32 v8, 0x1800, v6
	v_mov_b32_e32 v9, v67
	v_cndmask_b32_e32 v4, v2, v4, vcc
	v_lshlrev_b32_e32 v137, 2, v4
	v_xor_b32_e32 v4, 4, v2
	v_cmp_lt_i32_e32 vcc, v4, v3
	v_or_b32_e32 v10, 0x1c00, v6
	v_mov_b32_e32 v11, v67
	v_cndmask_b32_e32 v4, v2, v4, vcc
	v_lshlrev_b32_e32 v138, 2, v4
	v_xor_b32_e32 v4, 8, v2
	v_cmp_lt_i32_e32 vcc, v4, v3
	s_ashr_i32 s15, s14, 31
	s_ashr_i32 s23, s22, 31
	v_cndmask_b32_e32 v4, v2, v4, vcc
	v_lshlrev_b32_e32 v139, 2, v4
	v_xor_b32_e32 v4, 16, v2
	v_cmp_lt_i32_e32 vcc, v4, v3
	v_lshl_add_u64 v[68:69], s[8:9], 0, v[6:7]
	v_lshl_add_u64 v[74:75], s[8:9], 0, v[8:9]
	v_cndmask_b32_e32 v4, v2, v4, vcc
	v_lshlrev_b32_e32 v140, 2, v4
	v_xor_b32_e32 v4, 32, v2
	v_cmp_lt_i32_e32 vcc, v4, v3
	v_mov_b32_e32 v3, v67
	v_lshl_add_u64 v[76:77], s[8:9], 0, v[10:11]
	v_cndmask_b32_e32 v2, v2, v4, vcc
	v_lshlrev_b32_e32 v141, 2, v2
	v_or_b32_e32 v2, 0x1000, v6
	v_or_b32_e32 v4, 0x1400, v6
	v_lshl_add_u64 v[70:71], s[8:9], 0, v[2:3]
	v_lshl_add_u64 v[72:73], s[8:9], 0, v[4:5]
	v_lshl_add_u64 v[78:79], s[10:11], 0, v[6:7]
	v_lshl_add_u64 v[80:81], s[10:11], 0, v[2:3]
	v_lshl_add_u64 v[82:83], s[10:11], 0, v[4:5]
	v_lshl_add_u64 v[84:85], s[10:11], 0, v[8:9]
	v_lshl_add_u64 v[86:87], s[10:11], 0, v[10:11]
	s_lshl_b64 s[8:9], s[14:15], 12
	s_lshl_b64 s[10:11], s[22:23], 13
	s_add_u32 s10, s20, s10
	s_addc_u32 s11, s21, s11
	v_lshl_add_u64 v[2:3], s[10:11], 0, v[6:7]
	s_mov_b64 s[10:11], 0x1000
	v_lshl_add_u64 v[88:89], v[2:3], 0, s[10:11]
	s_lshl_b64 s[10:11], s[14:15], 13
	s_lshl_b64 s[20:21], s[22:23], 12
	s_add_u32 s18, s18, s20
	s_addc_u32 s19, s19, s21
	v_mov_b32_e32 v142, 0x358637bd
	s_mov_b32 s3, 0x800000
	s_movk_i32 s13, 0x7fff
	s_mov_b32 s15, 0xc000
	s_mov_b32 s22, 0x10dcc000
	v_mov_b32_e32 v143, 1
	v_and_b32_e32 v162, 63, v1
	v_lshlrev_b32_e32 v162, 4, v162
	global_load_dwordx4 v[164:167], v[68:69], off
	global_load_dwordx4 v[168:171], v[68:69], off offset:1024
	global_load_dwordx4 v[172:175], v[68:69], off offset:2048
	global_load_dwordx4 v[176:179], v[68:69], off offset:3072
	global_load_dwordx4 v[180:183], v[70:71], off
	global_load_dwordx4 v[184:187], v[72:73], off
	global_load_dwordx4 v[188:191], v[74:75], off
	global_load_dwordx4 v[192:195], v[76:77], off
	global_load_dwordx4 v[196:199], v[78:79], off
	global_load_dwordx4 v[200:203], v[78:79], off offset:1024
	global_load_dwordx4 v[204:207], v[78:79], off offset:2048
	global_load_dwordx4 v[208:211], v[78:79], off offset:3072
	global_load_dwordx4 v[212:215], v[80:81], off
	global_load_dwordx4 v[216:219], v[82:83], off
	global_load_dwordx4 v[220:223], v[84:85], off
	global_load_dwordx4 v[224:227], v[86:87], off
	s_waitcnt vmcnt(0)
	ds_write_b128 v162, v[164:167] offset:0
	ds_write_b128 v162, v[168:171] offset:1024
	ds_write_b128 v162, v[172:175] offset:2048
	ds_write_b128 v162, v[176:179] offset:3072
	ds_write_b128 v162, v[180:183] offset:4096
	ds_write_b128 v162, v[184:187] offset:5120
	ds_write_b128 v162, v[188:191] offset:6144
	ds_write_b128 v162, v[192:195] offset:7168
	ds_write_b128 v162, v[196:199] offset:8192
	ds_write_b128 v162, v[200:203] offset:9216
	ds_write_b128 v162, v[204:207] offset:10240
	ds_write_b128 v162, v[208:211] offset:11264
	ds_write_b128 v162, v[212:215] offset:12288
	ds_write_b128 v162, v[216:219] offset:13312
	ds_write_b128 v162, v[220:223] offset:14336
	ds_write_b128 v162, v[224:227] offset:15360
	s_waitcnt lgkmcnt(0)
	s_branch .LBB0_436
; DI unsigned pk2(float lo, float hi) { return f2bf(lo) | (f2bf(hi) << 16); }
; DI float lo_f(unsigned w) { return __uint_as_float(w << 16); }
; DI float hi_f(unsigned w) { return __uint_as_float(w & 0xffff0000u); }
; template <int MODE, bool FIRST, bool LAST>
; DI void phase_rowpass(const float* xin, const bf16_t* M, const float* gpost, float* outf, bf16_t* HB, bf16_t* XN, const float* gnext, int gw, int NGW, int lane) {
;     ...
;         f32x4 hv[8], mv[8]; float ss = 0.f;
; #pragma unroll
;         for (int j = 0; j < 8; ++j) { const u32x2 w = mw[j]; mv[j] = (f32x4){lo_f(w.x), hi_f(w.x), lo_f(w.y), hi_f(w.y)};
;             if constexpr (FIRST) hv[j] = hc.f[j]; else { const u32x2 hw = hc.f[j]; hv[j] = (f32x4){lo_f(hw.x), hi_f(hw.x), lo_f(hw.y), hi_f(hw.y)}; }
;             ss += (mv[j][0] * mv[j][0] + mv[j][1] * mv[j][1]) + (mv[j][2] * mv[j][2] + mv[j][3] * mv[j][3]); }
;         const float rs = rsqrtf(wave_sum(ss) * (1.f / D_) + EPS);
;         float s2 = 0.f;
; #pragma unroll
;         for (int j = 0; j < 8; ++j) { const f32x4 gv = ((const f32x4*)gpost)[lane + 64 * j]; hv[j] = hv[j] + mv[j] * rs * gv;
;             if constexpr (LAST) ((f32x4*)(outf + (size_t)row * D_) + lane)[64 * j] = hv[j];
;             else { u32x2 w; w.x = pk2(hv[j][0], hv[j][1]); w.y = pk2(hv[j][2], hv[j][3]); ((u32x2*)(HB + (size_t)row * D_) + lane)[64 * j] = w; }
.LBB0_435:
	ds_read_b128 v[144:147], v162 offset:0
	s_waitcnt vmcnt(0) lgkmcnt(0)
	v_and_b32_e32 v151, 0xffff0000, v124
	v_and_b32_e32 v150, 0xffff0000, v120
	v_and_b32_e32 v155, 0xffff0000, v125
	v_and_b32_e32 v154, 0xffff0000, v121
	v_and_b32_e32 v135, 0xffff0000, v119
	v_and_b32_e32 v134, 0xffff0000, v118
	v_lshlrev_b32_e32 v149, 16, v124
	v_lshlrev_b32_e32 v148, 16, v120
	v_lshlrev_b32_e32 v153, 16, v125
	v_lshlrev_b32_e32 v152, 16, v121
	v_pk_mul_f32 v[116:117], v[150:151], v[150:151]
	v_pk_mul_f32 v[120:121], v[154:155], v[154:155]
	v_lshlrev_b32_e32 v133, 16, v119
	v_lshlrev_b32_e32 v132, 16, v118
	v_pk_mul_f32 v[118:119], v[134:135], v[134:135]
	v_pk_fma_f32 v[116:117], v[148:149], v[148:149], v[116:117]
	v_pk_fma_f32 v[120:121], v[152:153], v[152:153], v[120:121]
	v_pk_fma_f32 v[118:119], v[132:133], v[132:133], v[118:119]
	v_pk_add_f32 v[116:117], v[116:117], v[120:121]
	v_pk_add_f32 v[120:121], v[118:119], v[118:119] op_sel_hi:[0,1]
	v_lshlrev_b32_e32 v128, 16, v114
	v_and_b32_e32 v129, 0xffff0000, v114
	v_lshlrev_b32_e32 v130, 16, v115
	v_lshlrev_b32_e32 v118, 16, v112
	v_mul_f32_e32 v119, v128, v128
	v_mul_f32_e32 v125, v129, v129
	v_and_b32_e32 v131, 0xffff0000, v115
	v_mul_f32_e32 v114, v130, v130
	v_mov_b32_e32 v124, v118
	v_pk_add_f32 v[116:117], v[116:117], v[116:117] op_sel_hi:[0,1]
	v_pk_fma_f32 v[114:115], v[130:131], v[130:131], v[114:115] op_sel_hi:[1,1,0]
	v_and_b32_e32 v160, 0xffff0000, v112
	v_lshlrev_b32_e32 v122, 16, v113
	v_and_b32_e32 v123, 0xffff0000, v113
	v_pk_add_f32 v[124:125], v[118:119], v[124:125]
	v_mul_f32_e32 v114, v160, v160
	v_mul_f32_e32 v120, v122, v122
	v_mul_f32_e32 v116, v123, v123
	v_mul_f32_e32 v112, v118, v118
	v_mov_b32_e32 v113, v125
	v_pk_add_f32 v[112:113], v[112:113], v[114:115]
	v_pk_add_f32 v[114:115], v[120:121], v[116:117]
	v_lshlrev_b32_e32 v124, 16, v108
	v_pk_add_f32 v[112:113], v[112:113], v[114:115]
	v_and_b32_e32 v115, 0xffff0000, v111
	v_and_b32_e32 v114, 0xffff0000, v110
	v_pk_add_f32 v[116:117], v[112:113], v[112:113] op_sel_hi:[0,1]
	v_lshlrev_b32_e32 v113, 16, v111
	v_lshlrev_b32_e32 v112, 16, v110
	v_pk_mul_f32 v[110:111], v[114:115], v[114:115]
	v_and_b32_e32 v125, 0xffff0000, v108
	v_pk_fma_f32 v[110:111], v[112:113], v[112:113], v[110:111]
	v_lshlrev_b32_e32 v126, 16, v109
	v_pk_add_f32 v[120:121], v[110:111], v[110:111] op_sel_hi:[0,1]
	v_lshlrev_b32_e32 v110, 16, v106
	v_mul_f32_e32 v111, v124, v124
	v_mul_f32_e32 v157, v125, v125
	v_and_b32_e32 v127, 0xffff0000, v109
	v_mul_f32_e32 v108, v126, v126
	v_mov_b32_e32 v156, v110
	v_pk_fma_f32 v[158:159], v[126:127], v[126:127], v[108:109] op_sel_hi:[1,1,0]
	v_and_b32_e32 v161, 0xffff0000, v106
	v_lshlrev_b32_e32 v108, 16, v107
	v_and_b32_e32 v109, 0xffff0000, v107
	v_pk_add_f32 v[156:157], v[110:111], v[156:157]
	v_mul_f32_e32 v158, v161, v161
	v_mul_f32_e32 v120, v108, v108
	v_mul_f32_e32 v116, v109, v109
	v_mul_f32_e32 v106, v110, v110
	v_mov_b32_e32 v107, v157
	v_pk_add_f32 v[106:107], v[106:107], v[158:159]
	v_pk_add_f32 v[116:117], v[120:121], v[116:117]
	v_mov_b32_e32 v156, v149
	v_pk_add_f32 v[106:107], v[106:107], v[116:117]
	v_mov_b32_e32 v157, v151
	v_add_f32_e32 v106, v106, v107
	ds_bpermute_b32 v107, v136, v106
	v_mov_b32_e32 v116, v153
	v_mov_b32_e32 v117, v155
	v_mov_b32_e32 v149, v150
	v_mov_b32_e32 v153, v154
	s_waitcnt lgkmcnt(0)
	v_add_f32_e32 v106, v106, v107
	ds_bpermute_b32 v107, v137, v106
	v_lshl_add_u64 v[88:89], v[88:89], 0, s[10:11]
	s_waitcnt lgkmcnt(0)
	v_add_f32_e32 v106, v106, v107
	ds_bpermute_b32 v107, v138, v106
	s_waitcnt lgkmcnt(0)
	v_add_f32_e32 v106, v106, v107
	ds_bpermute_b32 v107, v139, v106
	s_waitcnt lgkmcnt(0)
	v_add_f32_e32 v106, v106, v107
	ds_bpermute_b32 v107, v140, v106
	s_waitcnt lgkmcnt(0)
	v_add_f32_e32 v106, v106, v107
	ds_bpermute_b32 v107, v141, v106
	s_waitcnt lgkmcnt(0)
	v_add_f32_e32 v106, v106, v107
	v_fmamk_f32 v106, v106, 0x3a000000, v142
	v_mul_f32_e32 v107, 0x4b800000, v106
	v_cmp_gt_f32_e32 vcc, s3, v106
	s_nop 1
	v_cndmask_b32_e32 v106, v106, v107, vcc
	v_rsq_f32_e32 v106, v106
	s_nop 0
	v_mul_f32_e32 v107, 0x45800000, v106
	v_cndmask_b32_e32 v120, v106, v107, vcc
	v_pk_mul_f32 v[156:157], v[156:157], v[120:121] op_sel_hi:[1,0]
	v_pk_mul_f32 v[116:117], v[116:117], v[120:121] op_sel_hi:[1,0]
	v_pk_fma_f32 v[62:63], v[144:145], v[156:157], v[62:63]
	v_pk_fma_f32 v[64:65], v[146:147], v[116:117], v[64:65]
	v_and_b32_sdwa v119, v63, v143 dst_sel:DWORD dst_unused:UNUSED_PAD src0_sel:WORD_1 src1_sel:DWORD
	v_and_b32_sdwa v116, v62, v143 dst_sel:DWORD dst_unused:UNUSED_PAD src0_sel:WORD_1 src1_sel:DWORD
	v_and_b32_sdwa v117, v65, v143 dst_sel:DWORD dst_unused:UNUSED_PAD src0_sel:WORD_1 src1_sel:DWORD
	v_add3_u32 v119, v63, v119, s13
	v_lshl_add_u64 v[106:107], s[16:17], 0, v[66:67]
	v_and_b32_sdwa v111, v64, v143 dst_sel:DWORD dst_unused:UNUSED_PAD src0_sel:WORD_1 src1_sel:DWORD
	v_add3_u32 v116, v62, v116, s13
	v_add3_u32 v117, v65, v117, s13
	v_and_b32_e32 v119, 0xffff0000, v119
	v_add3_u32 v111, v64, v111, s13
	v_and_b32_e32 v117, 0xffff0000, v117
	v_or_b32_sdwa v144, v119, v116 dst_sel:DWORD dst_unused:UNUSED_PAD src0_sel:DWORD src1_sel:WORD_1
	v_add_co_u32_e32 v116, vcc, s15, v106
	v_or_b32_sdwa v145, v117, v111 dst_sel:DWORD dst_unused:UNUSED_PAD src0_sel:DWORD src1_sel:WORD_1
	s_nop 0
	v_addc_co_u32_e32 v117, vcc, 0, v107, vcc
	global_store_dwordx2 v[116:117], v[144:145], off
	s_nop 0
	ds_read_b128 v[144:147], v162 offset:1024
	v_pk_mul_f32 v[148:149], v[148:149], v[120:121] op_sel_hi:[1,0]
	v_pk_mul_f32 v[150:151], v[152:153], v[120:121] op_sel_hi:[1,0]
	s_add_u32 s16, s16, s8
	s_addc_u32 s17, s17, s9
	s_add_u32 s18, s18, s8
	s_addc_u32 s19, s19, s9
	s_waitcnt lgkmcnt(0)
; DI unsigned pk2(float lo, float hi) { return f2bf(lo) | (f2bf(hi) << 16); }
; template <int MODE, bool FIRST, bool LAST>
; DI void phase_rowpass(const float* xin, const bf16_t* M, const float* gpost, float* outf, bf16_t* HB, bf16_t* XN, const float* gnext, int gw, int NGW, int lane) {
;     ...
;         for (int j = 0; j < 8; ++j) { const f32x4 gv = ((const f32x4*)gpost)[lane + 64 * j]; hv[j] = hv[j] + mv[j] * rs * gv;
;             if constexpr (LAST) ((f32x4*)(outf + (size_t)row * D_) + lane)[64 * j] = hv[j];
;             else { u32x2 w; w.x = pk2(hv[j][0], hv[j][1]); w.y = pk2(hv[j][2], hv[j][3]); ((u32x2*)(HB + (size_t)row * D_) + lane)[64 * j] = w; }
	v_pk_fma_f32 v[60:61], v[146:147], v[150:151], v[60:61]
	v_pk_fma_f32 v[58:59], v[144:145], v[148:149], v[58:59]
	v_and_b32_sdwa v121, v61, v143 dst_sel:DWORD dst_unused:UNUSED_PAD src0_sel:WORD_1 src1_sel:DWORD
	v_and_b32_sdwa v144, v59, v143 dst_sel:DWORD dst_unused:UNUSED_PAD src0_sel:WORD_1 src1_sel:DWORD
	v_and_b32_sdwa v111, v60, v143 dst_sel:DWORD dst_unused:UNUSED_PAD src0_sel:WORD_1 src1_sel:DWORD
	v_and_b32_sdwa v119, v58, v143 dst_sel:DWORD dst_unused:UNUSED_PAD src0_sel:WORD_1 src1_sel:DWORD
	v_add3_u32 v121, v61, v121, s13
	v_add3_u32 v144, v59, v144, s13
	v_add3_u32 v119, v58, v119, s13
	v_add3_u32 v111, v60, v111, s13
	v_and_b32_e32 v121, 0xffff0000, v121
	v_and_b32_e32 v144, 0xffff0000, v144
	v_or_b32_sdwa v145, v121, v111 dst_sel:DWORD dst_unused:UNUSED_PAD src0_sel:DWORD src1_sel:WORD_1
	v_or_b32_sdwa v144, v144, v119 dst_sel:DWORD dst_unused:UNUSED_PAD src0_sel:DWORD src1_sel:WORD_1
	global_store_dwordx2 v[116:117], v[144:145], off offset:512
	s_nop 0
	ds_read_b128 v[144:147], v162 offset:2048
	v_mov_b32_e32 v148, v132
	v_mov_b32_e32 v149, v134
	v_mov_b32_e32 v134, v133
	v_pk_mul_f32 v[132:133], v[120:121], v[148:149] op_sel_hi:[0,1]
	v_pk_mul_f32 v[134:135], v[120:121], v[134:135] op_sel_hi:[0,1]
	s_waitcnt lgkmcnt(0)
	v_pk_fma_f32 v[56:57], v[146:147], v[134:135], v[56:57]
	v_pk_fma_f32 v[54:55], v[144:145], v[132:133], v[54:55]
	v_and_b32_sdwa v121, v57, v143 dst_sel:DWORD dst_unused:UNUSED_PAD src0_sel:WORD_1 src1_sel:DWORD
	v_and_b32_sdwa v132, v55, v143 dst_sel:DWORD dst_unused:UNUSED_PAD src0_sel:WORD_1 src1_sel:DWORD
	v_and_b32_sdwa v111, v56, v143 dst_sel:DWORD dst_unused:UNUSED_PAD src0_sel:WORD_1 src1_sel:DWORD
	v_and_b32_sdwa v119, v54, v143 dst_sel:DWORD dst_unused:UNUSED_PAD src0_sel:WORD_1 src1_sel:DWORD
	v_add3_u32 v121, v57, v121, s13
	v_add3_u32 v132, v55, v132, s13
	v_add3_u32 v119, v54, v119, s13
	v_add3_u32 v111, v56, v111, s13
	v_and_b32_e32 v121, 0xffff0000, v121
	v_and_b32_e32 v132, 0xffff0000, v132
	v_or_b32_sdwa v133, v121, v111 dst_sel:DWORD dst_unused:UNUSED_PAD src0_sel:DWORD src1_sel:WORD_1
	v_or_b32_sdwa v132, v132, v119 dst_sel:DWORD dst_unused:UNUSED_PAD src0_sel:DWORD src1_sel:WORD_1
	global_store_dwordx2 v[116:117], v[132:133], off offset:1024
	s_nop 0
	ds_read_b128 v[132:135], v162 offset:3072
	v_pk_mul_f32 v[128:129], v[128:129], v[120:121] op_sel_hi:[1,0]
	v_pk_mul_f32 v[130:131], v[130:131], v[120:121] op_sel_hi:[1,0]
	s_waitcnt lgkmcnt(0)
	v_pk_fma_f32 v[50:51], v[132:133], v[128:129], v[50:51]
	v_pk_fma_f32 v[52:53], v[134:135], v[130:131], v[52:53]
	v_and_b32_sdwa v128, v51, v143 dst_sel:DWORD dst_unused:UNUSED_PAD src0_sel:WORD_1 src1_sel:DWORD
	v_and_b32_sdwa v121, v53, v143 dst_sel:DWORD dst_unused:UNUSED_PAD src0_sel:WORD_1 src1_sel:DWORD
	v_and_b32_sdwa v111, v52, v143 dst_sel:DWORD dst_unused:UNUSED_PAD src0_sel:WORD_1 src1_sel:DWORD
	v_and_b32_sdwa v119, v50, v143 dst_sel:DWORD dst_unused:UNUSED_PAD src0_sel:WORD_1 src1_sel:DWORD
	v_add3_u32 v121, v53, v121, s13
	v_add3_u32 v128, v51, v128, s13
	v_add3_u32 v119, v50, v119, s13
	v_add3_u32 v111, v52, v111, s13
	v_and_b32_e32 v121, 0xffff0000, v121
	v_and_b32_e32 v128, 0xffff0000, v128
	v_or_b32_sdwa v129, v121, v111 dst_sel:DWORD dst_unused:UNUSED_PAD src0_sel:DWORD src1_sel:WORD_1
	v_or_b32_sdwa v128, v128, v119 dst_sel:DWORD dst_unused:UNUSED_PAD src0_sel:DWORD src1_sel:WORD_1
	global_store_dwordx2 v[116:117], v[128:129], off offset:1536
	s_nop 0
	ds_read_b128 v[128:131], v162 offset:4096
	v_mov_b32_e32 v119, v160
	v_pk_mul_f32 v[118:119], v[118:119], v[120:121] op_sel_hi:[1,0]
	v_pk_mul_f32 v[122:123], v[122:123], v[120:121] op_sel_hi:[1,0]
	s_waitcnt lgkmcnt(0)
	v_pk_fma_f32 v[46:47], v[128:129], v[118:119], v[46:47]
	v_pk_fma_f32 v[48:49], v[130:131], v[122:123], v[48:49]
	v_and_b32_sdwa v121, v47, v143 dst_sel:DWORD dst_unused:UNUSED_PAD src0_sel:WORD_1 src1_sel:DWORD
	v_and_b32_sdwa v119, v49, v143 dst_sel:DWORD dst_unused:UNUSED_PAD src0_sel:WORD_1 src1_sel:DWORD
	v_and_b32_sdwa v111, v48, v143 dst_sel:DWORD dst_unused:UNUSED_PAD src0_sel:WORD_1 src1_sel:DWORD
	v_and_b32_sdwa v118, v46, v143 dst_sel:DWORD dst_unused:UNUSED_PAD src0_sel:WORD_1 src1_sel:DWORD
	v_add3_u32 v119, v49, v119, s13
	v_add3_u32 v121, v47, v121, s13
	v_add3_u32 v118, v46, v118, s13
	v_add3_u32 v111, v48, v111, s13
	v_and_b32_e32 v119, 0xffff0000, v119
	v_and_b32_e32 v121, 0xffff0000, v121
	v_or_b32_sdwa v119, v119, v111 dst_sel:DWORD dst_unused:UNUSED_PAD src0_sel:DWORD src1_sel:WORD_1
	v_or_b32_sdwa v118, v121, v118 dst_sel:DWORD dst_unused:UNUSED_PAD src0_sel:DWORD src1_sel:WORD_1
	global_store_dwordx2 v[116:117], v[118:119], off offset:2048
	s_nop 0
	ds_read_b128 v[128:131], v162 offset:5120
	v_mov_b32_e32 v118, v112
	v_mov_b32_e32 v119, v114
	v_mov_b32_e32 v114, v113
	v_pk_mul_f32 v[112:113], v[120:121], v[118:119] op_sel_hi:[0,1]
	v_pk_mul_f32 v[114:115], v[120:121], v[114:115] op_sel_hi:[0,1]
	v_pk_mul_f32 v[118:119], v[124:125], v[120:121] op_sel_hi:[1,0]
	v_pk_mul_f32 v[122:123], v[126:127], v[120:121] op_sel_hi:[1,0]
	v_pk_mul_f32 v[108:109], v[108:109], v[120:121] op_sel_hi:[1,0]
	v_mov_b32_e32 v124, v58
	v_mov_b32_e32 v125, v60
	s_waitcnt lgkmcnt(0)
; DI unsigned pk2(float lo, float hi) { return f2bf(lo) | (f2bf(hi) << 16); }
; template <int MODE, bool FIRST, bool LAST>
; DI void phase_rowpass(const float* xin, const bf16_t* M, const float* gpost, float* outf, bf16_t* HB, bf16_t* XN, const float* gnext, int gw, int NGW, int lane) {
;     ...
;         for (int j = 0; j < 8; ++j) { const f32x4 gv = ((const f32x4*)gpost)[lane + 64 * j]; hv[j] = hv[j] + mv[j] * rs * gv;
;             if constexpr (LAST) ((f32x4*)(outf + (size_t)row * D_) + lane)[64 * j] = hv[j];
;             else { u32x2 w; w.x = pk2(hv[j][0], hv[j][1]); w.y = pk2(hv[j][2], hv[j][3]); ((u32x2*)(HB + (size_t)row * D_) + lane)[64 * j] = w; }
;             s2 += (hv[j][0] * hv[j][0] + hv[j][1] * hv[j][1]) + (hv[j][2] * hv[j][2] + hv[j][3] * hv[j][3]); }
;         if (MODE == 1) { const float r2 = rsqrtf(wave_sum(s2) * (1.f / D_) + EPS); u32x2* o = (u32x2*)(XN + (size_t)row * D_) + lane;
; #pragma unroll
;             for (int j = 0; j < 8; ++j) { const f32x4 gv = ((const f32x4*)gnext)[lane + 64 * j]; u32x2 w; w.x = pk2(hv[j][0] * r2 * gv[0], hv[j][1] * r2 * gv[1]); w.y = pk2(hv[j][2] * r2 * gv[2], hv[j][3] * r2 * gv[3]); o[64 * j] = w; } }
	v_pk_fma_f32 v[44:45], v[130:131], v[114:115], v[44:45]
	v_pk_fma_f32 v[42:43], v[128:129], v[112:113], v[42:43]
	v_and_b32_sdwa v113, v45, v143 dst_sel:DWORD dst_unused:UNUSED_PAD src0_sel:WORD_1 src1_sel:DWORD
	v_and_b32_sdwa v114, v43, v143 dst_sel:DWORD dst_unused:UNUSED_PAD src0_sel:WORD_1 src1_sel:DWORD
	v_and_b32_sdwa v111, v44, v143 dst_sel:DWORD dst_unused:UNUSED_PAD src0_sel:WORD_1 src1_sel:DWORD
	v_and_b32_sdwa v112, v42, v143 dst_sel:DWORD dst_unused:UNUSED_PAD src0_sel:WORD_1 src1_sel:DWORD
	v_add3_u32 v113, v45, v113, s13
	v_add3_u32 v114, v43, v114, s13
	v_add3_u32 v112, v42, v112, s13
	v_add3_u32 v111, v44, v111, s13
	v_and_b32_e32 v113, 0xffff0000, v113
	v_and_b32_e32 v114, 0xffff0000, v114
	v_or_b32_sdwa v113, v113, v111 dst_sel:DWORD dst_unused:UNUSED_PAD src0_sel:DWORD src1_sel:WORD_1
	v_or_b32_sdwa v112, v114, v112 dst_sel:DWORD dst_unused:UNUSED_PAD src0_sel:DWORD src1_sel:WORD_1
	global_store_dwordx2 v[116:117], v[112:113], off offset:2560
	s_nop 0
	ds_read_b128 v[112:115], v162 offset:6144
	s_waitcnt lgkmcnt(0)
	v_pk_fma_f32 v[40:41], v[122:123], v[114:115], v[40:41]
	v_pk_fma_f32 v[38:39], v[118:119], v[112:113], v[38:39]
	v_and_b32_sdwa v113, v41, v143 dst_sel:DWORD dst_unused:UNUSED_PAD src0_sel:WORD_1 src1_sel:DWORD
	v_and_b32_sdwa v114, v39, v143 dst_sel:DWORD dst_unused:UNUSED_PAD src0_sel:WORD_1 src1_sel:DWORD
	v_and_b32_sdwa v111, v40, v143 dst_sel:DWORD dst_unused:UNUSED_PAD src0_sel:WORD_1 src1_sel:DWORD
	v_and_b32_sdwa v112, v38, v143 dst_sel:DWORD dst_unused:UNUSED_PAD src0_sel:WORD_1 src1_sel:DWORD
	v_add3_u32 v113, v41, v113, s13
	v_add3_u32 v114, v39, v114, s13
	v_add3_u32 v112, v38, v112, s13
	v_add3_u32 v111, v40, v111, s13
	v_and_b32_e32 v113, 0xffff0000, v113
	v_and_b32_e32 v114, 0xffff0000, v114
	v_or_b32_sdwa v113, v113, v111 dst_sel:DWORD dst_unused:UNUSED_PAD src0_sel:DWORD src1_sel:WORD_1
	v_or_b32_sdwa v112, v114, v112 dst_sel:DWORD dst_unused:UNUSED_PAD src0_sel:DWORD src1_sel:WORD_1
	global_store_dwordx2 v[116:117], v[112:113], off offset:3072
	s_nop 0
	ds_read_b128 v[112:115], v162 offset:7168
	v_mov_b32_e32 v111, v161
	v_pk_mul_f32 v[110:111], v[110:111], v[120:121] op_sel_hi:[1,0]
	v_mov_b32_e32 v120, v64
	v_mov_b32_e32 v121, v60
	v_mov_b32_e32 v119, v58
	v_mov_b32_e32 v58, v63
	v_pk_mul_f32 v[120:121], v[120:121], v[120:121]
	v_mov_b32_e32 v60, v65
	v_pk_mul_f32 v[122:123], v[58:59], v[58:59]
	v_pk_fma_f32 v[120:121], v[60:61], v[60:61], v[120:121]
	v_mov_b32_e32 v118, v62
	v_pk_fma_f32 v[118:119], v[118:119], v[118:119], v[122:123]
	v_pk_mul_f32 v[122:123], v[56:57], v[56:57]
	v_pk_add_f32 v[118:119], v[118:119], v[120:121]
	v_pk_mul_f32 v[120:121], v[54:55], v[54:55]
	v_pk_add_f32 v[118:119], v[118:119], v[118:119] op_sel_hi:[0,1]
	v_pk_mov_b32 v[126:127], v[120:121], v[122:123] op_sel:[1,0]
	v_mov_b32_e32 v121, v123
	v_pk_add_f32 v[120:121], v[120:121], v[126:127]
	v_mul_f32_e32 v118, v48, v48
	v_pk_add_f32 v[120:121], v[120:121], v[120:121] op_sel_hi:[0,1]
	v_mul_f32_e32 v120, v49, v49
	s_waitcnt lgkmcnt(0)
	v_pk_fma_f32 v[36:37], v[108:109], v[114:115], v[36:37]
	v_pk_fma_f32 v[34:35], v[110:111], v[112:113], v[34:35]
	v_and_b32_sdwa v108, v37, v143 dst_sel:DWORD dst_unused:UNUSED_PAD src0_sel:WORD_1 src1_sel:DWORD
	v_and_b32_sdwa v109, v35, v143 dst_sel:DWORD dst_unused:UNUSED_PAD src0_sel:WORD_1 src1_sel:DWORD
	v_and_b32_sdwa v58, v36, v143 dst_sel:DWORD dst_unused:UNUSED_PAD src0_sel:WORD_1 src1_sel:DWORD
	v_and_b32_sdwa v60, v34, v143 dst_sel:DWORD dst_unused:UNUSED_PAD src0_sel:WORD_1 src1_sel:DWORD
	v_add3_u32 v108, v37, v108, s13
	v_add3_u32 v109, v35, v109, s13
	v_add3_u32 v60, v34, v60, s13
	v_add3_u32 v58, v36, v58, s13
	v_and_b32_e32 v108, 0xffff0000, v108
	v_and_b32_e32 v110, 0xffff0000, v109
	v_or_b32_sdwa v109, v108, v58 dst_sel:DWORD dst_unused:UNUSED_PAD src0_sel:DWORD src1_sel:WORD_1
	v_or_b32_sdwa v108, v110, v60 dst_sel:DWORD dst_unused:UNUSED_PAD src0_sel:DWORD src1_sel:WORD_1
	global_store_dwordx2 v[116:117], v[108:109], off offset:3584
	s_nop 0
	ds_read_b128 v[108:111], v162 offset:8192
	v_mul_f32_e32 v58, v50, v50
	v_mul_f32_e32 v60, v52, v52
	v_pk_fma_f32 v[112:113], v[50:51], v[50:51], v[58:59] op_sel_hi:[1,1,0]
	v_pk_fma_f32 v[114:115], v[52:53], v[52:53], v[60:61] op_sel_hi:[1,1,0]
	v_mul_f32_e32 v112, v46, v46
	v_mul_f32_e32 v114, v47, v47
	v_pk_add_f32 v[112:113], v[112:113], v[114:115]
	v_pk_add_f32 v[114:115], v[120:121], v[118:119]
	v_pk_mul_f32 v[116:117], v[44:45], v[44:45]
	v_pk_add_f32 v[112:113], v[112:113], v[114:115]
	v_pk_mul_f32 v[114:115], v[42:43], v[42:43]
	v_mul_f32_e32 v58, v38, v38
	v_pk_mov_b32 v[118:119], v[114:115], v[116:117] op_sel:[1,0]
	v_mov_b32_e32 v115, v117
	v_pk_add_f32 v[114:115], v[114:115], v[118:119]
	v_mul_f32_e32 v60, v40, v40
	v_pk_add_f32 v[112:113], v[112:113], v[112:113] op_sel_hi:[0,1]
	v_pk_add_f32 v[114:115], v[114:115], v[114:115] op_sel_hi:[0,1]
	v_pk_fma_f32 v[116:117], v[38:39], v[38:39], v[58:59] op_sel_hi:[1,1,0]
	v_pk_fma_f32 v[118:119], v[40:41], v[40:41], v[60:61] op_sel_hi:[1,1,0]
	v_mul_f32_e32 v116, v34, v34
	v_mul_f32_e32 v118, v35, v35
	v_mul_f32_e32 v112, v36, v36
	v_mul_f32_e32 v114, v37, v37
	v_pk_add_f32 v[116:117], v[116:117], v[118:119]
	v_pk_add_f32 v[112:113], v[114:115], v[112:113]
	v_mov_b32_e32 v130, v34
	v_pk_add_f32 v[112:113], v[116:117], v[112:113]
	v_add_co_u32_e32 v116, vcc, s22, v106
	v_add_f32_e32 v58, v112, v113
	ds_bpermute_b32 v60, v136, v58
	v_addc_co_u32_e32 v117, vcc, 0, v107, vcc
	v_mov_b32_e32 v106, v62
	v_mov_b32_e32 v107, v64
	s_waitcnt lgkmcnt(0)
	v_add_f32_e32 v58, v58, v60
	ds_bpermute_b32 v60, v137, v58
	v_mov_b32_e32 v64, v63
	v_mov_b32_e32 v131, v36
	v_mov_b32_e32 v36, v35
	v_mov_b64_e32 v[112:113], v[104:105]
	s_waitcnt lgkmcnt(0)
; DI unsigned pk2(float lo, float hi) { return f2bf(lo) | (f2bf(hi) << 16); }
; template <int MODE, bool FIRST, bool LAST>
; DI void phase_rowpass(const float* xin, const bf16_t* M, const float* gpost, float* outf, bf16_t* HB, bf16_t* XN, const float* gnext, int gw, int NGW, int lane) {
;     ...
;         if (MODE == 1) { const float r2 = rsqrtf(wave_sum(s2) * (1.f / D_) + EPS); u32x2* o = (u32x2*)(XN + (size_t)row * D_) + lane;
; #pragma unroll
;             for (int j = 0; j < 8; ++j) { const f32x4 gv = ((const f32x4*)gnext)[lane + 64 * j]; u32x2 w; w.x = pk2(hv[j][0] * r2 * gv[0], hv[j][1] * r2 * gv[1]); w.y = pk2(hv[j][2] * r2 * gv[2], hv[j][3] * r2 * gv[3]); o[64 * j] = w; } }
	v_add_f32_e32 v58, v58, v60
	ds_bpermute_b32 v60, v138, v58
	v_mov_b64_e32 v[114:115], v[90:91]
	v_mov_b64_e32 v[118:119], v[92:93]
	v_mov_b64_e32 v[120:121], v[94:95]
	s_waitcnt lgkmcnt(0)
	v_add_f32_e32 v58, v58, v60
	ds_bpermute_b32 v60, v139, v58
	s_waitcnt lgkmcnt(0)
	v_add_f32_e32 v58, v58, v60
	ds_bpermute_b32 v60, v140, v58
	s_waitcnt lgkmcnt(0)
	v_add_f32_e32 v58, v58, v60
	ds_bpermute_b32 v60, v141, v58
	s_waitcnt lgkmcnt(0)
	v_add_f32_e32 v58, v58, v60
	v_fmamk_f32 v58, v58, 0x3a000000, v142
	v_mul_f32_e32 v60, 0x4b800000, v58
	v_cmp_gt_f32_e32 vcc, s3, v58
	s_nop 1
	v_cndmask_b32_e32 v58, v58, v60, vcc
	v_rsq_f32_e32 v58, v58
	s_nop 0
	v_mul_f32_e32 v60, 0x45800000, v58
	v_cndmask_b32_e32 v122, v58, v60, vcc
	v_pk_mul_f32 v[62:63], v[106:107], v[122:123] op_sel_hi:[1,0]
	v_pk_mul_f32 v[64:65], v[64:65], v[122:123] op_sel_hi:[1,0]
	s_waitcnt lgkmcnt(0)
	v_mov_b32_e32 v106, v108
	v_mov_b32_e32 v107, v110
	v_mov_b32_e32 v110, v109
	v_pk_mul_f32 v[62:63], v[106:107], v[62:63]
	v_pk_mul_f32 v[64:65], v[110:111], v[64:65]
	v_and_b32_sdwa v58, v63, v143 dst_sel:DWORD dst_unused:UNUSED_PAD src0_sel:WORD_1 src1_sel:DWORD
	v_and_b32_sdwa v60, v62, v143 dst_sel:DWORD dst_unused:UNUSED_PAD src0_sel:WORD_1 src1_sel:DWORD
	v_and_b32_sdwa v106, v65, v143 dst_sel:DWORD dst_unused:UNUSED_PAD src0_sel:WORD_1 src1_sel:DWORD
	v_and_b32_sdwa v107, v64, v143 dst_sel:DWORD dst_unused:UNUSED_PAD src0_sel:WORD_1 src1_sel:DWORD
	v_add3_u32 v60, v62, v60, s13
	v_add3_u32 v58, v63, v58, s13
	v_add3_u32 v62, v65, v106, s13
	v_add3_u32 v63, v64, v107, s13
	v_and_b32_e32 v62, 0xffff0000, v62
	v_and_b32_e32 v64, 0xffff0000, v63
	v_or_b32_sdwa v63, v62, v58 dst_sel:DWORD dst_unused:UNUSED_PAD src0_sel:DWORD src1_sel:WORD_1
	v_or_b32_sdwa v62, v64, v60 dst_sel:DWORD dst_unused:UNUSED_PAD src0_sel:DWORD src1_sel:WORD_1
	global_store_dwordx2 v[116:117], v[62:63], off
	s_nop 0
	ds_read_b128 v[62:65], v162 offset:9216
	v_mov_b32_e32 v60, v59
	v_pk_mul_f32 v[60:61], v[60:61], v[122:123] op_sel_hi:[1,0]
	v_pk_mul_f32 v[58:59], v[124:125], v[122:123] op_sel_hi:[1,0]
	v_pk_mul_f32 v[34:35], v[130:131], v[122:123] op_sel_hi:[1,0]
	v_pk_mul_f32 v[36:37], v[36:37], v[122:123] op_sel_hi:[1,0]
	v_mov_b64_e32 v[108:109], v[100:101]
	v_mov_b64_e32 v[110:111], v[102:103]
	v_mov_b64_e32 v[124:125], v[96:97]
	s_andn2_b64 vcc, exec, s[20:21]
	s_waitcnt lgkmcnt(0)
	v_mov_b32_e32 v107, v64
	v_mov_b32_e32 v64, v63
	v_mov_b32_e32 v106, v62
	v_pk_mul_f32 v[60:61], v[64:65], v[60:61]
	v_pk_mul_f32 v[58:59], v[106:107], v[58:59]
	v_and_b32_sdwa v64, v61, v143 dst_sel:DWORD dst_unused:UNUSED_PAD src0_sel:WORD_1 src1_sel:DWORD
	v_and_b32_sdwa v65, v60, v143 dst_sel:DWORD dst_unused:UNUSED_PAD src0_sel:WORD_1 src1_sel:DWORD
	v_and_b32_sdwa v62, v59, v143 dst_sel:DWORD dst_unused:UNUSED_PAD src0_sel:WORD_1 src1_sel:DWORD
	v_and_b32_sdwa v63, v58, v143 dst_sel:DWORD dst_unused:UNUSED_PAD src0_sel:WORD_1 src1_sel:DWORD
	v_add3_u32 v61, v61, v64, s13
	v_add3_u32 v60, v60, v65, s13
	v_add3_u32 v58, v58, v63, s13
	v_add3_u32 v59, v59, v62, s13
	v_and_b32_e32 v61, 0xffff0000, v61
	v_and_b32_e32 v60, 0xffff0000, v60
	v_or_b32_sdwa v59, v61, v59 dst_sel:DWORD dst_unused:UNUSED_PAD src0_sel:DWORD src1_sel:WORD_1
	v_or_b32_sdwa v58, v60, v58 dst_sel:DWORD dst_unused:UNUSED_PAD src0_sel:DWORD src1_sel:WORD_1
	global_store_dwordx2 v[116:117], v[58:59], off offset:512
	s_nop 0
	ds_read_b128 v[58:61], v162 offset:10240
	v_mov_b32_e32 v62, v54
	v_mov_b32_e32 v63, v56
	v_mov_b32_e32 v56, v55
	v_pk_mul_f32 v[54:55], v[62:63], v[122:123] op_sel_hi:[1,0]
	v_pk_mul_f32 v[56:57], v[56:57], v[122:123] op_sel_hi:[1,0]
	v_mov_b64_e32 v[106:107], v[98:99]
	s_waitcnt lgkmcnt(0)
	v_mov_b32_e32 v63, v60
	v_mov_b32_e32 v60, v59
	v_mov_b32_e32 v62, v58
	v_pk_mul_f32 v[56:57], v[60:61], v[56:57]
	v_pk_mul_f32 v[54:55], v[62:63], v[54:55]
	v_and_b32_sdwa v60, v57, v143 dst_sel:DWORD dst_unused:UNUSED_PAD src0_sel:WORD_1 src1_sel:DWORD
	v_and_b32_sdwa v61, v56, v143 dst_sel:DWORD dst_unused:UNUSED_PAD src0_sel:WORD_1 src1_sel:DWORD
	v_and_b32_sdwa v58, v55, v143 dst_sel:DWORD dst_unused:UNUSED_PAD src0_sel:WORD_1 src1_sel:DWORD
	v_and_b32_sdwa v59, v54, v143 dst_sel:DWORD dst_unused:UNUSED_PAD src0_sel:WORD_1 src1_sel:DWORD
	v_add3_u32 v57, v57, v60, s13
	v_add3_u32 v56, v56, v61, s13
	v_add3_u32 v54, v54, v59, s13
	v_add3_u32 v55, v55, v58, s13
	v_and_b32_e32 v57, 0xffff0000, v57
	v_and_b32_e32 v56, 0xffff0000, v56
	v_or_b32_sdwa v55, v57, v55 dst_sel:DWORD dst_unused:UNUSED_PAD src0_sel:DWORD src1_sel:WORD_1
	v_or_b32_sdwa v54, v56, v54 dst_sel:DWORD dst_unused:UNUSED_PAD src0_sel:DWORD src1_sel:WORD_1
	global_store_dwordx2 v[116:117], v[54:55], off offset:1024
	s_nop 0
	ds_read_b128 v[54:57], v162 offset:11264
	v_mov_b32_e32 v58, v50
	v_mov_b32_e32 v59, v52
	v_mov_b32_e32 v52, v51
	v_pk_mul_f32 v[50:51], v[58:59], v[122:123] op_sel_hi:[1,0]
	v_pk_mul_f32 v[52:53], v[52:53], v[122:123] op_sel_hi:[1,0]
	v_mov_b64_e32 v[64:65], v[4:5]
	v_mov_b64_e32 v[62:63], v[2:3]
	s_waitcnt lgkmcnt(0)
; DI unsigned pk2(float lo, float hi) { return f2bf(lo) | (f2bf(hi) << 16); }
; template <int MODE, bool FIRST, bool LAST>
; DI void phase_rowpass(const float* xin, const bf16_t* M, const float* gpost, float* outf, bf16_t* HB, bf16_t* XN, const float* gnext, int gw, int NGW, int lane) {
;     ...
;             for (int j = 0; j < 8; ++j) { const f32x4 gv = ((const f32x4*)gnext)[lane + 64 * j]; u32x2 w; w.x = pk2(hv[j][0] * r2 * gv[0], hv[j][1] * r2 * gv[1]); w.y = pk2(hv[j][2] * r2 * gv[2], hv[j][3] * r2 * gv[3]); o[64 * j] = w; } }
;         if (MODE == 2) { u32x2* o = (u32x2*)(XN + (size_t)row * D_) + lane;
; #pragma unroll
;             for (int j = 0; j < 8; ++j) { u32x2 w; w.x = pk2(hv[j][0], hv[j][1]); w.y = pk2(hv[j][2], hv[j][3]); o[64 * j] = w; } }
;         if (!has) break;
; #pragma unroll
;         for (int j = 0; j < 8; ++j) { hc.f[j] = hn.f[j]; mw[j] = mn[j]; }
;         row = nrow;
	v_mov_b32_e32 v59, v56
	v_mov_b32_e32 v56, v55
	v_mov_b32_e32 v58, v54
	v_pk_mul_f32 v[52:53], v[56:57], v[52:53]
	v_pk_mul_f32 v[50:51], v[58:59], v[50:51]
	v_and_b32_sdwa v56, v53, v143 dst_sel:DWORD dst_unused:UNUSED_PAD src0_sel:WORD_1 src1_sel:DWORD
	v_and_b32_sdwa v57, v52, v143 dst_sel:DWORD dst_unused:UNUSED_PAD src0_sel:WORD_1 src1_sel:DWORD
	v_and_b32_sdwa v54, v51, v143 dst_sel:DWORD dst_unused:UNUSED_PAD src0_sel:WORD_1 src1_sel:DWORD
	v_and_b32_sdwa v55, v50, v143 dst_sel:DWORD dst_unused:UNUSED_PAD src0_sel:WORD_1 src1_sel:DWORD
	v_add3_u32 v53, v53, v56, s13
	v_add3_u32 v52, v52, v57, s13
	v_add3_u32 v50, v50, v55, s13
	v_add3_u32 v51, v51, v54, s13
	v_and_b32_e32 v53, 0xffff0000, v53
	v_and_b32_e32 v52, 0xffff0000, v52
	v_or_b32_sdwa v51, v53, v51 dst_sel:DWORD dst_unused:UNUSED_PAD src0_sel:DWORD src1_sel:WORD_1
	v_or_b32_sdwa v50, v52, v50 dst_sel:DWORD dst_unused:UNUSED_PAD src0_sel:DWORD src1_sel:WORD_1
	global_store_dwordx2 v[116:117], v[50:51], off offset:1536
	s_nop 0
	ds_read_b128 v[50:53], v162 offset:12288
	v_mov_b32_e32 v54, v46
	v_mov_b32_e32 v55, v48
	v_mov_b32_e32 v48, v47
	v_pk_mul_f32 v[46:47], v[54:55], v[122:123] op_sel_hi:[1,0]
	v_pk_mul_f32 v[48:49], v[48:49], v[122:123] op_sel_hi:[1,0]
	v_mov_b64_e32 v[60:61], v[8:9]
	v_mov_b64_e32 v[58:59], v[6:7]
	s_waitcnt lgkmcnt(0)
	v_mov_b32_e32 v55, v52
	v_mov_b32_e32 v52, v51
	v_mov_b32_e32 v54, v50
	v_pk_mul_f32 v[48:49], v[52:53], v[48:49]
	v_pk_mul_f32 v[46:47], v[54:55], v[46:47]
	v_and_b32_sdwa v52, v49, v143 dst_sel:DWORD dst_unused:UNUSED_PAD src0_sel:WORD_1 src1_sel:DWORD
	v_and_b32_sdwa v53, v48, v143 dst_sel:DWORD dst_unused:UNUSED_PAD src0_sel:WORD_1 src1_sel:DWORD
	v_and_b32_sdwa v50, v47, v143 dst_sel:DWORD dst_unused:UNUSED_PAD src0_sel:WORD_1 src1_sel:DWORD
	v_and_b32_sdwa v51, v46, v143 dst_sel:DWORD dst_unused:UNUSED_PAD src0_sel:WORD_1 src1_sel:DWORD
	v_add3_u32 v49, v49, v52, s13
	v_add3_u32 v48, v48, v53, s13
	v_add3_u32 v46, v46, v51, s13
	v_add3_u32 v47, v47, v50, s13
	v_and_b32_e32 v49, 0xffff0000, v49
	v_and_b32_e32 v48, 0xffff0000, v48
	v_or_b32_sdwa v47, v49, v47 dst_sel:DWORD dst_unused:UNUSED_PAD src0_sel:DWORD src1_sel:WORD_1
	v_or_b32_sdwa v46, v48, v46 dst_sel:DWORD dst_unused:UNUSED_PAD src0_sel:DWORD src1_sel:WORD_1
	global_store_dwordx2 v[116:117], v[46:47], off offset:2048
	s_nop 0
	ds_read_b128 v[46:49], v162 offset:13312
	v_mov_b32_e32 v50, v42
	v_mov_b32_e32 v51, v44
	v_mov_b32_e32 v44, v43
	v_pk_mul_f32 v[42:43], v[50:51], v[122:123] op_sel_hi:[1,0]
	v_pk_mul_f32 v[44:45], v[44:45], v[122:123] op_sel_hi:[1,0]
	v_mov_b64_e32 v[56:57], v[12:13]
	v_mov_b64_e32 v[54:55], v[10:11]
	s_waitcnt lgkmcnt(0)
	v_mov_b32_e32 v51, v48
	v_mov_b32_e32 v48, v47
	v_mov_b32_e32 v50, v46
	v_pk_mul_f32 v[44:45], v[48:49], v[44:45]
	v_pk_mul_f32 v[42:43], v[50:51], v[42:43]
	v_and_b32_sdwa v48, v45, v143 dst_sel:DWORD dst_unused:UNUSED_PAD src0_sel:WORD_1 src1_sel:DWORD
	v_and_b32_sdwa v49, v44, v143 dst_sel:DWORD dst_unused:UNUSED_PAD src0_sel:WORD_1 src1_sel:DWORD
	v_and_b32_sdwa v46, v43, v143 dst_sel:DWORD dst_unused:UNUSED_PAD src0_sel:WORD_1 src1_sel:DWORD
	v_and_b32_sdwa v47, v42, v143 dst_sel:DWORD dst_unused:UNUSED_PAD src0_sel:WORD_1 src1_sel:DWORD
	v_add3_u32 v45, v45, v48, s13
	v_add3_u32 v44, v44, v49, s13
	v_add3_u32 v42, v42, v47, s13
	v_add3_u32 v43, v43, v46, s13
	v_and_b32_e32 v45, 0xffff0000, v45
	v_and_b32_e32 v44, 0xffff0000, v44
	v_or_b32_sdwa v43, v45, v43 dst_sel:DWORD dst_unused:UNUSED_PAD src0_sel:DWORD src1_sel:WORD_1
	v_or_b32_sdwa v42, v44, v42 dst_sel:DWORD dst_unused:UNUSED_PAD src0_sel:DWORD src1_sel:WORD_1
	global_store_dwordx2 v[116:117], v[42:43], off offset:2560
	s_nop 0
	ds_read_b128 v[42:45], v162 offset:14336
	v_mov_b32_e32 v46, v38
	v_mov_b32_e32 v47, v40
	v_mov_b32_e32 v40, v39
	v_pk_mul_f32 v[38:39], v[46:47], v[122:123] op_sel_hi:[1,0]
	v_pk_mul_f32 v[40:41], v[40:41], v[122:123] op_sel_hi:[1,0]
	v_mov_b64_e32 v[52:53], v[16:17]
	v_mov_b64_e32 v[50:51], v[14:15]
	s_waitcnt lgkmcnt(0)
	v_mov_b32_e32 v47, v44
	v_mov_b32_e32 v44, v43
	v_mov_b32_e32 v46, v42
	v_pk_mul_f32 v[40:41], v[44:45], v[40:41]
	v_pk_mul_f32 v[38:39], v[46:47], v[38:39]
	v_and_b32_sdwa v44, v41, v143 dst_sel:DWORD dst_unused:UNUSED_PAD src0_sel:WORD_1 src1_sel:DWORD
	v_and_b32_sdwa v45, v40, v143 dst_sel:DWORD dst_unused:UNUSED_PAD src0_sel:WORD_1 src1_sel:DWORD
	v_and_b32_sdwa v42, v39, v143 dst_sel:DWORD dst_unused:UNUSED_PAD src0_sel:WORD_1 src1_sel:DWORD
	v_and_b32_sdwa v43, v38, v143 dst_sel:DWORD dst_unused:UNUSED_PAD src0_sel:WORD_1 src1_sel:DWORD
	v_add3_u32 v41, v41, v44, s13
	v_add3_u32 v40, v40, v45, s13
	v_add3_u32 v38, v38, v43, s13
	v_add3_u32 v39, v39, v42, s13
	v_and_b32_e32 v41, 0xffff0000, v41
	v_and_b32_e32 v40, 0xffff0000, v40
	v_or_b32_sdwa v39, v41, v39 dst_sel:DWORD dst_unused:UNUSED_PAD src0_sel:DWORD src1_sel:WORD_1
	v_or_b32_sdwa v38, v40, v38 dst_sel:DWORD dst_unused:UNUSED_PAD src0_sel:DWORD src1_sel:WORD_1
	global_store_dwordx2 v[116:117], v[38:39], off offset:3072
	s_nop 0
	ds_read_b128 v[126:129], v162 offset:15360
	v_mov_b64_e32 v[48:49], v[20:21]
	v_mov_b64_e32 v[44:45], v[24:25]
	v_mov_b64_e32 v[40:41], v[28:29]
	v_mov_b64_e32 v[46:47], v[18:19]
	v_mov_b64_e32 v[42:43], v[22:23]
	v_mov_b64_e32 v[38:39], v[26:27]
	s_waitcnt vmcnt(0) lgkmcnt(0)
	v_mov_b32_e32 v123, v128
	v_mov_b32_e32 v128, v127
	v_mov_b32_e32 v122, v126
	v_pk_mul_f32 v[36:37], v[128:129], v[36:37]
	v_pk_mul_f32 v[34:35], v[122:123], v[34:35]
	v_and_b32_sdwa v126, v37, v143 dst_sel:DWORD dst_unused:UNUSED_PAD src0_sel:WORD_1 src1_sel:DWORD
	v_and_b32_sdwa v127, v36, v143 dst_sel:DWORD dst_unused:UNUSED_PAD src0_sel:WORD_1 src1_sel:DWORD
	v_and_b32_sdwa v122, v35, v143 dst_sel:DWORD dst_unused:UNUSED_PAD src0_sel:WORD_1 src1_sel:DWORD
	v_and_b32_sdwa v123, v34, v143 dst_sel:DWORD dst_unused:UNUSED_PAD src0_sel:WORD_1 src1_sel:DWORD
	v_add3_u32 v37, v37, v126, s13
	v_add3_u32 v36, v36, v127, s13
	v_add3_u32 v34, v34, v123, s13
	v_add3_u32 v35, v35, v122, s13
	v_and_b32_e32 v37, 0xffff0000, v37
	v_and_b32_e32 v36, 0xffff0000, v36
	v_or_b32_sdwa v35, v37, v35 dst_sel:DWORD dst_unused:UNUSED_PAD src0_sel:DWORD src1_sel:WORD_1
	v_or_b32_sdwa v34, v36, v34 dst_sel:DWORD dst_unused:UNUSED_PAD src0_sel:DWORD src1_sel:WORD_1
	global_store_dwordx2 v[116:117], v[34:35], off offset:3584
	v_mov_b64_e32 v[36:37], v[32:33]
	v_mov_b64_e32 v[34:35], v[30:31]
	s_cbranch_vccz .LBB0_438

; template <int MODE, bool FIRST, bool LAST>
; DI void phase_rowpass(const float* xin, const bf16_t* M, const float* gpost, float* outf, bf16_t* HB, bf16_t* XN, const float* gnext, int gw, int NGW, int lane) {
;     int row = gw; if (row >= T_) return;
;     HRow<FIRST> hc; u32x2 mw[8];
;     { const u32x2* mr = (const u32x2*)(M + (size_t)row * D_) + lane;
; #pragma unroll
;       for (int j = 0; j < 8; ++j) { if constexpr (FIRST) hc.f[j] = ((const f32x4*)(xin + (size_t)row * D_) + lane)[64 * j]; else hc.f[j] = ((const u32x2*)(HB + (size_t)row * D_) + lane)[64 * j]; mw[j] = mr[64 * j]; } }
;     ...
;         for (int j = 0; j < 8; ++j) { const f32x4 gv = ((const f32x4*)gpost)[lane + 64 * j]; hv[j] = hv[j] + mv[j] * rs * gv;
.LBB0_664:
	s_cmp_lt_i32 s62, 8
	s_cselect_b64 s[8:9], -1, 0
	s_and_b64 s[6:7], s[8:9], s[6:7]
	s_andn2_b64 vcc, exec, s[6:7]
	s_cbranch_vccnz .LBB0_670
	v_mov_b32_e32 v2, v1
	s_lshl_b32 s3, s2, 3
	v_readfirstlane_b32 s8, v2
	s_ashr_i32 s8, s8, 6
	s_add_i32 s8, s8, s3
	s_mov_b64 s[12:13], s[0:1]
	s_cmpk_gt_i32 s8, 0x3fff
	s_cbranch_scc1 .LBB0_670
	s_waitcnt lgkmcnt(0)
	s_load_dwordx2 s[16:17], s[12:13], 0xc8
	s_load_dwordx2 s[14:15], s[12:13], 0x28
	s_ashr_i32 s9, s8, 31
	s_lshl_b32 s10, s74, 3
	s_lshl_b64 s[12:13], s[8:9], 12
	v_and_b32_e32 v12, 63, v2
	s_waitcnt lgkmcnt(0)
	s_add_u32 s12, s16, s12
	v_lshlrev_b32_e32 v2, 3, v12
	v_mov_b32_e32 v3, 0
	s_addc_u32 s13, s17, s13
	v_lshl_add_u64 v[4:5], s[12:13], 0, v[2:3]
	s_mov_b32 s3, 0xc000
	s_mov_b64 s[18:19], 0x14dcc000
	v_add_co_u32_e32 v10, vcc, s3, v4
	v_lshl_add_u64 v[6:7], v[4:5], 0, s[18:19]
	s_mov_b64 s[18:19], 0xc000
	v_addc_co_u32_e32 v11, vcc, 0, v5, vcc
	s_mov_b32 s9, 0x14dcc000
	v_lshl_add_u64 v[8:9], v[4:5], 0, s[18:19]
	v_add_co_u32_e32 v4, vcc, s9, v4
	s_add_i32 s18, s8, s10
	s_nop 0
	v_addc_co_u32_e32 v5, vcc, 0, v5, vcc
	global_load_dwordx2 v[82:83], v[6:7], off offset:512
	global_load_dwordx2 v[80:81], v[6:7], off offset:1024
	global_load_dwordx2 v[76:77], v[6:7], off offset:1536
	global_load_dwordx2 v[74:75], v[6:7], off offset:2048
	global_load_dwordx2 v[56:57], v[8:9], off offset:1024
	global_load_dwordx2 v[54:55], v[8:9], off offset:1536
	global_load_dwordx2 v[52:53], v[8:9], off offset:2048
	global_load_dwordx2 v[50:51], v[8:9], off offset:2560
	global_load_dwordx2 v[60:61], v[10:11], off
	global_load_dwordx2 v[84:85], v[4:5], off
	global_load_dwordx2 v[32:33], v[8:9], off offset:3072
	global_load_dwordx2 v[20:21], v[8:9], off offset:3584
	global_load_dwordx2 v[58:59], v[8:9], off offset:512
	global_load_dwordx2 v[70:71], v[6:7], off offset:2560
	global_load_dwordx2 v[64:65], v[6:7], off offset:3072
	global_load_dwordx2 v[62:63], v[6:7], off offset:3584
	v_mbcnt_lo_u32_b32 v4, -1, 0
	v_mbcnt_hi_u32_b32 v4, -1, v4
	v_and_b32_e32 v5, 64, v4
	v_add_u32_e32 v5, 64, v5
	v_xor_b32_e32 v6, 1, v4
	v_cmp_lt_i32_e32 vcc, v6, v5
	s_ashr_i32 s11, s10, 31
	s_ashr_i32 s19, s18, 31
	v_cndmask_b32_e32 v6, v4, v6, vcc
	v_lshlrev_b32_e32 v73, 2, v6
	v_xor_b32_e32 v6, 2, v4
	v_cmp_lt_i32_e32 vcc, v6, v5
	s_lshl_b64 s[18:19], s[18:19], 12
	s_mov_b32 s9, 0xffff0000
	v_cndmask_b32_e32 v6, v4, v6, vcc
	v_lshlrev_b32_e32 v94, 2, v6
	v_xor_b32_e32 v6, 4, v4
	v_cmp_lt_i32_e32 vcc, v6, v5
	v_mov_b32_e32 v99, 0x358637bd
	s_movk_i32 s20, 0x7fff
	v_cndmask_b32_e32 v6, v4, v6, vcc
	v_lshlrev_b32_e32 v95, 2, v6
	v_xor_b32_e32 v6, 8, v4
	v_cmp_lt_i32_e32 vcc, v6, v5
	s_nop 1
	v_cndmask_b32_e32 v6, v4, v6, vcc
	v_lshlrev_b32_e32 v96, 2, v6
	v_xor_b32_e32 v6, 16, v4
	v_cmp_lt_i32_e32 vcc, v6, v5
	s_nop 1
	v_cndmask_b32_e32 v6, v4, v6, vcc
	v_lshlrev_b32_e32 v97, 2, v6
	v_xor_b32_e32 v6, 32, v4
	v_cmp_lt_i32_e32 vcc, v6, v5
	v_mov_b32_e32 v5, v3
	s_nop 0
	v_cndmask_b32_e32 v4, v4, v6, vcc
	v_lshlrev_b32_e32 v98, 2, v4
	v_lshlrev_b32_e32 v4, 4, v12
	v_lshl_add_u64 v[4:5], s[14:15], 0, v[4:5]
	s_mov_b64 s[14:15], 0x1000
	v_lshl_add_u64 v[6:7], v[4:5], 0, s[14:15]
	s_mov_b64 s[14:15], 0x1400
	v_lshl_add_u64 v[8:9], v[4:5], 0, s[14:15]
	s_mov_b64 s[14:15], 0x1800
	v_lshl_add_u64 v[10:11], v[4:5], 0, s[14:15]
	s_mov_b64 s[14:15], 0x1c00
	v_lshl_add_u64 v[12:13], v[4:5], 0, s[14:15]
	s_lshl_b64 s[14:15], s[10:11], 12
	s_add_u32 s16, s16, s18
	s_addc_u32 s17, s17, s19
	s_mov_b32 s11, 0x800000
	v_and_b32_e32 v118, 63, v1
	v_lshlrev_b32_e32 v118, 4, v118
	global_load_dwordx4 v[120:123], v[4:5], off
	global_load_dwordx4 v[124:127], v[4:5], off offset:1024
	global_load_dwordx4 v[128:131], v[4:5], off offset:2048
	global_load_dwordx4 v[132:135], v[4:5], off offset:3072
	global_load_dwordx4 v[136:139], v[6:7], off
	global_load_dwordx4 v[140:143], v[8:9], off
	global_load_dwordx4 v[144:147], v[10:11], off
	global_load_dwordx4 v[148:151], v[12:13], off
	s_waitcnt vmcnt(0)
	ds_write_b128 v118, v[120:123] offset:0
	ds_write_b128 v118, v[124:127] offset:1024
	ds_write_b128 v118, v[128:131] offset:2048
	ds_write_b128 v118, v[132:135] offset:3072
	ds_write_b128 v118, v[136:139] offset:4096
	ds_write_b128 v118, v[140:143] offset:5120
	ds_write_b128 v118, v[144:147] offset:6144
	ds_write_b128 v118, v[148:151] offset:7168
	s_waitcnt lgkmcnt(0)
	s_branch .LBB0_668
; DI unsigned pk2(float lo, float hi) { return f2bf(lo) | (f2bf(hi) << 16); }
; DI float lo_f(unsigned w) { return __uint_as_float(w << 16); }
; DI float hi_f(unsigned w) { return __uint_as_float(w & 0xffff0000u); }
; template <int MODE, bool FIRST, bool LAST>
; DI void phase_rowpass(const float* xin, const bf16_t* M, const float* gpost, float* outf, bf16_t* HB, bf16_t* XN, const float* gnext, int gw, int NGW, int lane) {
;     ...
;         f32x4 hv[8], mv[8]; float ss = 0.f;
; #pragma unroll
;         for (int j = 0; j < 8; ++j) { const u32x2 w = mw[j]; mv[j] = (f32x4){lo_f(w.x), hi_f(w.x), lo_f(w.y), hi_f(w.y)};
;             if constexpr (FIRST) hv[j] = hc.f[j]; else { const u32x2 hw = hc.f[j]; hv[j] = (f32x4){lo_f(hw.x), hi_f(hw.x), lo_f(hw.y), hi_f(hw.y)}; }
;             ss += (mv[j][0] * mv[j][0] + mv[j][1] * mv[j][1]) + (mv[j][2] * mv[j][2] + mv[j][3] * mv[j][3]); }
;         const float rs = rsqrtf(wave_sum(ss) * (1.f / D_) + EPS);
;         float s2 = 0.f;
; #pragma unroll
;         for (int j = 0; j < 8; ++j) { const f32x4 gv = ((const f32x4*)gpost)[lane + 64 * j]; hv[j] = hv[j] + mv[j] * rs * gv;
;             if constexpr (LAST) ((f32x4*)(outf + (size_t)row * D_) + lane)[64 * j] = hv[j];
;             else { u32x2 w; w.x = pk2(hv[j][0], hv[j][1]); w.y = pk2(hv[j][2], hv[j][3]); ((u32x2*)(HB + (size_t)row * D_) + lane)[64 * j] = w; }
.LBB0_667:
	ds_read_b128 v[100:103], v118 offset:0
	s_waitcnt vmcnt(0) lgkmcnt(0)
	v_and_b32_e32 v105, 0xffff0000, v84
	v_and_b32_e32 v104, 0xffff0000, v82
	v_and_b32_e32 v109, 0xffff0000, v85
	v_and_b32_e32 v108, 0xffff0000, v83
	v_lshlrev_b32_e32 v93, 16, v84
	v_lshlrev_b32_e32 v92, 16, v82
	v_lshlrev_b32_e32 v107, 16, v85
	v_lshlrev_b32_e32 v106, 16, v83
	v_pk_mul_f32 v[66:67], v[104:105], v[104:105]
	v_pk_mul_f32 v[68:69], v[108:109], v[108:109]
	v_pk_fma_f32 v[66:67], v[92:93], v[92:93], v[66:67]
	v_pk_fma_f32 v[68:69], v[106:107], v[106:107], v[68:69]
	v_and_b32_e32 v91, 0xffff0000, v81
	v_pk_add_f32 v[66:67], v[66:67], v[68:69]
	v_and_b32_e32 v90, 0xffff0000, v80
	v_pk_add_f32 v[66:67], v[66:67], v[66:67] op_sel_hi:[0,1]
	v_lshlrev_b32_e32 v89, 16, v81
	v_lshlrev_b32_e32 v88, 16, v80
	v_pk_mul_f32 v[68:69], v[90:91], v[90:91]
	v_lshlrev_b32_e32 v82, 16, v76
	v_and_b32_e32 v83, 0xffff0000, v76
	v_lshlrev_b32_e32 v84, 16, v77
	v_lshlrev_b32_e32 v80, 16, v74
	v_pk_fma_f32 v[68:69], v[88:89], v[88:89], v[68:69]
	v_mul_f32_e32 v81, v82, v82
	v_mul_f32_e32 v79, v83, v83
	v_and_b32_e32 v85, 0xffff0000, v77
	v_mul_f32_e32 v66, v84, v84
	v_mov_b32_e32 v78, v80
	v_pk_add_f32 v[68:69], v[68:69], v[68:69] op_sel_hi:[0,1]
	v_pk_fma_f32 v[86:87], v[84:85], v[84:85], v[66:67] op_sel_hi:[1,1,0]
	v_and_b32_e32 v116, 0xffff0000, v74
	v_lshlrev_b32_e32 v76, 16, v75
	v_and_b32_e32 v77, 0xffff0000, v75
	v_pk_add_f32 v[78:79], v[80:81], v[78:79]
	v_mul_f32_e32 v86, v116, v116
	v_mul_f32_e32 v68, v76, v76
	v_mul_f32_e32 v66, v77, v77
	v_mul_f32_e32 v74, v80, v80
	v_mov_b32_e32 v75, v79
	v_pk_add_f32 v[74:75], v[74:75], v[86:87]
	v_pk_add_f32 v[66:67], v[68:69], v[66:67]
	v_lshlrev_b32_e32 v86, 16, v64
	v_pk_add_f32 v[66:67], v[74:75], v[66:67]
	v_lshlrev_b32_e32 v75, 16, v71
	v_lshlrev_b32_e32 v74, 16, v70
	v_and_b32_e32 v71, 0xffff0000, v71
	v_and_b32_e32 v70, 0xffff0000, v70
	v_pk_add_f32 v[78:79], v[66:67], v[66:67] op_sel_hi:[0,1]
	v_pk_mul_f32 v[66:67], v[70:71], v[70:71]
	v_and_b32_e32 v87, 0xffff0000, v64
	v_pk_fma_f32 v[66:67], v[74:75], v[74:75], v[66:67]
	v_lshlrev_b32_e32 v64, 16, v65
	v_pk_add_f32 v[110:111], v[66:67], v[66:67] op_sel_hi:[0,1]
	v_mul_f32_e32 v67, v86, v86
	v_and_b32_e32 v65, 0xffff0000, v65
	v_mul_f32_e32 v66, v64, v64
	v_pk_fma_f32 v[114:115], v[64:65], v[64:65], v[66:67] op_sel_hi:[1,1,0]
	v_lshlrev_b32_e32 v66, 16, v62
	v_mul_f32_e32 v113, v87, v87
	v_mov_b32_e32 v112, v66
	v_and_b32_e32 v117, 0xffff0000, v62
	v_lshlrev_b32_e32 v68, 16, v63
	v_and_b32_e32 v69, 0xffff0000, v63
	v_pk_add_f32 v[112:113], v[66:67], v[112:113]
	v_mul_f32_e32 v114, v117, v117
	v_mul_f32_e32 v110, v68, v68
	v_mul_f32_e32 v78, v69, v69
	v_mul_f32_e32 v62, v66, v66
	v_mov_b32_e32 v63, v113
	v_pk_add_f32 v[62:63], v[62:63], v[114:115]
	v_pk_add_f32 v[78:79], v[110:111], v[78:79]
	v_mov_b32_e32 v110, v93
	v_pk_add_f32 v[62:63], v[62:63], v[78:79]
	v_mov_b32_e32 v111, v105
	v_add_f32_e32 v62, v62, v63
	ds_bpermute_b32 v63, v73, v62
	v_mov_b32_e32 v112, v107
	v_mov_b32_e32 v113, v109
	v_lshl_add_u64 v[78:79], s[12:13], 0, v[2:3]
	v_mov_b32_e32 v93, v104
	s_waitcnt lgkmcnt(0)
	v_add_f32_e32 v62, v62, v63
	ds_bpermute_b32 v63, v94, v62
	v_mov_b32_e32 v107, v108
	s_add_u32 s12, s12, s14
	s_addc_u32 s13, s13, s15
	s_add_u32 s16, s16, s14
	s_waitcnt lgkmcnt(0)
	v_add_f32_e32 v62, v62, v63
	ds_bpermute_b32 v63, v95, v62
	s_addc_u32 s17, s17, s15
	s_waitcnt lgkmcnt(0)
	v_add_f32_e32 v62, v62, v63
	ds_bpermute_b32 v63, v96, v62
	s_waitcnt lgkmcnt(0)
	v_add_f32_e32 v62, v62, v63
	ds_bpermute_b32 v63, v97, v62
	s_waitcnt lgkmcnt(0)
	v_add_f32_e32 v63, v62, v63
	ds_bpermute_b32 v67, v98, v63
	v_lshlrev_b32_e32 v62, 16, v60
	s_waitcnt lgkmcnt(0)
	v_add_f32_e32 v63, v63, v67
	v_fmamk_f32 v63, v63, 0x3a000000, v99
	v_mul_f32_e32 v67, 0x4b800000, v63
	v_cmp_gt_f32_e32 vcc, s11, v63
	s_nop 1
	v_cndmask_b32_e32 v63, v63, v67, vcc
	v_rsq_f32_e32 v67, v63
	v_and_b32_e32 v63, 0xffff0000, v60
	v_lshlrev_b32_e32 v60, 16, v61
	v_and_b32_e32 v61, 0xffff0000, v61
	v_mul_f32_e32 v72, 0x45800000, v67
	v_cndmask_b32_e32 v72, v67, v72, vcc
	v_pk_mul_f32 v[110:111], v[110:111], v[72:73] op_sel_hi:[1,0]
	v_pk_mul_f32 v[112:113], v[112:113], v[72:73] op_sel_hi:[1,0]
	v_pk_fma_f32 v[62:63], v[100:101], v[110:111], v[62:63]
	v_pk_fma_f32 v[60:61], v[102:103], v[112:113], v[60:61]
	v_bfe_u32 v67, v62, 16, 1
	v_add3_u32 v62, v62, v67, s20
	v_bfe_u32 v67, v63, 16, 1
	v_lshrrev_b32_e32 v62, 16, v62
	v_add3_u32 v63, v63, v67, s20
	v_and_or_b32 v62, v63, s9, v62
	v_bfe_u32 v63, v60, 16, 1
	v_add3_u32 v60, v60, v63, s20
	v_bfe_u32 v63, v61, 16, 1
	v_lshrrev_b32_e32 v60, 16, v60
	v_add3_u32 v61, v61, v63, s20
	v_add_co_u32_e32 v78, vcc, s3, v78
	v_and_or_b32 v63, v61, s9, v60
	s_nop 0
	v_addc_co_u32_e32 v79, vcc, 0, v79, vcc
	global_store_dwordx2 v[78:79], v[62:63], off
	s_nop 0
	ds_read_b128 v[60:63], v118 offset:1024
	v_lshlrev_b32_e32 v100, 16, v58
	v_and_b32_e32 v101, 0xffff0000, v58
	v_lshlrev_b32_e32 v58, 16, v59
	v_and_b32_e32 v59, 0xffff0000, v59
	v_pk_mul_f32 v[92:93], v[92:93], v[72:73] op_sel_hi:[1,0]
	v_pk_mul_f32 v[102:103], v[106:107], v[72:73] op_sel_hi:[1,0]
	v_pk_mul_f32 v[68:69], v[68:69], v[72:73] op_sel_hi:[1,0]
	s_andn2_b64 vcc, exec, s[18:19]
	s_waitcnt lgkmcnt(0)
; DI unsigned pk2(float lo, float hi) { return f2bf(lo) | (f2bf(hi) << 16); }
; template <int MODE, bool FIRST, bool LAST>
; DI void phase_rowpass(const float* xin, const bf16_t* M, const float* gpost, float* outf, bf16_t* HB, bf16_t* XN, const float* gnext, int gw, int NGW, int lane) {
;     ...
;         for (int j = 0; j < 8; ++j) { const f32x4 gv = ((const f32x4*)gpost)[lane + 64 * j]; hv[j] = hv[j] + mv[j] * rs * gv;
;             if constexpr (LAST) ((f32x4*)(outf + (size_t)row * D_) + lane)[64 * j] = hv[j];
;             else { u32x2 w; w.x = pk2(hv[j][0], hv[j][1]); w.y = pk2(hv[j][2], hv[j][3]); ((u32x2*)(HB + (size_t)row * D_) + lane)[64 * j] = w; }
;             s2 += (hv[j][0] * hv[j][0] + hv[j][1] * hv[j][1]) + (hv[j][2] * hv[j][2] + hv[j][3] * hv[j][3]); }
;         if (MODE == 1) { const float r2 = rsqrtf(wave_sum(s2) * (1.f / D_) + EPS); u32x2* o = (u32x2*)(XN + (size_t)row * D_) + lane;
; #pragma unroll
;             for (int j = 0; j < 8; ++j) { const f32x4 gv = ((const f32x4*)gnext)[lane + 64 * j]; u32x2 w; w.x = pk2(hv[j][0] * r2 * gv[0], hv[j][1] * r2 * gv[1]); w.y = pk2(hv[j][2] * r2 * gv[2], hv[j][3] * r2 * gv[3]); o[64 * j] = w; } }
;         if (MODE == 2) { u32x2* o = (u32x2*)(XN + (size_t)row * D_) + lane;
; #pragma unroll
;             for (int j = 0; j < 8; ++j) { u32x2 w; w.x = pk2(hv[j][0], hv[j][1]); w.y = pk2(hv[j][2], hv[j][3]); o[64 * j] = w; } }
;         if (!has) break;
; #pragma unroll
;         for (int j = 0; j < 8; ++j) { hc.f[j] = hn.f[j]; mw[j] = mn[j]; }
;         row = nrow;
	v_pk_fma_f32 v[58:59], v[62:63], v[102:103], v[58:59]
	v_pk_fma_f32 v[60:61], v[60:61], v[92:93], v[100:101]
	v_bfe_u32 v67, v58, 16, 1
	v_bfe_u32 v62, v60, 16, 1
	v_bfe_u32 v63, v61, 16, 1
	v_bfe_u32 v81, v59, 16, 1
	v_add3_u32 v60, v60, v62, s20
	v_add3_u32 v58, v58, v67, s20
	v_add3_u32 v61, v61, v63, s20
	v_add3_u32 v59, v59, v81, s20
	v_lshrrev_b32_e32 v60, 16, v60
	v_lshrrev_b32_e32 v62, 16, v58
	v_and_or_b32 v58, v61, s9, v60
	v_and_or_b32 v59, v59, s9, v62
	global_store_dwordx2 v[78:79], v[58:59], off offset:512
	s_nop 0
	ds_read_b128 v[58:61], v118 offset:2048
	v_mov_b32_e32 v92, v88
	v_mov_b32_e32 v93, v90
	v_mov_b32_e32 v90, v89
	v_lshlrev_b32_e32 v62, 16, v56
	v_and_b32_e32 v63, 0xffff0000, v56
	v_lshlrev_b32_e32 v56, 16, v57
	v_and_b32_e32 v57, 0xffff0000, v57
	v_pk_mul_f32 v[88:89], v[72:73], v[92:93] op_sel_hi:[0,1]
	v_pk_mul_f32 v[90:91], v[72:73], v[90:91] op_sel_hi:[0,1]
	v_mov_b32_e32 v81, v116
	v_mov_b32_e32 v67, v117
	v_pk_mul_f32 v[66:67], v[66:67], v[72:73] op_sel_hi:[1,0]
	s_waitcnt lgkmcnt(0)
	v_pk_fma_f32 v[56:57], v[60:61], v[90:91], v[56:57]
	v_pk_fma_f32 v[58:59], v[58:59], v[88:89], v[62:63]
	v_bfe_u32 v62, v56, 16, 1
	v_bfe_u32 v60, v58, 16, 1
	v_bfe_u32 v61, v59, 16, 1
	v_bfe_u32 v63, v57, 16, 1
	v_add3_u32 v58, v58, v60, s20
	v_add3_u32 v56, v56, v62, s20
	v_add3_u32 v59, v59, v61, s20
	v_add3_u32 v57, v57, v63, s20
	v_lshrrev_b32_e32 v58, 16, v58
	v_lshrrev_b32_e32 v60, 16, v56
	v_and_or_b32 v56, v59, s9, v58
	v_and_or_b32 v57, v57, s9, v60
	global_store_dwordx2 v[78:79], v[56:57], off offset:1024
	s_nop 0
	ds_read_b128 v[56:59], v118 offset:3072
	v_lshlrev_b32_e32 v60, 16, v54
	v_and_b32_e32 v61, 0xffff0000, v54
	v_lshlrev_b32_e32 v54, 16, v55
	v_and_b32_e32 v55, 0xffff0000, v55
	v_pk_mul_f32 v[62:63], v[82:83], v[72:73] op_sel_hi:[1,0]
	v_pk_mul_f32 v[82:83], v[84:85], v[72:73] op_sel_hi:[1,0]
	v_lshlrev_b32_e32 v90, 16, v20
	v_and_b32_e32 v91, 0xffff0000, v20
	v_lshlrev_b32_e32 v20, 16, v21
	v_and_b32_e32 v21, 0xffff0000, v21
	v_mov_b64_e32 v[84:85], v[40:41]
	s_waitcnt lgkmcnt(0)
	v_pk_fma_f32 v[54:55], v[58:59], v[82:83], v[54:55]
	v_pk_fma_f32 v[56:57], v[56:57], v[62:63], v[60:61]
	v_bfe_u32 v60, v54, 16, 1
	v_bfe_u32 v58, v56, 16, 1
	v_bfe_u32 v59, v57, 16, 1
	v_bfe_u32 v61, v55, 16, 1
	v_add3_u32 v56, v56, v58, s20
	v_add3_u32 v54, v54, v60, s20
	v_add3_u32 v57, v57, v59, s20
	v_add3_u32 v55, v55, v61, s20
	v_lshrrev_b32_e32 v56, 16, v56
	v_lshrrev_b32_e32 v58, 16, v54
	v_and_or_b32 v54, v57, s9, v56
	v_and_or_b32 v55, v55, s9, v58
	global_store_dwordx2 v[78:79], v[54:55], off offset:1536
	s_nop 0
	ds_read_b128 v[54:57], v118 offset:4096
	v_lshlrev_b32_e32 v58, 16, v52
	v_and_b32_e32 v59, 0xffff0000, v52
	v_lshlrev_b32_e32 v52, 16, v53
	v_and_b32_e32 v53, 0xffff0000, v53
	v_pk_mul_f32 v[60:61], v[80:81], v[72:73] op_sel_hi:[1,0]
	v_pk_mul_f32 v[62:63], v[76:77], v[72:73] op_sel_hi:[1,0]
	v_mov_b64_e32 v[76:77], v[34:35]
	v_mov_b64_e32 v[80:81], v[36:37]
	v_mov_b64_e32 v[82:83], v[38:39]
	s_waitcnt lgkmcnt(0)
	v_pk_fma_f32 v[52:53], v[56:57], v[62:63], v[52:53]
	v_pk_fma_f32 v[54:55], v[54:55], v[60:61], v[58:59]
	v_bfe_u32 v58, v52, 16, 1
	v_bfe_u32 v56, v54, 16, 1
	v_bfe_u32 v57, v55, 16, 1
	v_bfe_u32 v59, v53, 16, 1
	v_add3_u32 v54, v54, v56, s20
	v_add3_u32 v52, v52, v58, s20
	v_add3_u32 v55, v55, v57, s20
	v_add3_u32 v53, v53, v59, s20
	v_lshrrev_b32_e32 v54, 16, v54
	v_lshrrev_b32_e32 v56, 16, v52
	v_and_or_b32 v52, v55, s9, v54
	v_and_or_b32 v53, v53, s9, v56
	global_store_dwordx2 v[78:79], v[52:53], off offset:2048
	s_nop 0
	ds_read_b128 v[52:55], v118 offset:5120
	v_mov_b32_e32 v58, v74
	v_mov_b32_e32 v59, v70
	v_mov_b32_e32 v70, v75
	v_lshlrev_b32_e32 v56, 16, v50
	v_and_b32_e32 v57, 0xffff0000, v50
	v_lshlrev_b32_e32 v50, 16, v51
	v_and_b32_e32 v51, 0xffff0000, v51
	v_pk_mul_f32 v[58:59], v[72:73], v[58:59] op_sel_hi:[0,1]
	v_pk_mul_f32 v[60:61], v[72:73], v[70:71] op_sel_hi:[0,1]
	v_mov_b64_e32 v[62:63], v[48:49]
	v_mov_b64_e32 v[70:71], v[44:45]
	v_mov_b64_e32 v[74:75], v[46:47]
	s_waitcnt lgkmcnt(0)
	v_pk_fma_f32 v[50:51], v[54:55], v[60:61], v[50:51]
	v_pk_fma_f32 v[52:53], v[52:53], v[58:59], v[56:57]
	v_bfe_u32 v56, v50, 16, 1
	v_bfe_u32 v54, v52, 16, 1
	v_bfe_u32 v55, v53, 16, 1
	v_bfe_u32 v57, v51, 16, 1
	v_add3_u32 v52, v52, v54, s20
	v_add3_u32 v50, v50, v56, s20
	v_add3_u32 v53, v53, v55, s20
	v_add3_u32 v51, v51, v57, s20
	v_lshrrev_b32_e32 v52, 16, v52
	v_lshrrev_b32_e32 v54, 16, v50
	v_and_or_b32 v50, v53, s9, v52
	v_and_or_b32 v51, v51, s9, v54
	global_store_dwordx2 v[78:79], v[50:51], off offset:2560
	s_nop 0
	ds_read_b128 v[50:53], v118 offset:6144
	v_lshlrev_b32_e32 v54, 16, v32
	v_and_b32_e32 v55, 0xffff0000, v32
	v_lshlrev_b32_e32 v32, 16, v33
	v_and_b32_e32 v33, 0xffff0000, v33
	v_pk_mul_f32 v[56:57], v[86:87], v[72:73] op_sel_hi:[1,0]
	v_pk_mul_f32 v[58:59], v[64:65], v[72:73] op_sel_hi:[1,0]
	v_mov_b64_e32 v[64:65], v[42:43]
	v_mov_b64_e32 v[60:61], v[14:15]
	s_waitcnt lgkmcnt(0)
	v_pk_fma_f32 v[32:33], v[58:59], v[52:53], v[32:33]
	v_pk_fma_f32 v[50:51], v[56:57], v[50:51], v[54:55]
	v_bfe_u32 v54, v32, 16, 1
	v_bfe_u32 v52, v50, 16, 1
	v_bfe_u32 v53, v51, 16, 1
	v_bfe_u32 v55, v33, 16, 1
	v_add3_u32 v50, v50, v52, s20
	v_add3_u32 v32, v32, v54, s20
	v_add3_u32 v51, v51, v53, s20
	v_add3_u32 v33, v33, v55, s20
	v_lshrrev_b32_e32 v50, 16, v50
	v_lshrrev_b32_e32 v52, 16, v32
	v_and_or_b32 v32, v51, s9, v50
	v_and_or_b32 v33, v33, s9, v52
	global_store_dwordx2 v[78:79], v[32:33], off offset:3072
	s_nop 0
	ds_read_b128 v[86:89], v118 offset:7168
	v_mov_b64_e32 v[58:59], v[16:17]
	v_mov_b64_e32 v[56:57], v[18:19]
	v_mov_b64_e32 v[54:55], v[22:23]
	v_mov_b64_e32 v[52:53], v[24:25]
	v_mov_b64_e32 v[50:51], v[26:27]
	v_mov_b64_e32 v[32:33], v[28:29]
	s_waitcnt vmcnt(0) lgkmcnt(0)
	v_pk_fma_f32 v[20:21], v[68:69], v[88:89], v[20:21]
	v_pk_fma_f32 v[66:67], v[66:67], v[86:87], v[90:91]
	v_bfe_u32 v72, v20, 16, 1
	v_bfe_u32 v68, v66, 16, 1
	v_bfe_u32 v69, v67, 16, 1
	v_bfe_u32 v86, v21, 16, 1
	v_add3_u32 v66, v66, v68, s20
	v_add3_u32 v20, v20, v72, s20
	v_add3_u32 v67, v67, v69, s20
	v_add3_u32 v21, v21, v86, s20
	v_lshrrev_b32_e32 v66, 16, v66
	v_lshrrev_b32_e32 v68, 16, v20
	v_and_or_b32 v20, v67, s9, v66
	v_and_or_b32 v21, v21, s9, v68
	global_store_dwordx2 v[78:79], v[20:21], off offset:3584
	v_mov_b64_e32 v[20:21], v[30:31]
	s_cbranch_vccz .LBB0_670

; DI unsigned pk2(float lo, float hi) { return f2bf(lo) | (f2bf(hi) << 16); }
; template <int MODE, bool FIRST, bool LAST>
; DI void phase_rowpass(const float* xin, const bf16_t* M, const float* gpost, float* outf, bf16_t* HB, bf16_t* XN, const float* gnext, int gw, int NGW, int lane) {
;     int row = gw; if (row >= T_) return;
;     HRow<FIRST> hc; u32x2 mw[8];
;     { const u32x2* mr = (const u32x2*)(M + (size_t)row * D_) + lane;
; #pragma unroll
;       for (int j = 0; j < 8; ++j) { if constexpr (FIRST) hc.f[j] = ((const f32x4*)(xin + (size_t)row * D_) + lane)[64 * j]; else hc.f[j] = ((const u32x2*)(HB + (size_t)row * D_) + lane)[64 * j]; mw[j] = mr[64 * j]; } }
;     ...
;         for (int j = 0; j < 8; ++j) { const f32x4 gv = ((const f32x4*)gpost)[lane + 64 * j]; hv[j] = hv[j] + mv[j] * rs * gv;
;             if constexpr (LAST) ((f32x4*)(outf + (size_t)row * D_) + lane)[64 * j] = hv[j];
;             else { u32x2 w; w.x = pk2(hv[j][0], hv[j][1]); w.y = pk2(hv[j][2], hv[j][3]); ((u32x2*)(HB + (size_t)row * D_) + lane)[64 * j] = w; }
;             s2 += (hv[j][0] * hv[j][0] + hv[j][1] * hv[j][1]) + (hv[j][2] * hv[j][2] + hv[j][3] * hv[j][3]); }
;         if (MODE == 1) { const float r2 = rsqrtf(wave_sum(s2) * (1.f / D_) + EPS); u32x2* o = (u32x2*)(XN + (size_t)row * D_) + lane;
; #pragma unroll
;             for (int j = 0; j < 8; ++j) { const f32x4 gv = ((const f32x4*)gnext)[lane + 64 * j]; u32x2 w; w.x = pk2(hv[j][0] * r2 * gv[0], hv[j][1] * r2 * gv[1]); w.y = pk2(hv[j][2] * r2 * gv[2], hv[j][3] * r2 * gv[3]); o[64 * j] = w; } }
.LBB0_759:
	s_cmp_lt_i32 s62, 10
	s_cselect_b64 s[8:9], -1, 0
	s_and_b64 s[6:7], s[8:9], s[6:7]
	s_andn2_b64 vcc, exec, s[6:7]
	s_cbranch_vccnz .LBB0_765
	v_mov_b32_e32 v2, v1
	s_lshl_b32 s3, s2, 3
	v_readfirstlane_b32 s8, v2
	s_ashr_i32 s8, s8, 6
	s_add_i32 s8, s8, s3
	s_mov_b64 s[12:13], s[0:1]
	s_cmpk_gt_i32 s8, 0x3fff
	s_cbranch_scc1 .LBB0_765
	s_load_dwordx2 s[14:15], s[12:13], 0x10
	s_load_dwordx2 s[18:19], s[12:13], 0x30
	s_waitcnt lgkmcnt(0)
	s_load_dwordx2 s[16:17], s[12:13], 0xc8
	s_lshl_b32 s10, s74, 3
	v_and_b32_e32 v12, 63, v2
	v_lshlrev_b32_e32 v2, 3, v12
	s_add_u32 s14, s14, 0x2000
	s_addc_u32 s15, s15, 0
	s_ashr_i32 s9, s8, 31
	s_lshl_b64 s[12:13], s[8:9], 12
	s_waitcnt lgkmcnt(0)
	s_add_u32 s12, s16, s12
	v_mov_b32_e32 v3, 0
	s_addc_u32 s13, s17, s13
	v_lshl_add_u64 v[4:5], s[12:13], 0, v[2:3]
	s_mov_b32 s3, 0xc000
	s_mov_b64 s[20:21], 0x14dcc000
	v_add_co_u32_e32 v10, vcc, s3, v4
	v_lshl_add_u64 v[6:7], v[4:5], 0, s[20:21]
	s_mov_b64 s[20:21], 0xc000
	v_addc_co_u32_e32 v11, vcc, 0, v5, vcc
	s_mov_b32 s9, 0x14dcc000
	v_lshl_add_u64 v[8:9], v[4:5], 0, s[20:21]
	v_add_co_u32_e32 v4, vcc, s9, v4
	v_lshlrev_b32_e32 v20, 4, v12
	s_nop 0
	v_addc_co_u32_e32 v5, vcc, 0, v5, vcc
	global_load_dwordx2 v[92:93], v[6:7], off offset:512
	global_load_dwordx2 v[90:91], v[6:7], off offset:1024
	global_load_dwordx2 v[86:87], v[6:7], off offset:1536
	global_load_dwordx2 v[84:85], v[6:7], off offset:2048
	global_load_dwordx2 v[72:73], v[8:9], off offset:1024
	global_load_dwordx2 v[70:71], v[8:9], off offset:1536
	global_load_dwordx2 v[68:69], v[8:9], off offset:2048
	global_load_dwordx2 v[66:67], v[8:9], off offset:2560
	global_load_dwordx2 v[76:77], v[10:11], off
	global_load_dwordx2 v[94:95], v[4:5], off
	global_load_dwordx2 v[64:65], v[8:9], off offset:3072
	global_load_dwordx2 v[62:63], v[8:9], off offset:3584
	global_load_dwordx2 v[74:75], v[8:9], off offset:512
	global_load_dwordx2 v[82:83], v[6:7], off offset:2560
	global_load_dwordx2 v[80:81], v[6:7], off offset:3072
	global_load_dwordx2 v[78:79], v[6:7], off offset:3584
	v_mbcnt_lo_u32_b32 v4, -1, 0
	v_mbcnt_hi_u32_b32 v4, -1, v4
	v_and_b32_e32 v5, 64, v4
	v_add_u32_e32 v5, 64, v5
	v_xor_b32_e32 v6, 1, v4
	v_cmp_lt_i32_e32 vcc, v6, v5
	v_mov_b32_e32 v21, v3
	v_or_b32_e32 v22, 0x1000, v20
	v_cndmask_b32_e32 v6, v4, v6, vcc
	v_lshlrev_b32_e32 v103, 2, v6
	v_xor_b32_e32 v6, 2, v4
	v_cmp_lt_i32_e32 vcc, v6, v5
	v_mov_b32_e32 v23, v3
	v_or_b32_e32 v24, 0x1400, v20
	v_cndmask_b32_e32 v6, v4, v6, vcc
	v_lshlrev_b32_e32 v118, 2, v6
	v_xor_b32_e32 v6, 4, v4
	v_cmp_lt_i32_e32 vcc, v6, v5
	v_mov_b32_e32 v25, v3
	v_or_b32_e32 v26, 0x1800, v20
	v_cndmask_b32_e32 v6, v4, v6, vcc
	v_lshlrev_b32_e32 v119, 2, v6
	v_xor_b32_e32 v6, 8, v4
	v_cmp_lt_i32_e32 vcc, v6, v5
	v_mov_b32_e32 v27, v3
	v_or_b32_e32 v28, 0x1c00, v20
	v_cndmask_b32_e32 v6, v4, v6, vcc
	v_lshlrev_b32_e32 v120, 2, v6
	v_xor_b32_e32 v6, 16, v4
	v_cmp_lt_i32_e32 vcc, v6, v5
	v_mov_b32_e32 v29, v3
	v_lshl_add_u64 v[8:9], s[18:19], 0, v[24:25]
	v_cndmask_b32_e32 v6, v4, v6, vcc
	v_lshlrev_b32_e32 v121, 2, v6
	v_xor_b32_e32 v6, 32, v4
	v_cmp_lt_i32_e32 vcc, v6, v5
	v_lshl_add_u64 v[10:11], s[18:19], 0, v[26:27]
	v_lshl_add_u64 v[12:13], s[18:19], 0, v[28:29]
	v_cndmask_b32_e32 v4, v4, v6, vcc
	v_lshlrev_b32_e32 v122, 2, v4
	v_lshl_add_u64 v[4:5], s[18:19], 0, v[20:21]
	v_lshl_add_u64 v[6:7], s[18:19], 0, v[22:23]
	s_add_i32 s18, s8, s10
	v_lshl_add_u64 v[14:15], s[14:15], 0, v[20:21]
	v_or_b32_e32 v16, 0x400, v20
	v_mov_b32_e32 v17, v3
	v_or_b32_e32 v18, 0x800, v20
	v_mov_b32_e32 v19, v3
	v_or_b32_e32 v20, 0xc00, v20
	s_ashr_i32 s11, s10, 31
	s_ashr_i32 s19, s18, 31
	v_lshl_add_u64 v[16:17], s[14:15], 0, v[16:17]
	v_lshl_add_u64 v[18:19], s[14:15], 0, v[18:19]
	v_lshl_add_u64 v[20:21], s[14:15], 0, v[20:21]
	v_lshl_add_u64 v[22:23], s[14:15], 0, v[22:23]
	v_lshl_add_u64 v[24:25], s[14:15], 0, v[24:25]
	v_lshl_add_u64 v[26:27], s[14:15], 0, v[26:27]
	v_lshl_add_u64 v[28:29], s[14:15], 0, v[28:29]
	s_lshl_b64 s[14:15], s[10:11], 12
	s_lshl_b64 s[18:19], s[18:19], 12
	s_add_u32 s16, s16, s18
	s_addc_u32 s17, s17, s19
	v_mov_b32_e32 v123, 0x358637bd
	s_mov_b32 s9, 0x800000
	s_movk_i32 s11, 0x7fff
	s_mov_b32 s20, 0x10dcc000
	v_mov_b32_e32 v124, 1
	v_and_b32_e32 v135, 63, v1
	v_lshlrev_b32_e32 v135, 4, v135
	global_load_dwordx4 v[136:139], v[4:5], off
	global_load_dwordx4 v[140:143], v[4:5], off offset:1024
	global_load_dwordx4 v[144:147], v[4:5], off offset:2048
	global_load_dwordx4 v[148:151], v[4:5], off offset:3072
	global_load_dwordx4 v[152:155], v[6:7], off
	global_load_dwordx4 v[156:159], v[8:9], off
	global_load_dwordx4 v[160:163], v[10:11], off
	global_load_dwordx4 v[164:167], v[12:13], off
	global_load_dwordx4 v[168:171], v[14:15], off
	global_load_dwordx4 v[172:175], v[16:17], off
	global_load_dwordx4 v[176:179], v[18:19], off
	global_load_dwordx4 v[180:183], v[20:21], off
	global_load_dwordx4 v[184:187], v[22:23], off
	global_load_dwordx4 v[188:191], v[24:25], off
	global_load_dwordx4 v[192:195], v[26:27], off
	global_load_dwordx4 v[196:199], v[28:29], off
	s_waitcnt vmcnt(0)
	ds_write_b128 v135, v[136:139] offset:0
	ds_write_b128 v135, v[140:143] offset:1024
	ds_write_b128 v135, v[144:147] offset:2048
	ds_write_b128 v135, v[148:151] offset:3072
	ds_write_b128 v135, v[152:155] offset:4096
	ds_write_b128 v135, v[156:159] offset:5120
	ds_write_b128 v135, v[160:163] offset:6144
	ds_write_b128 v135, v[164:167] offset:7168
	ds_write_b128 v135, v[168:171] offset:8192
	ds_write_b128 v135, v[172:175] offset:9216
	ds_write_b128 v135, v[176:179] offset:10240
	ds_write_b128 v135, v[180:183] offset:11264
	ds_write_b128 v135, v[184:187] offset:12288
	ds_write_b128 v135, v[188:191] offset:13312
	ds_write_b128 v135, v[192:195] offset:14336
	ds_write_b128 v135, v[196:199] offset:15360
	s_waitcnt lgkmcnt(0)
	s_branch .LBB0_763
; DI unsigned pk2(float lo, float hi) { return f2bf(lo) | (f2bf(hi) << 16); }
; DI float lo_f(unsigned w) { return __uint_as_float(w << 16); }
; DI float hi_f(unsigned w) { return __uint_as_float(w & 0xffff0000u); }
; template <int MODE, bool FIRST, bool LAST>
; DI void phase_rowpass(const float* xin, const bf16_t* M, const float* gpost, float* outf, bf16_t* HB, bf16_t* XN, const float* gnext, int gw, int NGW, int lane) {
;     ...
;         f32x4 hv[8], mv[8]; float ss = 0.f;
; #pragma unroll
;         for (int j = 0; j < 8; ++j) { const u32x2 w = mw[j]; mv[j] = (f32x4){lo_f(w.x), hi_f(w.x), lo_f(w.y), hi_f(w.y)};
;             if constexpr (FIRST) hv[j] = hc.f[j]; else { const u32x2 hw = hc.f[j]; hv[j] = (f32x4){lo_f(hw.x), hi_f(hw.x), lo_f(hw.y), hi_f(hw.y)}; }
;             ss += (mv[j][0] * mv[j][0] + mv[j][1] * mv[j][1]) + (mv[j][2] * mv[j][2] + mv[j][3] * mv[j][3]); }
;         const float rs = rsqrtf(wave_sum(ss) * (1.f / D_) + EPS);
;         float s2 = 0.f;
; #pragma unroll
;         for (int j = 0; j < 8; ++j) { const f32x4 gv = ((const f32x4*)gpost)[lane + 64 * j]; hv[j] = hv[j] + mv[j] * rs * gv;
;             if constexpr (LAST) ((f32x4*)(outf + (size_t)row * D_) + lane)[64 * j] = hv[j];
;             else { u32x2 w; w.x = pk2(hv[j][0], hv[j][1]); w.y = pk2(hv[j][2], hv[j][3]); ((u32x2*)(HB + (size_t)row * D_) + lane)[64 * j] = w; }
.LBB0_762:
	s_waitcnt vmcnt(0)
	v_and_b32_e32 v127, 0xffff0000, v94
	v_and_b32_e32 v126, 0xffff0000, v92
	v_and_b32_e32 v129, 0xffff0000, v95
	v_and_b32_e32 v128, 0xffff0000, v93
	v_lshlrev_b32_e32 v115, 16, v94
	v_lshlrev_b32_e32 v114, 16, v92
	v_lshlrev_b32_e32 v117, 16, v95
	v_lshlrev_b32_e32 v116, 16, v93
	v_pk_mul_f32 v[88:89], v[126:127], v[126:127]
	v_pk_mul_f32 v[92:93], v[128:129], v[128:129]
	v_and_b32_e32 v113, 0xffff0000, v91
	v_and_b32_e32 v112, 0xffff0000, v90
	v_pk_fma_f32 v[88:89], v[114:115], v[114:115], v[88:89]
	v_pk_fma_f32 v[92:93], v[116:117], v[116:117], v[92:93]
	v_lshlrev_b32_e32 v111, 16, v91
	v_lshlrev_b32_e32 v110, 16, v90
	v_pk_mul_f32 v[90:91], v[112:113], v[112:113]
	v_pk_add_f32 v[88:89], v[88:89], v[92:93]
	v_pk_fma_f32 v[90:91], v[110:111], v[110:111], v[90:91]
	v_pk_add_f32 v[88:89], v[88:89], v[88:89] op_sel_hi:[0,1]
	v_pk_add_f32 v[92:93], v[90:91], v[90:91] op_sel_hi:[0,1]
	v_lshlrev_b32_e32 v108, 16, v86
	v_and_b32_e32 v109, 0xffff0000, v86
	v_lshlrev_b32_e32 v86, 16, v87
	v_lshlrev_b32_e32 v90, 16, v84
	v_mul_f32_e32 v91, v108, v108
	v_mul_f32_e32 v95, v109, v109
	v_and_b32_e32 v87, 0xffff0000, v87
	v_mul_f32_e32 v88, v86, v86
	v_mov_b32_e32 v94, v90
	v_pk_fma_f32 v[96:97], v[86:87], v[86:87], v[88:89] op_sel_hi:[1,1,0]
	v_and_b32_e32 v125, 0xffff0000, v84
	v_lshlrev_b32_e32 v100, 16, v85
	v_and_b32_e32 v101, 0xffff0000, v85
	v_pk_add_f32 v[94:95], v[90:91], v[94:95]
	v_mul_f32_e32 v96, v125, v125
	v_mul_f32_e32 v92, v100, v100
	v_mul_f32_e32 v88, v101, v101
	v_mul_f32_e32 v84, v90, v90
	v_mov_b32_e32 v85, v95
	v_pk_add_f32 v[84:85], v[84:85], v[96:97]
	v_pk_add_f32 v[88:89], v[92:93], v[88:89]
	v_lshlrev_b32_e32 v93, 16, v83
	v_pk_add_f32 v[84:85], v[84:85], v[88:89]
	v_lshlrev_b32_e32 v92, 16, v82
	v_pk_add_f32 v[98:99], v[84:85], v[84:85] op_sel_hi:[0,1]
	v_and_b32_e32 v95, 0xffff0000, v83
	v_and_b32_e32 v94, 0xffff0000, v82
	ds_read_b128 v[82:85], v135 offset:0
	v_pk_mul_f32 v[88:89], v[94:95], v[94:95]
	v_lshlrev_b32_e32 v104, 16, v80
	v_pk_fma_f32 v[88:89], v[92:93], v[92:93], v[88:89]
	v_and_b32_e32 v105, 0xffff0000, v80
	v_pk_add_f32 v[130:131], v[88:89], v[88:89] op_sel_hi:[0,1]
	v_lshlrev_b32_e32 v106, 16, v81
	v_lshlrev_b32_e32 v88, 16, v78
	v_mul_f32_e32 v89, v104, v104
	v_mul_f32_e32 v133, v105, v105
	v_and_b32_e32 v107, 0xffff0000, v81
	v_mul_f32_e32 v80, v106, v106
	v_mov_b32_e32 v132, v88
	v_pk_fma_f32 v[80:81], v[106:107], v[106:107], v[80:81] op_sel_hi:[1,1,0]
	v_and_b32_e32 v134, 0xffff0000, v78
	v_lshlrev_b32_e32 v96, 16, v79
	v_and_b32_e32 v97, 0xffff0000, v79
	v_pk_add_f32 v[132:133], v[88:89], v[132:133]
	v_mul_f32_e32 v80, v134, v134
	v_mul_f32_e32 v130, v96, v96
	v_mul_f32_e32 v98, v97, v97
	v_mul_f32_e32 v78, v88, v88
	v_mov_b32_e32 v79, v133
	v_pk_add_f32 v[78:79], v[78:79], v[80:81]
	v_pk_add_f32 v[80:81], v[130:131], v[98:99]
	v_mov_b32_e32 v130, v115
	v_pk_add_f32 v[78:79], v[78:79], v[80:81]
	v_mov_b32_e32 v131, v127
	v_add_f32_e32 v78, v78, v79
	ds_bpermute_b32 v79, v103, v78
	v_mov_b32_e32 v98, v117
	v_mov_b32_e32 v99, v129
	v_and_b32_e32 v81, 0xffff0000, v77
	v_mov_b32_e32 v115, v126
	s_waitcnt lgkmcnt(0)
	v_add_f32_e32 v78, v78, v79
	ds_bpermute_b32 v79, v118, v78
	v_mov_b32_e32 v117, v128
	v_mov_b32_e32 v126, v110
	v_mov_b32_e32 v127, v112
	v_mov_b32_e32 v112, v111
	s_waitcnt lgkmcnt(0)
	v_add_f32_e32 v78, v78, v79
	ds_bpermute_b32 v79, v119, v78
	s_waitcnt lgkmcnt(0)
	v_add_f32_e32 v78, v78, v79
	ds_bpermute_b32 v79, v120, v78
	s_waitcnt lgkmcnt(0)
	v_add_f32_e32 v78, v78, v79
	ds_bpermute_b32 v79, v121, v78
	s_waitcnt lgkmcnt(0)
	v_add_f32_e32 v79, v78, v79
	ds_bpermute_b32 v80, v122, v79
	v_lshlrev_b32_e32 v78, 16, v76
	s_waitcnt lgkmcnt(0)
	v_add_f32_e32 v79, v79, v80
	v_fmamk_f32 v79, v79, 0x3a000000, v123
	v_mul_f32_e32 v80, 0x4b800000, v79
	v_cmp_gt_f32_e32 vcc, s9, v79
	s_nop 1
	v_cndmask_b32_e32 v79, v79, v80, vcc
	v_rsq_f32_e32 v89, v79
	v_and_b32_e32 v79, 0xffff0000, v76
	v_lshlrev_b32_e32 v80, 16, v77
	v_mul_f32_e32 v76, 0x45800000, v89
	v_cndmask_b32_e32 v102, v89, v76, vcc
	v_pk_mul_f32 v[130:131], v[130:131], v[102:103] op_sel_hi:[1,0]
	v_pk_mul_f32 v[98:99], v[98:99], v[102:103] op_sel_hi:[1,0]
	v_lshl_add_u64 v[76:77], s[12:13], 0, v[2:3]
	s_waitcnt vmcnt(0) lgkmcnt(0)
	v_pk_fma_f32 v[78:79], v[82:83], v[130:131], v[78:79]
	v_pk_fma_f32 v[80:81], v[84:85], v[98:99], v[80:81]
	v_and_b32_sdwa v83, v78, v124 dst_sel:DWORD dst_unused:UNUSED_PAD src0_sel:WORD_1 src1_sel:DWORD
	v_add3_u32 v84, v78, v83, s11
	v_and_b32_sdwa v83, v81, v124 dst_sel:DWORD dst_unused:UNUSED_PAD src0_sel:WORD_1 src1_sel:DWORD
	v_and_b32_sdwa v85, v79, v124 dst_sel:DWORD dst_unused:UNUSED_PAD src0_sel:WORD_1 src1_sel:DWORD
	v_and_b32_sdwa v82, v80, v124 dst_sel:DWORD dst_unused:UNUSED_PAD src0_sel:WORD_1 src1_sel:DWORD
	v_add3_u32 v83, v81, v83, s11
	v_add3_u32 v85, v79, v85, s11
	v_add3_u32 v82, v80, v82, s11
	v_and_b32_e32 v83, 0xffff0000, v83
	v_and_b32_e32 v85, 0xffff0000, v85
	v_add_co_u32_e32 v98, vcc, s3, v76
	v_or_b32_sdwa v83, v83, v82 dst_sel:DWORD dst_unused:UNUSED_PAD src0_sel:DWORD src1_sel:WORD_1
	v_or_b32_sdwa v82, v85, v84 dst_sel:DWORD dst_unused:UNUSED_PAD src0_sel:DWORD src1_sel:WORD_1
	v_addc_co_u32_e32 v99, vcc, 0, v77, vcc
	global_store_dwordx2 v[98:99], v[82:83], off
	s_nop 0
	ds_read_b128 v[82:85], v135 offset:1024
	v_lshlrev_b32_e32 v130, 16, v74
	v_and_b32_e32 v131, 0xffff0000, v74
	v_lshlrev_b32_e32 v74, 16, v75
	v_and_b32_e32 v75, 0xffff0000, v75
	v_pk_mul_f32 v[114:115], v[114:115], v[102:103] op_sel_hi:[1,0]
	v_pk_mul_f32 v[116:117], v[116:117], v[102:103] op_sel_hi:[1,0]
	v_pk_mul_f32 v[110:111], v[102:103], v[126:127] op_sel_hi:[0,1]
	v_pk_mul_f32 v[112:113], v[102:103], v[112:113] op_sel_hi:[0,1]
	v_pk_mul_f32 v[108:109], v[108:109], v[102:103] op_sel_hi:[1,0]
	v_pk_mul_f32 v[86:87], v[86:87], v[102:103] op_sel_hi:[1,0]
	v_pk_mul_f32 v[100:101], v[100:101], v[102:103] op_sel_hi:[1,0]
	v_pk_mul_f32 v[96:97], v[96:97], v[102:103] op_sel_hi:[1,0]
	s_add_u32 s12, s12, s14
	s_addc_u32 s13, s13, s15
	s_add_u32 s16, s16, s14
	s_addc_u32 s17, s17, s15
	s_waitcnt lgkmcnt(0)
; DI unsigned pk2(float lo, float hi) { return f2bf(lo) | (f2bf(hi) << 16); }
; template <int MODE, bool FIRST, bool LAST>
; DI void phase_rowpass(const float* xin, const bf16_t* M, const float* gpost, float* outf, bf16_t* HB, bf16_t* XN, const float* gnext, int gw, int NGW, int lane) {
;     ...
;         for (int j = 0; j < 8; ++j) { const f32x4 gv = ((const f32x4*)gpost)[lane + 64 * j]; hv[j] = hv[j] + mv[j] * rs * gv;
;             if constexpr (LAST) ((f32x4*)(outf + (size_t)row * D_) + lane)[64 * j] = hv[j];
;             else { u32x2 w; w.x = pk2(hv[j][0], hv[j][1]); w.y = pk2(hv[j][2], hv[j][3]); ((u32x2*)(HB + (size_t)row * D_) + lane)[64 * j] = w; }
	v_pk_fma_f32 v[74:75], v[84:85], v[116:117], v[74:75]
	v_pk_fma_f32 v[82:83], v[82:83], v[114:115], v[130:131]
	v_and_b32_sdwa v89, v75, v124 dst_sel:DWORD dst_unused:UNUSED_PAD src0_sel:WORD_1 src1_sel:DWORD
	v_and_b32_sdwa v85, v82, v124 dst_sel:DWORD dst_unused:UNUSED_PAD src0_sel:WORD_1 src1_sel:DWORD
	v_and_b32_sdwa v91, v83, v124 dst_sel:DWORD dst_unused:UNUSED_PAD src0_sel:WORD_1 src1_sel:DWORD
	v_and_b32_sdwa v84, v74, v124 dst_sel:DWORD dst_unused:UNUSED_PAD src0_sel:WORD_1 src1_sel:DWORD
	v_add3_u32 v114, v82, v85, s11
	v_add3_u32 v85, v75, v89, s11
	v_add3_u32 v89, v83, v91, s11
	v_add3_u32 v84, v74, v84, s11
	v_and_b32_e32 v85, 0xffff0000, v85
	v_and_b32_e32 v89, 0xffff0000, v89
	v_or_b32_sdwa v85, v85, v84 dst_sel:DWORD dst_unused:UNUSED_PAD src0_sel:DWORD src1_sel:WORD_1
	v_or_b32_sdwa v84, v89, v114 dst_sel:DWORD dst_unused:UNUSED_PAD src0_sel:DWORD src1_sel:WORD_1
	global_store_dwordx2 v[98:99], v[84:85], off offset:512
	s_nop 0
	ds_read_b128 v[114:117], v135 offset:2048
	v_lshlrev_b32_e32 v84, 16, v72
	v_and_b32_e32 v85, 0xffff0000, v72
	v_lshlrev_b32_e32 v72, 16, v73
	v_and_b32_e32 v73, 0xffff0000, v73
	s_waitcnt lgkmcnt(0)
	v_pk_fma_f32 v[72:73], v[116:117], v[112:113], v[72:73]
	v_pk_fma_f32 v[84:85], v[114:115], v[110:111], v[84:85]
	v_and_b32_sdwa v110, v73, v124 dst_sel:DWORD dst_unused:UNUSED_PAD src0_sel:WORD_1 src1_sel:DWORD
	v_and_b32_sdwa v111, v85, v124 dst_sel:DWORD dst_unused:UNUSED_PAD src0_sel:WORD_1 src1_sel:DWORD
	v_and_b32_sdwa v89, v72, v124 dst_sel:DWORD dst_unused:UNUSED_PAD src0_sel:WORD_1 src1_sel:DWORD
	v_and_b32_sdwa v91, v84, v124 dst_sel:DWORD dst_unused:UNUSED_PAD src0_sel:WORD_1 src1_sel:DWORD
	v_add3_u32 v110, v73, v110, s11
	v_add3_u32 v111, v85, v111, s11
	v_add3_u32 v91, v84, v91, s11
	v_add3_u32 v89, v72, v89, s11
	v_and_b32_e32 v110, 0xffff0000, v110
	v_and_b32_e32 v112, 0xffff0000, v111
	v_or_b32_sdwa v111, v110, v89 dst_sel:DWORD dst_unused:UNUSED_PAD src0_sel:DWORD src1_sel:WORD_1
	v_or_b32_sdwa v110, v112, v91 dst_sel:DWORD dst_unused:UNUSED_PAD src0_sel:DWORD src1_sel:WORD_1
	global_store_dwordx2 v[98:99], v[110:111], off offset:1024
	s_nop 0
	ds_read_b128 v[110:113], v135 offset:3072
	v_lshlrev_b32_e32 v114, 16, v70
	v_and_b32_e32 v115, 0xffff0000, v70
	v_lshlrev_b32_e32 v70, 16, v71
	v_and_b32_e32 v71, 0xffff0000, v71
	s_waitcnt lgkmcnt(0)
	v_pk_fma_f32 v[70:71], v[112:113], v[86:87], v[70:71]
	v_pk_fma_f32 v[86:87], v[110:111], v[108:109], v[114:115]
	v_and_b32_sdwa v108, v71, v124 dst_sel:DWORD dst_unused:UNUSED_PAD src0_sel:WORD_1 src1_sel:DWORD
	v_and_b32_sdwa v109, v87, v124 dst_sel:DWORD dst_unused:UNUSED_PAD src0_sel:WORD_1 src1_sel:DWORD
	v_and_b32_sdwa v89, v70, v124 dst_sel:DWORD dst_unused:UNUSED_PAD src0_sel:WORD_1 src1_sel:DWORD
	v_and_b32_sdwa v91, v86, v124 dst_sel:DWORD dst_unused:UNUSED_PAD src0_sel:WORD_1 src1_sel:DWORD
	v_add3_u32 v108, v71, v108, s11
	v_add3_u32 v109, v87, v109, s11
	v_add3_u32 v91, v86, v91, s11
	v_add3_u32 v89, v70, v89, s11
	v_and_b32_e32 v108, 0xffff0000, v108
	v_and_b32_e32 v110, 0xffff0000, v109
	v_or_b32_sdwa v109, v108, v89 dst_sel:DWORD dst_unused:UNUSED_PAD src0_sel:DWORD src1_sel:WORD_1
	v_or_b32_sdwa v108, v110, v91 dst_sel:DWORD dst_unused:UNUSED_PAD src0_sel:DWORD src1_sel:WORD_1
	global_store_dwordx2 v[98:99], v[108:109], off offset:1536
	s_nop 0
	ds_read_b128 v[108:111], v135 offset:4096
	v_mov_b32_e32 v91, v125
	v_lshlrev_b32_e32 v112, 16, v68
	v_and_b32_e32 v113, 0xffff0000, v68
	v_lshlrev_b32_e32 v68, 16, v69
	v_and_b32_e32 v69, 0xffff0000, v69
	v_pk_mul_f32 v[90:91], v[90:91], v[102:103] op_sel_hi:[1,0]
	s_waitcnt lgkmcnt(0)
	v_pk_fma_f32 v[68:69], v[110:111], v[100:101], v[68:69]
	v_pk_fma_f32 v[90:91], v[108:109], v[90:91], v[112:113]
	v_and_b32_sdwa v101, v69, v124 dst_sel:DWORD dst_unused:UNUSED_PAD src0_sel:WORD_1 src1_sel:DWORD
	v_and_b32_sdwa v108, v91, v124 dst_sel:DWORD dst_unused:UNUSED_PAD src0_sel:WORD_1 src1_sel:DWORD
	v_and_b32_sdwa v89, v68, v124 dst_sel:DWORD dst_unused:UNUSED_PAD src0_sel:WORD_1 src1_sel:DWORD
	v_and_b32_sdwa v100, v90, v124 dst_sel:DWORD dst_unused:UNUSED_PAD src0_sel:WORD_1 src1_sel:DWORD
	v_add3_u32 v101, v69, v101, s11
	v_add3_u32 v108, v91, v108, s11
	v_add3_u32 v100, v90, v100, s11
	v_add3_u32 v89, v68, v89, s11
	v_and_b32_e32 v101, 0xffff0000, v101
	v_and_b32_e32 v108, 0xffff0000, v108
	v_or_b32_sdwa v101, v101, v89 dst_sel:DWORD dst_unused:UNUSED_PAD src0_sel:DWORD src1_sel:WORD_1
	v_or_b32_sdwa v100, v108, v100 dst_sel:DWORD dst_unused:UNUSED_PAD src0_sel:DWORD src1_sel:WORD_1
	global_store_dwordx2 v[98:99], v[100:101], off offset:2048
	s_nop 0
	ds_read_b128 v[108:111], v135 offset:5120
	v_mov_b32_e32 v112, v92
	v_mov_b32_e32 v113, v94
	v_mov_b32_e32 v94, v93
	v_lshlrev_b32_e32 v100, 16, v66
	v_and_b32_e32 v101, 0xffff0000, v66
	v_lshlrev_b32_e32 v66, 16, v67
	v_and_b32_e32 v67, 0xffff0000, v67
	v_pk_mul_f32 v[92:93], v[102:103], v[112:113] op_sel_hi:[0,1]
	v_pk_mul_f32 v[94:95], v[102:103], v[94:95] op_sel_hi:[0,1]
	v_mov_b32_e32 v112, v82
	v_mov_b32_e32 v113, v74
	s_waitcnt lgkmcnt(0)
; DI unsigned pk2(float lo, float hi) { return f2bf(lo) | (f2bf(hi) << 16); }
; template <int MODE, bool FIRST, bool LAST>
; DI void phase_rowpass(const float* xin, const bf16_t* M, const float* gpost, float* outf, bf16_t* HB, bf16_t* XN, const float* gnext, int gw, int NGW, int lane) {
;     ...
;         for (int j = 0; j < 8; ++j) { const f32x4 gv = ((const f32x4*)gpost)[lane + 64 * j]; hv[j] = hv[j] + mv[j] * rs * gv;
;             if constexpr (LAST) ((f32x4*)(outf + (size_t)row * D_) + lane)[64 * j] = hv[j];
;             else { u32x2 w; w.x = pk2(hv[j][0], hv[j][1]); w.y = pk2(hv[j][2], hv[j][3]); ((u32x2*)(HB + (size_t)row * D_) + lane)[64 * j] = w; }
;             s2 += (hv[j][0] * hv[j][0] + hv[j][1] * hv[j][1]) + (hv[j][2] * hv[j][2] + hv[j][3] * hv[j][3]); }
;         if (MODE == 1) { const float r2 = rsqrtf(wave_sum(s2) * (1.f / D_) + EPS); u32x2* o = (u32x2*)(XN + (size_t)row * D_) + lane;
	v_pk_fma_f32 v[66:67], v[110:111], v[94:95], v[66:67]
	v_pk_fma_f32 v[92:93], v[108:109], v[92:93], v[100:101]
	v_and_b32_sdwa v95, v67, v124 dst_sel:DWORD dst_unused:UNUSED_PAD src0_sel:WORD_1 src1_sel:DWORD
	v_and_b32_sdwa v100, v93, v124 dst_sel:DWORD dst_unused:UNUSED_PAD src0_sel:WORD_1 src1_sel:DWORD
	v_and_b32_sdwa v89, v66, v124 dst_sel:DWORD dst_unused:UNUSED_PAD src0_sel:WORD_1 src1_sel:DWORD
	v_and_b32_sdwa v94, v92, v124 dst_sel:DWORD dst_unused:UNUSED_PAD src0_sel:WORD_1 src1_sel:DWORD
	v_add3_u32 v95, v67, v95, s11
	v_add3_u32 v100, v93, v100, s11
	v_add3_u32 v94, v92, v94, s11
	v_add3_u32 v89, v66, v89, s11
	v_and_b32_e32 v95, 0xffff0000, v95
	v_and_b32_e32 v100, 0xffff0000, v100
	v_or_b32_sdwa v95, v95, v89 dst_sel:DWORD dst_unused:UNUSED_PAD src0_sel:DWORD src1_sel:WORD_1
	v_or_b32_sdwa v94, v100, v94 dst_sel:DWORD dst_unused:UNUSED_PAD src0_sel:DWORD src1_sel:WORD_1
	global_store_dwordx2 v[98:99], v[94:95], off offset:2560
	s_nop 0
	ds_read_b128 v[108:111], v135 offset:6144
	v_lshlrev_b32_e32 v94, 16, v64
	v_and_b32_e32 v95, 0xffff0000, v64
	v_lshlrev_b32_e32 v64, 16, v65
	v_and_b32_e32 v65, 0xffff0000, v65
	v_pk_mul_f32 v[100:101], v[104:105], v[102:103] op_sel_hi:[1,0]
	v_pk_mul_f32 v[104:105], v[106:107], v[102:103] op_sel_hi:[1,0]
	s_waitcnt lgkmcnt(0)
	v_pk_fma_f32 v[94:95], v[100:101], v[108:109], v[94:95]
	v_pk_fma_f32 v[64:65], v[104:105], v[110:111], v[64:65]
	v_and_b32_sdwa v104, v95, v124 dst_sel:DWORD dst_unused:UNUSED_PAD src0_sel:WORD_1 src1_sel:DWORD
	v_and_b32_sdwa v101, v65, v124 dst_sel:DWORD dst_unused:UNUSED_PAD src0_sel:WORD_1 src1_sel:DWORD
	v_and_b32_sdwa v89, v64, v124 dst_sel:DWORD dst_unused:UNUSED_PAD src0_sel:WORD_1 src1_sel:DWORD
	v_and_b32_sdwa v100, v94, v124 dst_sel:DWORD dst_unused:UNUSED_PAD src0_sel:WORD_1 src1_sel:DWORD
	v_add3_u32 v101, v65, v101, s11
	v_add3_u32 v104, v95, v104, s11
	v_add3_u32 v100, v94, v100, s11
	v_add3_u32 v89, v64, v89, s11
	v_and_b32_e32 v101, 0xffff0000, v101
	v_and_b32_e32 v104, 0xffff0000, v104
	v_or_b32_sdwa v101, v101, v89 dst_sel:DWORD dst_unused:UNUSED_PAD src0_sel:DWORD src1_sel:WORD_1
	v_or_b32_sdwa v100, v104, v100 dst_sel:DWORD dst_unused:UNUSED_PAD src0_sel:DWORD src1_sel:WORD_1
	global_store_dwordx2 v[98:99], v[100:101], off offset:3072
	s_nop 0
	ds_read_b128 v[104:107], v135 offset:7168
	v_mov_b32_e32 v89, v134
	v_lshlrev_b32_e32 v100, 16, v62
	v_and_b32_e32 v101, 0xffff0000, v62
	v_lshlrev_b32_e32 v62, 16, v63
	v_and_b32_e32 v63, 0xffff0000, v63
	v_pk_mul_f32 v[88:89], v[88:89], v[102:103] op_sel_hi:[1,0]
	v_mov_b32_e32 v110, v80
	v_mov_b32_e32 v111, v74
	v_mov_b32_e32 v109, v82
	v_mov_b32_e32 v82, v79
	v_pk_mul_f32 v[110:111], v[110:111], v[110:111]
	v_mov_b32_e32 v74, v81
	v_pk_mul_f32 v[114:115], v[82:83], v[82:83]
	v_pk_fma_f32 v[110:111], v[74:75], v[74:75], v[110:111]
	v_mov_b32_e32 v108, v78
	v_pk_fma_f32 v[108:109], v[108:109], v[108:109], v[114:115]
	v_pk_mul_f32 v[114:115], v[72:73], v[72:73]
	v_pk_add_f32 v[108:109], v[108:109], v[110:111]
	v_pk_mul_f32 v[110:111], v[84:85], v[84:85]
	v_pk_add_f32 v[108:109], v[108:109], v[108:109] op_sel_hi:[0,1]
	v_pk_mov_b32 v[116:117], v[110:111], v[114:115] op_sel:[1,0]
	v_mov_b32_e32 v111, v115
	v_pk_add_f32 v[110:111], v[110:111], v[116:117]
	v_mul_f32_e32 v108, v68, v68
	v_pk_add_f32 v[110:111], v[110:111], v[110:111] op_sel_hi:[0,1]
	v_mul_f32_e32 v110, v69, v69
	s_waitcnt lgkmcnt(0)
	v_pk_fma_f32 v[62:63], v[96:97], v[106:107], v[62:63]
	v_pk_fma_f32 v[88:89], v[88:89], v[104:105], v[100:101]
	v_and_b32_sdwa v96, v63, v124 dst_sel:DWORD dst_unused:UNUSED_PAD src0_sel:WORD_1 src1_sel:DWORD
	v_and_b32_sdwa v97, v89, v124 dst_sel:DWORD dst_unused:UNUSED_PAD src0_sel:WORD_1 src1_sel:DWORD
	v_and_b32_sdwa v74, v62, v124 dst_sel:DWORD dst_unused:UNUSED_PAD src0_sel:WORD_1 src1_sel:DWORD
	v_and_b32_sdwa v82, v88, v124 dst_sel:DWORD dst_unused:UNUSED_PAD src0_sel:WORD_1 src1_sel:DWORD
	v_add3_u32 v96, v63, v96, s11
	v_add3_u32 v97, v89, v97, s11
	v_add3_u32 v82, v88, v82, s11
	v_add3_u32 v74, v62, v74, s11
	v_and_b32_e32 v96, 0xffff0000, v96
	v_and_b32_e32 v100, 0xffff0000, v97
	v_or_b32_sdwa v97, v96, v74 dst_sel:DWORD dst_unused:UNUSED_PAD src0_sel:DWORD src1_sel:WORD_1
	v_or_b32_sdwa v96, v100, v82 dst_sel:DWORD dst_unused:UNUSED_PAD src0_sel:DWORD src1_sel:WORD_1
	global_store_dwordx2 v[98:99], v[96:97], off offset:3584
	s_nop 0
	ds_read_b128 v[104:107], v135 offset:8192
	v_mul_f32_e32 v74, v86, v86
	v_mul_f32_e32 v82, v70, v70
	v_pk_fma_f32 v[96:97], v[86:87], v[86:87], v[74:75] op_sel_hi:[1,1,0]
	v_pk_fma_f32 v[98:99], v[70:71], v[70:71], v[82:83] op_sel_hi:[1,1,0]
	v_mul_f32_e32 v96, v90, v90
	v_mul_f32_e32 v98, v91, v91
	v_pk_add_f32 v[96:97], v[96:97], v[98:99]
	v_pk_add_f32 v[98:99], v[110:111], v[108:109]
	v_pk_mul_f32 v[100:101], v[66:67], v[66:67]
	v_pk_add_f32 v[96:97], v[96:97], v[98:99]
	v_pk_mul_f32 v[98:99], v[92:93], v[92:93]
	v_mul_f32_e32 v74, v94, v94
	v_pk_mov_b32 v[108:109], v[98:99], v[100:101] op_sel:[1,0]
	v_mov_b32_e32 v99, v101
	v_pk_add_f32 v[98:99], v[98:99], v[108:109]
	v_mul_f32_e32 v82, v64, v64
	v_pk_add_f32 v[96:97], v[96:97], v[96:97] op_sel_hi:[0,1]
	v_pk_add_f32 v[98:99], v[98:99], v[98:99] op_sel_hi:[0,1]
	v_pk_fma_f32 v[100:101], v[94:95], v[94:95], v[74:75] op_sel_hi:[1,1,0]
	v_pk_fma_f32 v[108:109], v[64:65], v[64:65], v[82:83] op_sel_hi:[1,1,0]
	v_mul_f32_e32 v100, v88, v88
	v_mul_f32_e32 v108, v89, v89
	v_mul_f32_e32 v96, v62, v62
	v_mul_f32_e32 v98, v63, v63
	v_pk_add_f32 v[100:101], v[100:101], v[108:109]
	v_pk_add_f32 v[96:97], v[98:99], v[96:97]
	s_nop 0
	v_pk_add_f32 v[96:97], v[100:101], v[96:97]
	v_mov_b32_e32 v100, v88
	v_add_f32_e32 v74, v96, v97
	ds_bpermute_b32 v82, v103, v74
	v_add_co_u32_e32 v96, vcc, s20, v76
	v_mov_b32_e32 v76, v78
	s_nop 0
	v_addc_co_u32_e32 v97, vcc, 0, v77, vcc
	s_waitcnt lgkmcnt(0)
; DI unsigned pk2(float lo, float hi) { return f2bf(lo) | (f2bf(hi) << 16); }
; template <int MODE, bool FIRST, bool LAST>
; DI void phase_rowpass(const float* xin, const bf16_t* M, const float* gpost, float* outf, bf16_t* HB, bf16_t* XN, const float* gnext, int gw, int NGW, int lane) {
;     ...
;         if (MODE == 1) { const float r2 = rsqrtf(wave_sum(s2) * (1.f / D_) + EPS); u32x2* o = (u32x2*)(XN + (size_t)row * D_) + lane;
; #pragma unroll
;             for (int j = 0; j < 8; ++j) { const f32x4 gv = ((const f32x4*)gnext)[lane + 64 * j]; u32x2 w; w.x = pk2(hv[j][0] * r2 * gv[0], hv[j][1] * r2 * gv[1]); w.y = pk2(hv[j][2] * r2 * gv[2], hv[j][3] * r2 * gv[3]); o[64 * j] = w; } }
	v_add_f32_e32 v74, v74, v82
	ds_bpermute_b32 v82, v118, v74
	v_mov_b32_e32 v101, v62
	v_mov_b32_e32 v62, v89
	s_waitcnt lgkmcnt(0)
	v_add_f32_e32 v74, v74, v82
	ds_bpermute_b32 v82, v119, v74
	s_waitcnt lgkmcnt(0)
	v_add_f32_e32 v74, v74, v82
	ds_bpermute_b32 v82, v120, v74
	s_waitcnt lgkmcnt(0)
	v_add_f32_e32 v74, v74, v82
	ds_bpermute_b32 v82, v121, v74
	s_waitcnt lgkmcnt(0)
	v_add_f32_e32 v74, v74, v82
	ds_bpermute_b32 v82, v122, v74
	s_waitcnt lgkmcnt(0)
	v_add_f32_e32 v74, v74, v82
	v_fmamk_f32 v74, v74, 0x3a000000, v123
	v_mul_f32_e32 v77, 0x4b800000, v74
	v_cmp_gt_f32_e32 vcc, s9, v74
	s_nop 1
	v_cndmask_b32_e32 v74, v74, v77, vcc
	v_rsq_f32_e32 v74, v74
	v_mov_b32_e32 v77, v80
	v_mov_b32_e32 v80, v79
	v_mul_f32_e32 v78, 0x45800000, v74
	v_cndmask_b32_e32 v98, v74, v78, vcc
	v_pk_mul_f32 v[76:77], v[76:77], v[98:99] op_sel_hi:[1,0]
	v_pk_mul_f32 v[78:79], v[80:81], v[98:99] op_sel_hi:[1,0]
	s_waitcnt lgkmcnt(0)
	v_mov_b32_e32 v80, v104
	v_mov_b32_e32 v81, v106
	v_mov_b32_e32 v106, v105
	v_pk_mul_f32 v[76:77], v[80:81], v[76:77]
	v_pk_mul_f32 v[78:79], v[106:107], v[78:79]
	v_and_b32_sdwa v74, v77, v124 dst_sel:DWORD dst_unused:UNUSED_PAD src0_sel:WORD_1 src1_sel:DWORD
	v_and_b32_sdwa v81, v79, v124 dst_sel:DWORD dst_unused:UNUSED_PAD src0_sel:WORD_1 src1_sel:DWORD
	v_and_b32_sdwa v82, v78, v124 dst_sel:DWORD dst_unused:UNUSED_PAD src0_sel:WORD_1 src1_sel:DWORD
	v_and_b32_sdwa v80, v76, v124 dst_sel:DWORD dst_unused:UNUSED_PAD src0_sel:WORD_1 src1_sel:DWORD
	v_add3_u32 v74, v77, v74, s11
	v_add3_u32 v77, v79, v81, s11
	v_add3_u32 v78, v78, v82, s11
	v_add3_u32 v76, v76, v80, s11
	v_and_b32_e32 v77, 0xffff0000, v77
	v_and_b32_e32 v78, 0xffff0000, v78
	v_or_b32_sdwa v77, v77, v74 dst_sel:DWORD dst_unused:UNUSED_PAD src0_sel:DWORD src1_sel:WORD_1
	v_or_b32_sdwa v76, v78, v76 dst_sel:DWORD dst_unused:UNUSED_PAD src0_sel:DWORD src1_sel:WORD_1
	global_store_dwordx2 v[96:97], v[76:77], off
	s_nop 0
	ds_read_b128 v[76:79], v135 offset:9216
	v_mov_b32_e32 v74, v83
	v_pk_mul_f32 v[74:75], v[74:75], v[98:99] op_sel_hi:[1,0]
	v_pk_mul_f32 v[80:81], v[112:113], v[98:99] op_sel_hi:[1,0]
	v_pk_mul_f32 v[88:89], v[100:101], v[98:99] op_sel_hi:[1,0]
	v_pk_mul_f32 v[62:63], v[62:63], v[98:99] op_sel_hi:[1,0]
	s_andn2_b64 vcc, exec, s[18:19]
	s_waitcnt lgkmcnt(0)
	v_mov_b32_e32 v83, v78
	v_mov_b32_e32 v78, v77
	v_mov_b32_e32 v82, v76
	v_pk_mul_f32 v[74:75], v[78:79], v[74:75]
	v_pk_mul_f32 v[76:77], v[82:83], v[80:81]
	v_and_b32_sdwa v80, v75, v124 dst_sel:DWORD dst_unused:UNUSED_PAD src0_sel:WORD_1 src1_sel:DWORD
	v_and_b32_sdwa v81, v74, v124 dst_sel:DWORD dst_unused:UNUSED_PAD src0_sel:WORD_1 src1_sel:DWORD
	v_and_b32_sdwa v78, v77, v124 dst_sel:DWORD dst_unused:UNUSED_PAD src0_sel:WORD_1 src1_sel:DWORD
	v_and_b32_sdwa v79, v76, v124 dst_sel:DWORD dst_unused:UNUSED_PAD src0_sel:WORD_1 src1_sel:DWORD
	v_add3_u32 v75, v75, v80, s11
	v_add3_u32 v74, v74, v81, s11
	v_add3_u32 v76, v76, v79, s11
	v_add3_u32 v77, v77, v78, s11
	v_and_b32_e32 v75, 0xffff0000, v75
	v_and_b32_e32 v74, 0xffff0000, v74
	v_or_b32_sdwa v75, v75, v77 dst_sel:DWORD dst_unused:UNUSED_PAD src0_sel:DWORD src1_sel:WORD_1
	v_or_b32_sdwa v74, v74, v76 dst_sel:DWORD dst_unused:UNUSED_PAD src0_sel:DWORD src1_sel:WORD_1
	global_store_dwordx2 v[96:97], v[74:75], off offset:512
	s_nop 0
	ds_read_b128 v[74:77], v135 offset:10240
	v_mov_b32_e32 v79, v72
	v_mov_b32_e32 v72, v85
	v_mov_b32_e32 v78, v84
	v_pk_mul_f32 v[72:73], v[72:73], v[98:99] op_sel_hi:[1,0]
	v_pk_mul_f32 v[78:79], v[78:79], v[98:99] op_sel_hi:[1,0]
	v_mov_b64_e32 v[82:83], v[56:57]
	v_mov_b64_e32 v[84:85], v[58:59]
	s_waitcnt lgkmcnt(0)
	v_mov_b32_e32 v81, v76
	v_mov_b32_e32 v76, v75
	v_mov_b32_e32 v80, v74
	v_pk_mul_f32 v[72:73], v[76:77], v[72:73]
	v_pk_mul_f32 v[74:75], v[80:81], v[78:79]
	v_and_b32_sdwa v78, v73, v124 dst_sel:DWORD dst_unused:UNUSED_PAD src0_sel:WORD_1 src1_sel:DWORD
	v_and_b32_sdwa v79, v72, v124 dst_sel:DWORD dst_unused:UNUSED_PAD src0_sel:WORD_1 src1_sel:DWORD
	v_and_b32_sdwa v76, v75, v124 dst_sel:DWORD dst_unused:UNUSED_PAD src0_sel:WORD_1 src1_sel:DWORD
	v_and_b32_sdwa v77, v74, v124 dst_sel:DWORD dst_unused:UNUSED_PAD src0_sel:WORD_1 src1_sel:DWORD
	v_add3_u32 v73, v73, v78, s11
	v_add3_u32 v72, v72, v79, s11
	v_add3_u32 v74, v74, v77, s11
	v_add3_u32 v75, v75, v76, s11
	v_and_b32_e32 v73, 0xffff0000, v73
	v_and_b32_e32 v72, 0xffff0000, v72
	v_or_b32_sdwa v73, v73, v75 dst_sel:DWORD dst_unused:UNUSED_PAD src0_sel:DWORD src1_sel:WORD_1
	v_or_b32_sdwa v72, v72, v74 dst_sel:DWORD dst_unused:UNUSED_PAD src0_sel:DWORD src1_sel:WORD_1
	global_store_dwordx2 v[96:97], v[72:73], off offset:1024
	s_nop 0
	ds_read_b128 v[72:75], v135 offset:11264
	v_mov_b32_e32 v77, v70
	v_mov_b32_e32 v70, v87
	v_mov_b32_e32 v76, v86
	v_pk_mul_f32 v[70:71], v[70:71], v[98:99] op_sel_hi:[1,0]
	v_pk_mul_f32 v[76:77], v[76:77], v[98:99] op_sel_hi:[1,0]
	v_mov_b64_e32 v[80:81], v[54:55]
	v_mov_b64_e32 v[86:87], v[46:47]
	s_waitcnt lgkmcnt(0)
	v_mov_b32_e32 v79, v74
	v_mov_b32_e32 v74, v73
	v_mov_b32_e32 v78, v72
	v_pk_mul_f32 v[70:71], v[74:75], v[70:71]
	v_pk_mul_f32 v[72:73], v[78:79], v[76:77]
	v_and_b32_sdwa v76, v71, v124 dst_sel:DWORD dst_unused:UNUSED_PAD src0_sel:WORD_1 src1_sel:DWORD
	v_and_b32_sdwa v77, v70, v124 dst_sel:DWORD dst_unused:UNUSED_PAD src0_sel:WORD_1 src1_sel:DWORD
	v_and_b32_sdwa v74, v73, v124 dst_sel:DWORD dst_unused:UNUSED_PAD src0_sel:WORD_1 src1_sel:DWORD
	v_and_b32_sdwa v75, v72, v124 dst_sel:DWORD dst_unused:UNUSED_PAD src0_sel:WORD_1 src1_sel:DWORD
	v_add3_u32 v71, v71, v76, s11
	v_add3_u32 v70, v70, v77, s11
	v_add3_u32 v72, v72, v75, s11
	v_add3_u32 v73, v73, v74, s11
	v_and_b32_e32 v71, 0xffff0000, v71
	v_and_b32_e32 v70, 0xffff0000, v70
	v_or_b32_sdwa v71, v71, v73 dst_sel:DWORD dst_unused:UNUSED_PAD src0_sel:DWORD src1_sel:WORD_1
	v_or_b32_sdwa v70, v70, v72 dst_sel:DWORD dst_unused:UNUSED_PAD src0_sel:DWORD src1_sel:WORD_1
	global_store_dwordx2 v[96:97], v[70:71], off offset:1536
	s_nop 0
	ds_read_b128 v[70:73], v135 offset:12288
	v_mov_b32_e32 v75, v68
	v_mov_b32_e32 v68, v91
	v_mov_b32_e32 v74, v90
	v_pk_mul_f32 v[68:69], v[68:69], v[98:99] op_sel_hi:[1,0]
	v_pk_mul_f32 v[74:75], v[74:75], v[98:99] op_sel_hi:[1,0]
	v_mov_b64_e32 v[78:79], v[60:61]
	v_mov_b64_e32 v[90:91], v[48:49]
	s_waitcnt lgkmcnt(0)
; DI unsigned pk2(float lo, float hi) { return f2bf(lo) | (f2bf(hi) << 16); }
; template <int MODE, bool FIRST, bool LAST>
; DI void phase_rowpass(const float* xin, const bf16_t* M, const float* gpost, float* outf, bf16_t* HB, bf16_t* XN, const float* gnext, int gw, int NGW, int lane) {
;     ...
;             for (int j = 0; j < 8; ++j) { const f32x4 gv = ((const f32x4*)gnext)[lane + 64 * j]; u32x2 w; w.x = pk2(hv[j][0] * r2 * gv[0], hv[j][1] * r2 * gv[1]); w.y = pk2(hv[j][2] * r2 * gv[2], hv[j][3] * r2 * gv[3]); o[64 * j] = w; } }
;         if (MODE == 2) { u32x2* o = (u32x2*)(XN + (size_t)row * D_) + lane;
; #pragma unroll
;             for (int j = 0; j < 8; ++j) { u32x2 w; w.x = pk2(hv[j][0], hv[j][1]); w.y = pk2(hv[j][2], hv[j][3]); o[64 * j] = w; } }
;         if (!has) break;
; #pragma unroll
;         for (int j = 0; j < 8; ++j) { hc.f[j] = hn.f[j]; mw[j] = mn[j]; }
;         row = nrow;
	v_mov_b32_e32 v77, v72
	v_mov_b32_e32 v72, v71
	v_mov_b32_e32 v76, v70
	v_pk_mul_f32 v[68:69], v[72:73], v[68:69]
	v_pk_mul_f32 v[70:71], v[76:77], v[74:75]
	v_and_b32_sdwa v74, v69, v124 dst_sel:DWORD dst_unused:UNUSED_PAD src0_sel:WORD_1 src1_sel:DWORD
	v_and_b32_sdwa v75, v68, v124 dst_sel:DWORD dst_unused:UNUSED_PAD src0_sel:WORD_1 src1_sel:DWORD
	v_and_b32_sdwa v72, v71, v124 dst_sel:DWORD dst_unused:UNUSED_PAD src0_sel:WORD_1 src1_sel:DWORD
	v_and_b32_sdwa v73, v70, v124 dst_sel:DWORD dst_unused:UNUSED_PAD src0_sel:WORD_1 src1_sel:DWORD
	v_add3_u32 v69, v69, v74, s11
	v_add3_u32 v68, v68, v75, s11
	v_add3_u32 v70, v70, v73, s11
	v_add3_u32 v71, v71, v72, s11
	v_and_b32_e32 v69, 0xffff0000, v69
	v_and_b32_e32 v68, 0xffff0000, v68
	v_or_b32_sdwa v69, v69, v71 dst_sel:DWORD dst_unused:UNUSED_PAD src0_sel:DWORD src1_sel:WORD_1
	v_or_b32_sdwa v68, v68, v70 dst_sel:DWORD dst_unused:UNUSED_PAD src0_sel:DWORD src1_sel:WORD_1
	global_store_dwordx2 v[96:97], v[68:69], off offset:2048
	s_nop 0
	ds_read_b128 v[68:71], v135 offset:13312
	v_mov_b32_e32 v73, v66
	v_mov_b32_e32 v66, v93
	v_mov_b32_e32 v72, v92
	v_pk_mul_f32 v[66:67], v[66:67], v[98:99] op_sel_hi:[1,0]
	v_pk_mul_f32 v[72:73], v[72:73], v[98:99] op_sel_hi:[1,0]
	v_mov_b64_e32 v[92:93], v[50:51]
	v_mov_b64_e32 v[76:77], v[30:31]
	s_waitcnt lgkmcnt(0)
	v_mov_b32_e32 v75, v70
	v_mov_b32_e32 v70, v69
	v_mov_b32_e32 v74, v68
	v_pk_mul_f32 v[66:67], v[70:71], v[66:67]
	v_pk_mul_f32 v[68:69], v[74:75], v[72:73]
	v_and_b32_sdwa v72, v67, v124 dst_sel:DWORD dst_unused:UNUSED_PAD src0_sel:WORD_1 src1_sel:DWORD
	v_and_b32_sdwa v73, v66, v124 dst_sel:DWORD dst_unused:UNUSED_PAD src0_sel:WORD_1 src1_sel:DWORD
	v_and_b32_sdwa v70, v69, v124 dst_sel:DWORD dst_unused:UNUSED_PAD src0_sel:WORD_1 src1_sel:DWORD
	v_and_b32_sdwa v71, v68, v124 dst_sel:DWORD dst_unused:UNUSED_PAD src0_sel:WORD_1 src1_sel:DWORD
	v_add3_u32 v67, v67, v72, s11
	v_add3_u32 v66, v66, v73, s11
	v_add3_u32 v68, v68, v71, s11
	v_add3_u32 v69, v69, v70, s11
	v_and_b32_e32 v67, 0xffff0000, v67
	v_and_b32_e32 v66, 0xffff0000, v66
	v_or_b32_sdwa v67, v67, v69 dst_sel:DWORD dst_unused:UNUSED_PAD src0_sel:DWORD src1_sel:WORD_1
	v_or_b32_sdwa v66, v66, v68 dst_sel:DWORD dst_unused:UNUSED_PAD src0_sel:DWORD src1_sel:WORD_1
	global_store_dwordx2 v[96:97], v[66:67], off offset:2560
	s_nop 0
	ds_read_b128 v[66:69], v135 offset:14336
	v_mov_b32_e32 v71, v64
	v_mov_b32_e32 v64, v95
	v_mov_b32_e32 v70, v94
	v_pk_mul_f32 v[64:65], v[64:65], v[98:99] op_sel_hi:[1,0]
	v_pk_mul_f32 v[70:71], v[70:71], v[98:99] op_sel_hi:[1,0]
	v_mov_b64_e32 v[94:95], v[52:53]
	v_mov_b64_e32 v[74:75], v[32:33]
	s_waitcnt lgkmcnt(0)
	v_mov_b32_e32 v73, v68
	v_mov_b32_e32 v68, v67
	v_mov_b32_e32 v72, v66
	v_pk_mul_f32 v[64:65], v[68:69], v[64:65]
	v_pk_mul_f32 v[66:67], v[72:73], v[70:71]
	v_and_b32_sdwa v70, v65, v124 dst_sel:DWORD dst_unused:UNUSED_PAD src0_sel:WORD_1 src1_sel:DWORD
	v_and_b32_sdwa v71, v64, v124 dst_sel:DWORD dst_unused:UNUSED_PAD src0_sel:WORD_1 src1_sel:DWORD
	v_and_b32_sdwa v68, v67, v124 dst_sel:DWORD dst_unused:UNUSED_PAD src0_sel:WORD_1 src1_sel:DWORD
	v_and_b32_sdwa v69, v66, v124 dst_sel:DWORD dst_unused:UNUSED_PAD src0_sel:WORD_1 src1_sel:DWORD
	v_add3_u32 v65, v65, v70, s11
	v_add3_u32 v64, v64, v71, s11
	v_add3_u32 v66, v66, v69, s11
	v_add3_u32 v67, v67, v68, s11
	v_and_b32_e32 v65, 0xffff0000, v65
	v_and_b32_e32 v64, 0xffff0000, v64
	v_or_b32_sdwa v65, v65, v67 dst_sel:DWORD dst_unused:UNUSED_PAD src0_sel:DWORD src1_sel:WORD_1
	v_or_b32_sdwa v64, v64, v66 dst_sel:DWORD dst_unused:UNUSED_PAD src0_sel:DWORD src1_sel:WORD_1
	global_store_dwordx2 v[96:97], v[64:65], off offset:3072
	s_nop 0
	ds_read_b128 v[104:107], v135 offset:15360
	v_mov_b64_e32 v[72:73], v[34:35]
	v_mov_b64_e32 v[70:71], v[36:37]
	v_mov_b64_e32 v[68:69], v[38:39]
	v_mov_b64_e32 v[66:67], v[40:41]
	v_mov_b64_e32 v[64:65], v[42:43]
	s_waitcnt vmcnt(0) lgkmcnt(0)
	v_mov_b32_e32 v99, v106
	v_mov_b32_e32 v106, v105
	v_mov_b32_e32 v98, v104
	v_pk_mul_f32 v[62:63], v[106:107], v[62:63]
	v_pk_mul_f32 v[88:89], v[98:99], v[88:89]
	v_and_b32_sdwa v100, v63, v124 dst_sel:DWORD dst_unused:UNUSED_PAD src0_sel:WORD_1 src1_sel:DWORD
	v_and_b32_sdwa v101, v62, v124 dst_sel:DWORD dst_unused:UNUSED_PAD src0_sel:WORD_1 src1_sel:DWORD
	v_and_b32_sdwa v98, v89, v124 dst_sel:DWORD dst_unused:UNUSED_PAD src0_sel:WORD_1 src1_sel:DWORD
	v_and_b32_sdwa v99, v88, v124 dst_sel:DWORD dst_unused:UNUSED_PAD src0_sel:WORD_1 src1_sel:DWORD
	v_add3_u32 v63, v63, v100, s11
	v_add3_u32 v62, v62, v101, s11
	v_add3_u32 v88, v88, v99, s11
	v_add3_u32 v89, v89, v98, s11
	v_and_b32_e32 v63, 0xffff0000, v63
	v_and_b32_e32 v62, 0xffff0000, v62
	v_or_b32_sdwa v63, v63, v89 dst_sel:DWORD dst_unused:UNUSED_PAD src0_sel:DWORD src1_sel:WORD_1
	v_or_b32_sdwa v62, v62, v88 dst_sel:DWORD dst_unused:UNUSED_PAD src0_sel:DWORD src1_sel:WORD_1
	global_store_dwordx2 v[96:97], v[62:63], off offset:3584
	v_mov_b64_e32 v[62:63], v[44:45]
	s_cbranch_vccz .LBB0_765

; DI unsigned pk2(float lo, float hi) { return f2bf(lo) | (f2bf(hi) << 16); }
; template <int MODE, bool FIRST, bool LAST>
; DI void phase_rowpass(const float* xin, const bf16_t* M, const float* gpost, float* outf, bf16_t* HB, bf16_t* XN, const float* gnext, int gw, int NGW, int lane) {
;     int row = gw; if (row >= T_) return;
;     HRow<FIRST> hc; u32x2 mw[8];
;     { const u32x2* mr = (const u32x2*)(M + (size_t)row * D_) + lane;
; #pragma unroll
;       for (int j = 0; j < 8; ++j) { if constexpr (FIRST) hc.f[j] = ((const f32x4*)(xin + (size_t)row * D_) + lane)[64 * j]; else hc.f[j] = ((const u32x2*)(HB + (size_t)row * D_) + lane)[64 * j]; mw[j] = mr[64 * j]; } }
;     ...
;         for (int j = 0; j < 8; ++j) { const f32x4 gv = ((const f32x4*)gpost)[lane + 64 * j]; hv[j] = hv[j] + mv[j] * rs * gv;
;             if constexpr (LAST) ((f32x4*)(outf + (size_t)row * D_) + lane)[64 * j] = hv[j];
;             else { u32x2 w; w.x = pk2(hv[j][0], hv[j][1]); w.y = pk2(hv[j][2], hv[j][3]); ((u32x2*)(HB + (size_t)row * D_) + lane)[64 * j] = w; }
;             s2 += (hv[j][0] * hv[j][0] + hv[j][1] * hv[j][1]) + (hv[j][2] * hv[j][2] + hv[j][3] * hv[j][3]); }
;         if (MODE == 1) { const float r2 = rsqrtf(wave_sum(s2) * (1.f / D_) + EPS); u32x2* o = (u32x2*)(XN + (size_t)row * D_) + lane;
; #pragma unroll
;             for (int j = 0; j < 8; ++j) { const f32x4 gv = ((const f32x4*)gnext)[lane + 64 * j]; u32x2 w; w.x = pk2(hv[j][0] * r2 * gv[0], hv[j][1] * r2 * gv[1]); w.y = pk2(hv[j][2] * r2 * gv[2], hv[j][3] * r2 * gv[3]); o[64 * j] = w; } }
.LBB0_1129:
	s_cmp_lt_i32 s62, 16
	s_cselect_b64 s[8:9], -1, 0
	s_and_b64 s[6:7], s[8:9], s[6:7]
	s_andn2_b64 vcc, exec, s[6:7]
	s_cbranch_vccnz .LBB0_1135
	v_mov_b32_e32 v2, v1
	s_lshl_b32 s3, s2, 3
	v_readfirstlane_b32 s8, v2
	s_ashr_i32 s8, s8, 6
	s_add_i32 s8, s8, s3
	s_mov_b64 s[12:13], s[0:1]
	s_cmpk_gt_i32 s8, 0x3fff
	s_cbranch_scc1 .LBB0_1135
	s_load_dwordx4 s[20:23], s[12:13], 0x18
	s_waitcnt lgkmcnt(0)
	s_load_dwordx2 s[16:17], s[12:13], 0xc8
	s_lshl_b32 s10, s74, 3
	v_and_b32_e32 v12, 63, v2
	v_lshlrev_b32_e32 v2, 3, v12
	s_add_u32 s14, s22, 0x2000
	s_addc_u32 s15, s23, 0
	s_add_u32 s18, s20, 0x2000
	s_addc_u32 s19, s21, 0
	s_ashr_i32 s9, s8, 31
	s_lshl_b64 s[12:13], s[8:9], 12
	s_waitcnt lgkmcnt(0)
	s_add_u32 s12, s16, s12
	v_mov_b32_e32 v3, 0
	s_addc_u32 s13, s17, s13
	v_lshl_add_u64 v[4:5], s[12:13], 0, v[2:3]
	s_mov_b32 s3, 0xc000
	s_mov_b64 s[20:21], 0x14dcc000
	v_add_co_u32_e32 v10, vcc, s3, v4
	v_lshl_add_u64 v[6:7], v[4:5], 0, s[20:21]
	s_mov_b64 s[20:21], 0xc000
	v_addc_co_u32_e32 v11, vcc, 0, v5, vcc
	s_mov_b32 s9, 0x14dcc000
	v_lshl_add_u64 v[8:9], v[4:5], 0, s[20:21]
	v_add_co_u32_e32 v4, vcc, s9, v4
	v_lshlrev_b32_e32 v20, 4, v12
	s_nop 0
	v_addc_co_u32_e32 v5, vcc, 0, v5, vcc
	global_load_dwordx2 v[98:99], v[6:7], off offset:512
	global_load_dwordx2 v[96:97], v[6:7], off offset:1024
	global_load_dwordx2 v[92:93], v[6:7], off offset:1536
	global_load_dwordx2 v[90:91], v[6:7], off offset:2048
	global_load_dwordx2 v[78:79], v[8:9], off offset:1024
	global_load_dwordx2 v[76:77], v[8:9], off offset:1536
	global_load_dwordx2 v[74:75], v[8:9], off offset:2048
	global_load_dwordx2 v[72:73], v[8:9], off offset:2560
	global_load_dwordx2 v[82:83], v[10:11], off
	global_load_dwordx2 v[100:101], v[4:5], off
	global_load_dwordx2 v[70:71], v[8:9], off offset:3072
	global_load_dwordx2 v[68:69], v[8:9], off offset:3584
	global_load_dwordx2 v[80:81], v[8:9], off offset:512
	global_load_dwordx2 v[88:89], v[6:7], off offset:2560
	global_load_dwordx2 v[86:87], v[6:7], off offset:3072
	global_load_dwordx2 v[84:85], v[6:7], off offset:3584
	v_mbcnt_lo_u32_b32 v4, -1, 0
	v_mbcnt_hi_u32_b32 v4, -1, v4
	v_and_b32_e32 v5, 64, v4
	v_add_u32_e32 v5, 64, v5
	v_xor_b32_e32 v6, 1, v4
	v_cmp_lt_i32_e32 vcc, v6, v5
	v_mov_b32_e32 v21, v3
	v_or_b32_e32 v22, 0x400, v20
	v_cndmask_b32_e32 v6, v4, v6, vcc
	v_lshlrev_b32_e32 v109, 2, v6
	v_xor_b32_e32 v6, 2, v4
	v_cmp_lt_i32_e32 vcc, v6, v5
	v_mov_b32_e32 v23, v3
	v_or_b32_e32 v24, 0x800, v20
	v_cndmask_b32_e32 v6, v4, v6, vcc
	v_lshlrev_b32_e32 v124, 2, v6
	v_xor_b32_e32 v6, 4, v4
	v_cmp_lt_i32_e32 vcc, v6, v5
	v_mov_b32_e32 v25, v3
	v_or_b32_e32 v26, 0xc00, v20
	v_cndmask_b32_e32 v6, v4, v6, vcc
	v_lshlrev_b32_e32 v125, 2, v6
	v_xor_b32_e32 v6, 8, v4
	v_cmp_lt_i32_e32 vcc, v6, v5
	v_mov_b32_e32 v27, v3
	v_or_b32_e32 v28, 0x1000, v20
	v_cndmask_b32_e32 v6, v4, v6, vcc
	s_waitcnt vmcnt(0)
	v_lshlrev_b32_e32 v126, 2, v6
	v_xor_b32_e32 v6, 16, v4
	v_cmp_lt_i32_e32 vcc, v6, v5
	v_mov_b32_e32 v29, v3
	v_or_b32_e32 v30, 0x1400, v20
	v_cndmask_b32_e32 v6, v4, v6, vcc
	v_lshlrev_b32_e32 v127, 2, v6
	v_xor_b32_e32 v6, 32, v4
	v_cmp_lt_i32_e32 vcc, v6, v5
	v_mov_b32_e32 v31, v3
	v_or_b32_e32 v32, 0x1800, v20
	v_cndmask_b32_e32 v4, v4, v6, vcc
	v_mov_b32_e32 v33, v3
	v_or_b32_e32 v34, 0x1c00, v20
	v_mov_b32_e32 v35, v3
	v_lshlrev_b32_e32 v128, 2, v4
	v_lshl_add_u64 v[4:5], s[18:19], 0, v[20:21]
	v_lshl_add_u64 v[6:7], s[18:19], 0, v[22:23]
	v_lshl_add_u64 v[8:9], s[18:19], 0, v[24:25]
	v_lshl_add_u64 v[10:11], s[18:19], 0, v[26:27]
	v_lshl_add_u64 v[12:13], s[18:19], 0, v[28:29]
	v_lshl_add_u64 v[14:15], s[18:19], 0, v[30:31]
	v_lshl_add_u64 v[16:17], s[18:19], 0, v[32:33]
	v_lshl_add_u64 v[18:19], s[18:19], 0, v[34:35]
	s_add_i32 s18, s8, s10
	s_ashr_i32 s11, s10, 31
	s_ashr_i32 s19, s18, 31
	v_lshl_add_u64 v[20:21], s[14:15], 0, v[20:21]
	v_lshl_add_u64 v[22:23], s[14:15], 0, v[22:23]
	v_lshl_add_u64 v[24:25], s[14:15], 0, v[24:25]
	v_lshl_add_u64 v[26:27], s[14:15], 0, v[26:27]
	v_lshl_add_u64 v[28:29], s[14:15], 0, v[28:29]
	v_lshl_add_u64 v[30:31], s[14:15], 0, v[30:31]
	v_lshl_add_u64 v[32:33], s[14:15], 0, v[32:33]
	v_lshl_add_u64 v[34:35], s[14:15], 0, v[34:35]
	s_lshl_b64 s[14:15], s[10:11], 12
	s_lshl_b64 s[18:19], s[18:19], 12
	s_add_u32 s16, s16, s18
	s_addc_u32 s17, s17, s19
	v_mov_b32_e32 v129, 0x358637bd
	s_mov_b32 s9, 0x800000
	s_movk_i32 s11, 0x7fff
	s_mov_b32 s20, 0x10dcc000
	v_mov_b32_e32 v130, 1
	v_and_b32_e32 v141, 63, v1
	v_lshlrev_b32_e32 v141, 4, v141
	global_load_dwordx4 v[144:147], v[4:5], off
	global_load_dwordx4 v[148:151], v[6:7], off
	global_load_dwordx4 v[152:155], v[8:9], off
	global_load_dwordx4 v[156:159], v[10:11], off
	global_load_dwordx4 v[160:163], v[12:13], off
	global_load_dwordx4 v[164:167], v[14:15], off
	global_load_dwordx4 v[168:171], v[16:17], off
	global_load_dwordx4 v[172:175], v[18:19], off
	global_load_dwordx4 v[176:179], v[20:21], off
	global_load_dwordx4 v[180:183], v[22:23], off
	global_load_dwordx4 v[184:187], v[24:25], off
	global_load_dwordx4 v[188:191], v[26:27], off
	global_load_dwordx4 v[192:195], v[28:29], off
	global_load_dwordx4 v[196:199], v[30:31], off
	global_load_dwordx4 v[200:203], v[32:33], off
	global_load_dwordx4 v[204:207], v[34:35], off
	s_waitcnt vmcnt(0)
	ds_write_b128 v141, v[144:147] offset:0
	ds_write_b128 v141, v[148:151] offset:1024
	ds_write_b128 v141, v[152:155] offset:2048
	ds_write_b128 v141, v[156:159] offset:3072
	ds_write_b128 v141, v[160:163] offset:4096
	ds_write_b128 v141, v[164:167] offset:5120
	ds_write_b128 v141, v[168:171] offset:6144
	ds_write_b128 v141, v[172:175] offset:7168
	ds_write_b128 v141, v[176:179] offset:8192
	ds_write_b128 v141, v[180:183] offset:9216
	ds_write_b128 v141, v[184:187] offset:10240
	ds_write_b128 v141, v[188:191] offset:11264
	ds_write_b128 v141, v[192:195] offset:12288
	ds_write_b128 v141, v[196:199] offset:13312
	ds_write_b128 v141, v[200:203] offset:14336
	ds_write_b128 v141, v[204:207] offset:15360
	s_waitcnt lgkmcnt(0)
	s_branch .LBB0_1133
; DI unsigned pk2(float lo, float hi) { return f2bf(lo) | (f2bf(hi) << 16); }
; DI float lo_f(unsigned w) { return __uint_as_float(w << 16); }
; DI float hi_f(unsigned w) { return __uint_as_float(w & 0xffff0000u); }
; template <int MODE, bool FIRST, bool LAST>
; DI void phase_rowpass(const float* xin, const bf16_t* M, const float* gpost, float* outf, bf16_t* HB, bf16_t* XN, const float* gnext, int gw, int NGW, int lane) {
;     ...
;         f32x4 hv[8], mv[8]; float ss = 0.f;
; #pragma unroll
;         for (int j = 0; j < 8; ++j) { const u32x2 w = mw[j]; mv[j] = (f32x4){lo_f(w.x), hi_f(w.x), lo_f(w.y), hi_f(w.y)};
;             if constexpr (FIRST) hv[j] = hc.f[j]; else { const u32x2 hw = hc.f[j]; hv[j] = (f32x4){lo_f(hw.x), hi_f(hw.x), lo_f(hw.y), hi_f(hw.y)}; }
;             ss += (mv[j][0] * mv[j][0] + mv[j][1] * mv[j][1]) + (mv[j][2] * mv[j][2] + mv[j][3] * mv[j][3]); }
;         const float rs = rsqrtf(wave_sum(ss) * (1.f / D_) + EPS);
;         float s2 = 0.f;
; #pragma unroll
;         for (int j = 0; j < 8; ++j) { const f32x4 gv = ((const f32x4*)gpost)[lane + 64 * j]; hv[j] = hv[j] + mv[j] * rs * gv;
;             if constexpr (LAST) ((f32x4*)(outf + (size_t)row * D_) + lane)[64 * j] = hv[j];
;             else { u32x2 w; w.x = pk2(hv[j][0], hv[j][1]); w.y = pk2(hv[j][2], hv[j][3]); ((u32x2*)(HB + (size_t)row * D_) + lane)[64 * j] = w; }
.LBB0_1132:
	v_and_b32_e32 v133, 0xffff0000, v100
	v_and_b32_e32 v132, 0xffff0000, v98
	v_and_b32_e32 v135, 0xffff0000, v101
	v_and_b32_e32 v134, 0xffff0000, v99
	v_lshlrev_b32_e32 v121, 16, v100
	v_lshlrev_b32_e32 v120, 16, v98
	v_lshlrev_b32_e32 v123, 16, v101
	v_lshlrev_b32_e32 v122, 16, v99
	v_pk_mul_f32 v[94:95], v[132:133], v[132:133]
	v_pk_mul_f32 v[98:99], v[134:135], v[134:135]
	v_and_b32_e32 v119, 0xffff0000, v97
	v_and_b32_e32 v118, 0xffff0000, v96
	v_pk_fma_f32 v[94:95], v[120:121], v[120:121], v[94:95]
	v_pk_fma_f32 v[98:99], v[122:123], v[122:123], v[98:99]
	v_lshlrev_b32_e32 v117, 16, v97
	v_lshlrev_b32_e32 v116, 16, v96
	v_pk_mul_f32 v[96:97], v[118:119], v[118:119]
	v_pk_add_f32 v[94:95], v[94:95], v[98:99]
	v_pk_fma_f32 v[96:97], v[116:117], v[116:117], v[96:97]
	v_pk_add_f32 v[94:95], v[94:95], v[94:95] op_sel_hi:[0,1]
	v_pk_add_f32 v[98:99], v[96:97], v[96:97] op_sel_hi:[0,1]
	v_lshlrev_b32_e32 v114, 16, v92
	v_and_b32_e32 v115, 0xffff0000, v92
	v_lshlrev_b32_e32 v92, 16, v93
	v_lshlrev_b32_e32 v96, 16, v90
	v_mul_f32_e32 v97, v114, v114
	v_mul_f32_e32 v101, v115, v115
	v_and_b32_e32 v93, 0xffff0000, v93
	v_mul_f32_e32 v94, v92, v92
	v_mov_b32_e32 v100, v96
	v_pk_fma_f32 v[102:103], v[92:93], v[92:93], v[94:95] op_sel_hi:[1,1,0]
	v_and_b32_e32 v131, 0xffff0000, v90
	v_lshlrev_b32_e32 v106, 16, v91
	v_and_b32_e32 v107, 0xffff0000, v91
	v_pk_add_f32 v[100:101], v[96:97], v[100:101]
	v_mul_f32_e32 v102, v131, v131
	v_mul_f32_e32 v98, v106, v106
	v_mul_f32_e32 v94, v107, v107
	v_mul_f32_e32 v90, v96, v96
	v_mov_b32_e32 v91, v101
	v_pk_add_f32 v[90:91], v[90:91], v[102:103]
	v_pk_add_f32 v[94:95], v[98:99], v[94:95]
	v_lshlrev_b32_e32 v99, 16, v89
	v_pk_add_f32 v[90:91], v[90:91], v[94:95]
	v_lshlrev_b32_e32 v98, 16, v88
	v_pk_add_f32 v[104:105], v[90:91], v[90:91] op_sel_hi:[0,1]
	v_and_b32_e32 v101, 0xffff0000, v89
	v_and_b32_e32 v100, 0xffff0000, v88
	ds_read_b128 v[88:91], v141 offset:0
	v_pk_mul_f32 v[94:95], v[100:101], v[100:101]
	v_lshlrev_b32_e32 v110, 16, v86
	v_pk_fma_f32 v[94:95], v[98:99], v[98:99], v[94:95]
	v_and_b32_e32 v111, 0xffff0000, v86
	v_pk_add_f32 v[136:137], v[94:95], v[94:95] op_sel_hi:[0,1]
	v_lshlrev_b32_e32 v112, 16, v87
	v_lshlrev_b32_e32 v94, 16, v84
	v_mul_f32_e32 v95, v110, v110
	v_mul_f32_e32 v139, v111, v111
	v_and_b32_e32 v113, 0xffff0000, v87
	v_mul_f32_e32 v86, v112, v112
	v_mov_b32_e32 v138, v94
	v_pk_fma_f32 v[86:87], v[112:113], v[112:113], v[86:87] op_sel_hi:[1,1,0]
	v_and_b32_e32 v140, 0xffff0000, v84
	v_lshlrev_b32_e32 v102, 16, v85
	v_and_b32_e32 v103, 0xffff0000, v85
	v_pk_add_f32 v[138:139], v[94:95], v[138:139]
	v_mul_f32_e32 v86, v140, v140
	v_mul_f32_e32 v136, v102, v102
	v_mul_f32_e32 v104, v103, v103
	v_mul_f32_e32 v84, v94, v94
	v_mov_b32_e32 v85, v139
	v_pk_add_f32 v[84:85], v[84:85], v[86:87]
	v_pk_add_f32 v[86:87], v[136:137], v[104:105]
	v_mov_b32_e32 v136, v121
	v_pk_add_f32 v[84:85], v[84:85], v[86:87]
	v_mov_b32_e32 v137, v133
	v_add_f32_e32 v84, v84, v85
	ds_bpermute_b32 v85, v109, v84
	v_mov_b32_e32 v104, v123
	v_mov_b32_e32 v105, v135
	v_and_b32_e32 v87, 0xffff0000, v83
	v_mov_b32_e32 v121, v132
	s_waitcnt lgkmcnt(0)
	v_add_f32_e32 v84, v84, v85
	ds_bpermute_b32 v85, v124, v84
	v_mov_b32_e32 v123, v134
	v_mov_b32_e32 v132, v116
	v_mov_b32_e32 v133, v118
	v_mov_b32_e32 v118, v117
	s_waitcnt lgkmcnt(0)
	v_add_f32_e32 v84, v84, v85
	ds_bpermute_b32 v85, v125, v84
	s_waitcnt lgkmcnt(0)
	v_add_f32_e32 v84, v84, v85
	ds_bpermute_b32 v85, v126, v84
	s_waitcnt lgkmcnt(0)
	v_add_f32_e32 v84, v84, v85
	ds_bpermute_b32 v85, v127, v84
	s_waitcnt lgkmcnt(0)
	v_add_f32_e32 v85, v84, v85
	ds_bpermute_b32 v86, v128, v85
	v_lshlrev_b32_e32 v84, 16, v82
	s_waitcnt lgkmcnt(0)
	v_add_f32_e32 v85, v85, v86
	v_fmamk_f32 v85, v85, 0x3a000000, v129
	v_mul_f32_e32 v86, 0x4b800000, v85
	v_cmp_gt_f32_e32 vcc, s9, v85
	s_nop 1
	v_cndmask_b32_e32 v85, v85, v86, vcc
	v_rsq_f32_e32 v95, v85
	v_and_b32_e32 v85, 0xffff0000, v82
	v_lshlrev_b32_e32 v86, 16, v83
	v_mul_f32_e32 v82, 0x45800000, v95
	v_cndmask_b32_e32 v108, v95, v82, vcc
	v_pk_mul_f32 v[136:137], v[136:137], v[108:109] op_sel_hi:[1,0]
	v_pk_mul_f32 v[104:105], v[104:105], v[108:109] op_sel_hi:[1,0]
	v_lshl_add_u64 v[82:83], s[12:13], 0, v[2:3]
	s_waitcnt vmcnt(0) lgkmcnt(0)
	v_pk_fma_f32 v[84:85], v[88:89], v[136:137], v[84:85]
	v_pk_fma_f32 v[86:87], v[90:91], v[104:105], v[86:87]
	v_and_b32_sdwa v89, v84, v130 dst_sel:DWORD dst_unused:UNUSED_PAD src0_sel:WORD_1 src1_sel:DWORD
	v_add3_u32 v90, v84, v89, s11
	v_and_b32_sdwa v89, v87, v130 dst_sel:DWORD dst_unused:UNUSED_PAD src0_sel:WORD_1 src1_sel:DWORD
	v_and_b32_sdwa v91, v85, v130 dst_sel:DWORD dst_unused:UNUSED_PAD src0_sel:WORD_1 src1_sel:DWORD
	v_and_b32_sdwa v88, v86, v130 dst_sel:DWORD dst_unused:UNUSED_PAD src0_sel:WORD_1 src1_sel:DWORD
	v_add3_u32 v89, v87, v89, s11
	v_add3_u32 v91, v85, v91, s11
	v_add3_u32 v88, v86, v88, s11
	v_and_b32_e32 v89, 0xffff0000, v89
	v_and_b32_e32 v91, 0xffff0000, v91
	v_add_co_u32_e32 v104, vcc, s3, v82
	v_or_b32_sdwa v89, v89, v88 dst_sel:DWORD dst_unused:UNUSED_PAD src0_sel:DWORD src1_sel:WORD_1
	v_or_b32_sdwa v88, v91, v90 dst_sel:DWORD dst_unused:UNUSED_PAD src0_sel:DWORD src1_sel:WORD_1
	v_addc_co_u32_e32 v105, vcc, 0, v83, vcc
	global_store_dwordx2 v[104:105], v[88:89], off
	s_nop 0
	ds_read_b128 v[88:91], v141 offset:1024
	v_lshlrev_b32_e32 v136, 16, v80
	v_and_b32_e32 v137, 0xffff0000, v80
	v_lshlrev_b32_e32 v80, 16, v81
	v_and_b32_e32 v81, 0xffff0000, v81
	v_pk_mul_f32 v[120:121], v[120:121], v[108:109] op_sel_hi:[1,0]
	v_pk_mul_f32 v[122:123], v[122:123], v[108:109] op_sel_hi:[1,0]
	v_pk_mul_f32 v[116:117], v[108:109], v[132:133] op_sel_hi:[0,1]
	v_pk_mul_f32 v[118:119], v[108:109], v[118:119] op_sel_hi:[0,1]
	v_pk_mul_f32 v[114:115], v[114:115], v[108:109] op_sel_hi:[1,0]
	v_pk_mul_f32 v[92:93], v[92:93], v[108:109] op_sel_hi:[1,0]
	v_pk_mul_f32 v[106:107], v[106:107], v[108:109] op_sel_hi:[1,0]
	v_pk_mul_f32 v[102:103], v[102:103], v[108:109] op_sel_hi:[1,0]
	s_add_u32 s12, s12, s14
	s_addc_u32 s13, s13, s15
	s_add_u32 s16, s16, s14
	s_addc_u32 s17, s17, s15
	s_waitcnt lgkmcnt(0)
; DI unsigned pk2(float lo, float hi) { return f2bf(lo) | (f2bf(hi) << 16); }
; template <int MODE, bool FIRST, bool LAST>
; DI void phase_rowpass(const float* xin, const bf16_t* M, const float* gpost, float* outf, bf16_t* HB, bf16_t* XN, const float* gnext, int gw, int NGW, int lane) {
;     ...
;         for (int j = 0; j < 8; ++j) { const f32x4 gv = ((const f32x4*)gpost)[lane + 64 * j]; hv[j] = hv[j] + mv[j] * rs * gv;
;             if constexpr (LAST) ((f32x4*)(outf + (size_t)row * D_) + lane)[64 * j] = hv[j];
;             else { u32x2 w; w.x = pk2(hv[j][0], hv[j][1]); w.y = pk2(hv[j][2], hv[j][3]); ((u32x2*)(HB + (size_t)row * D_) + lane)[64 * j] = w; }
	v_pk_fma_f32 v[80:81], v[90:91], v[122:123], v[80:81]
	v_pk_fma_f32 v[88:89], v[88:89], v[120:121], v[136:137]
	v_and_b32_sdwa v95, v81, v130 dst_sel:DWORD dst_unused:UNUSED_PAD src0_sel:WORD_1 src1_sel:DWORD
	v_and_b32_sdwa v91, v88, v130 dst_sel:DWORD dst_unused:UNUSED_PAD src0_sel:WORD_1 src1_sel:DWORD
	v_and_b32_sdwa v97, v89, v130 dst_sel:DWORD dst_unused:UNUSED_PAD src0_sel:WORD_1 src1_sel:DWORD
	v_and_b32_sdwa v90, v80, v130 dst_sel:DWORD dst_unused:UNUSED_PAD src0_sel:WORD_1 src1_sel:DWORD
	v_add3_u32 v120, v88, v91, s11
	v_add3_u32 v91, v81, v95, s11
	v_add3_u32 v95, v89, v97, s11
	v_add3_u32 v90, v80, v90, s11
	v_and_b32_e32 v91, 0xffff0000, v91
	v_and_b32_e32 v95, 0xffff0000, v95
	v_or_b32_sdwa v91, v91, v90 dst_sel:DWORD dst_unused:UNUSED_PAD src0_sel:DWORD src1_sel:WORD_1
	v_or_b32_sdwa v90, v95, v120 dst_sel:DWORD dst_unused:UNUSED_PAD src0_sel:DWORD src1_sel:WORD_1
	global_store_dwordx2 v[104:105], v[90:91], off offset:512
	s_nop 0
	ds_read_b128 v[120:123], v141 offset:2048
	v_lshlrev_b32_e32 v90, 16, v78
	v_and_b32_e32 v91, 0xffff0000, v78
	v_lshlrev_b32_e32 v78, 16, v79
	v_and_b32_e32 v79, 0xffff0000, v79
	s_waitcnt lgkmcnt(0)
	v_pk_fma_f32 v[78:79], v[122:123], v[118:119], v[78:79]
	v_pk_fma_f32 v[90:91], v[120:121], v[116:117], v[90:91]
	v_and_b32_sdwa v116, v79, v130 dst_sel:DWORD dst_unused:UNUSED_PAD src0_sel:WORD_1 src1_sel:DWORD
	v_and_b32_sdwa v117, v91, v130 dst_sel:DWORD dst_unused:UNUSED_PAD src0_sel:WORD_1 src1_sel:DWORD
	v_and_b32_sdwa v95, v78, v130 dst_sel:DWORD dst_unused:UNUSED_PAD src0_sel:WORD_1 src1_sel:DWORD
	v_and_b32_sdwa v97, v90, v130 dst_sel:DWORD dst_unused:UNUSED_PAD src0_sel:WORD_1 src1_sel:DWORD
	v_add3_u32 v116, v79, v116, s11
	v_add3_u32 v117, v91, v117, s11
	v_add3_u32 v97, v90, v97, s11
	v_add3_u32 v95, v78, v95, s11
	v_and_b32_e32 v116, 0xffff0000, v116
	v_and_b32_e32 v118, 0xffff0000, v117
	v_or_b32_sdwa v117, v116, v95 dst_sel:DWORD dst_unused:UNUSED_PAD src0_sel:DWORD src1_sel:WORD_1
	v_or_b32_sdwa v116, v118, v97 dst_sel:DWORD dst_unused:UNUSED_PAD src0_sel:DWORD src1_sel:WORD_1
	global_store_dwordx2 v[104:105], v[116:117], off offset:1024
	s_nop 0
	ds_read_b128 v[116:119], v141 offset:3072
	v_lshlrev_b32_e32 v120, 16, v76
	v_and_b32_e32 v121, 0xffff0000, v76
	v_lshlrev_b32_e32 v76, 16, v77
	v_and_b32_e32 v77, 0xffff0000, v77
	s_waitcnt lgkmcnt(0)
	v_pk_fma_f32 v[76:77], v[118:119], v[92:93], v[76:77]
	v_pk_fma_f32 v[92:93], v[116:117], v[114:115], v[120:121]
	v_and_b32_sdwa v114, v77, v130 dst_sel:DWORD dst_unused:UNUSED_PAD src0_sel:WORD_1 src1_sel:DWORD
	v_and_b32_sdwa v115, v93, v130 dst_sel:DWORD dst_unused:UNUSED_PAD src0_sel:WORD_1 src1_sel:DWORD
	v_and_b32_sdwa v95, v76, v130 dst_sel:DWORD dst_unused:UNUSED_PAD src0_sel:WORD_1 src1_sel:DWORD
	v_and_b32_sdwa v97, v92, v130 dst_sel:DWORD dst_unused:UNUSED_PAD src0_sel:WORD_1 src1_sel:DWORD
	v_add3_u32 v114, v77, v114, s11
	v_add3_u32 v115, v93, v115, s11
	v_add3_u32 v97, v92, v97, s11
	v_add3_u32 v95, v76, v95, s11
	v_and_b32_e32 v114, 0xffff0000, v114
	v_and_b32_e32 v116, 0xffff0000, v115
	v_or_b32_sdwa v115, v114, v95 dst_sel:DWORD dst_unused:UNUSED_PAD src0_sel:DWORD src1_sel:WORD_1
	v_or_b32_sdwa v114, v116, v97 dst_sel:DWORD dst_unused:UNUSED_PAD src0_sel:DWORD src1_sel:WORD_1
	global_store_dwordx2 v[104:105], v[114:115], off offset:1536
	s_nop 0
	ds_read_b128 v[114:117], v141 offset:4096
	v_mov_b32_e32 v97, v131
	v_lshlrev_b32_e32 v118, 16, v74
	v_and_b32_e32 v119, 0xffff0000, v74
	v_lshlrev_b32_e32 v74, 16, v75
	v_and_b32_e32 v75, 0xffff0000, v75
	v_pk_mul_f32 v[96:97], v[96:97], v[108:109] op_sel_hi:[1,0]
	s_waitcnt lgkmcnt(0)
	v_pk_fma_f32 v[74:75], v[116:117], v[106:107], v[74:75]
	v_pk_fma_f32 v[96:97], v[114:115], v[96:97], v[118:119]
	v_and_b32_sdwa v107, v75, v130 dst_sel:DWORD dst_unused:UNUSED_PAD src0_sel:WORD_1 src1_sel:DWORD
	v_and_b32_sdwa v114, v97, v130 dst_sel:DWORD dst_unused:UNUSED_PAD src0_sel:WORD_1 src1_sel:DWORD
	v_and_b32_sdwa v95, v74, v130 dst_sel:DWORD dst_unused:UNUSED_PAD src0_sel:WORD_1 src1_sel:DWORD
	v_and_b32_sdwa v106, v96, v130 dst_sel:DWORD dst_unused:UNUSED_PAD src0_sel:WORD_1 src1_sel:DWORD
	v_add3_u32 v107, v75, v107, s11
	v_add3_u32 v114, v97, v114, s11
	v_add3_u32 v106, v96, v106, s11
	v_add3_u32 v95, v74, v95, s11
	v_and_b32_e32 v107, 0xffff0000, v107
	v_and_b32_e32 v114, 0xffff0000, v114
	v_or_b32_sdwa v107, v107, v95 dst_sel:DWORD dst_unused:UNUSED_PAD src0_sel:DWORD src1_sel:WORD_1
	v_or_b32_sdwa v106, v114, v106 dst_sel:DWORD dst_unused:UNUSED_PAD src0_sel:DWORD src1_sel:WORD_1
	global_store_dwordx2 v[104:105], v[106:107], off offset:2048
	s_nop 0
	ds_read_b128 v[114:117], v141 offset:5120
	v_mov_b32_e32 v118, v98
	v_mov_b32_e32 v119, v100
	v_mov_b32_e32 v100, v99
	v_lshlrev_b32_e32 v106, 16, v72
	v_and_b32_e32 v107, 0xffff0000, v72
	v_lshlrev_b32_e32 v72, 16, v73
	v_and_b32_e32 v73, 0xffff0000, v73
	v_pk_mul_f32 v[98:99], v[108:109], v[118:119] op_sel_hi:[0,1]
	v_pk_mul_f32 v[100:101], v[108:109], v[100:101] op_sel_hi:[0,1]
	v_mov_b32_e32 v118, v88
	v_mov_b32_e32 v119, v80
	s_waitcnt lgkmcnt(0)
; DI unsigned pk2(float lo, float hi) { return f2bf(lo) | (f2bf(hi) << 16); }
; template <int MODE, bool FIRST, bool LAST>
; DI void phase_rowpass(const float* xin, const bf16_t* M, const float* gpost, float* outf, bf16_t* HB, bf16_t* XN, const float* gnext, int gw, int NGW, int lane) {
;     ...
;         for (int j = 0; j < 8; ++j) { const f32x4 gv = ((const f32x4*)gpost)[lane + 64 * j]; hv[j] = hv[j] + mv[j] * rs * gv;
;             if constexpr (LAST) ((f32x4*)(outf + (size_t)row * D_) + lane)[64 * j] = hv[j];
;             else { u32x2 w; w.x = pk2(hv[j][0], hv[j][1]); w.y = pk2(hv[j][2], hv[j][3]); ((u32x2*)(HB + (size_t)row * D_) + lane)[64 * j] = w; }
;             s2 += (hv[j][0] * hv[j][0] + hv[j][1] * hv[j][1]) + (hv[j][2] * hv[j][2] + hv[j][3] * hv[j][3]); }
;         if (MODE == 1) { const float r2 = rsqrtf(wave_sum(s2) * (1.f / D_) + EPS); u32x2* o = (u32x2*)(XN + (size_t)row * D_) + lane;
	v_pk_fma_f32 v[72:73], v[116:117], v[100:101], v[72:73]
	v_pk_fma_f32 v[98:99], v[114:115], v[98:99], v[106:107]
	v_and_b32_sdwa v101, v73, v130 dst_sel:DWORD dst_unused:UNUSED_PAD src0_sel:WORD_1 src1_sel:DWORD
	v_and_b32_sdwa v106, v99, v130 dst_sel:DWORD dst_unused:UNUSED_PAD src0_sel:WORD_1 src1_sel:DWORD
	v_and_b32_sdwa v95, v72, v130 dst_sel:DWORD dst_unused:UNUSED_PAD src0_sel:WORD_1 src1_sel:DWORD
	v_and_b32_sdwa v100, v98, v130 dst_sel:DWORD dst_unused:UNUSED_PAD src0_sel:WORD_1 src1_sel:DWORD
	v_add3_u32 v101, v73, v101, s11
	v_add3_u32 v106, v99, v106, s11
	v_add3_u32 v100, v98, v100, s11
	v_add3_u32 v95, v72, v95, s11
	v_and_b32_e32 v101, 0xffff0000, v101
	v_and_b32_e32 v106, 0xffff0000, v106
	v_or_b32_sdwa v101, v101, v95 dst_sel:DWORD dst_unused:UNUSED_PAD src0_sel:DWORD src1_sel:WORD_1
	v_or_b32_sdwa v100, v106, v100 dst_sel:DWORD dst_unused:UNUSED_PAD src0_sel:DWORD src1_sel:WORD_1
	global_store_dwordx2 v[104:105], v[100:101], off offset:2560
	s_nop 0
	ds_read_b128 v[114:117], v141 offset:6144
	v_lshlrev_b32_e32 v100, 16, v70
	v_and_b32_e32 v101, 0xffff0000, v70
	v_lshlrev_b32_e32 v70, 16, v71
	v_and_b32_e32 v71, 0xffff0000, v71
	v_pk_mul_f32 v[106:107], v[110:111], v[108:109] op_sel_hi:[1,0]
	v_pk_mul_f32 v[110:111], v[112:113], v[108:109] op_sel_hi:[1,0]
	s_waitcnt lgkmcnt(0)
	v_pk_fma_f32 v[100:101], v[106:107], v[114:115], v[100:101]
	v_pk_fma_f32 v[70:71], v[110:111], v[116:117], v[70:71]
	v_and_b32_sdwa v110, v101, v130 dst_sel:DWORD dst_unused:UNUSED_PAD src0_sel:WORD_1 src1_sel:DWORD
	v_and_b32_sdwa v107, v71, v130 dst_sel:DWORD dst_unused:UNUSED_PAD src0_sel:WORD_1 src1_sel:DWORD
	v_and_b32_sdwa v95, v70, v130 dst_sel:DWORD dst_unused:UNUSED_PAD src0_sel:WORD_1 src1_sel:DWORD
	v_and_b32_sdwa v106, v100, v130 dst_sel:DWORD dst_unused:UNUSED_PAD src0_sel:WORD_1 src1_sel:DWORD
	v_add3_u32 v107, v71, v107, s11
	v_add3_u32 v110, v101, v110, s11
	v_add3_u32 v106, v100, v106, s11
	v_add3_u32 v95, v70, v95, s11
	v_and_b32_e32 v107, 0xffff0000, v107
	v_and_b32_e32 v110, 0xffff0000, v110
	v_or_b32_sdwa v107, v107, v95 dst_sel:DWORD dst_unused:UNUSED_PAD src0_sel:DWORD src1_sel:WORD_1
	v_or_b32_sdwa v106, v110, v106 dst_sel:DWORD dst_unused:UNUSED_PAD src0_sel:DWORD src1_sel:WORD_1
	global_store_dwordx2 v[104:105], v[106:107], off offset:3072
	s_nop 0
	ds_read_b128 v[110:113], v141 offset:7168
	v_mov_b32_e32 v95, v140
	v_lshlrev_b32_e32 v106, 16, v68
	v_and_b32_e32 v107, 0xffff0000, v68
	v_lshlrev_b32_e32 v68, 16, v69
	v_and_b32_e32 v69, 0xffff0000, v69
	v_pk_mul_f32 v[94:95], v[94:95], v[108:109] op_sel_hi:[1,0]
	v_mov_b32_e32 v116, v86
	v_mov_b32_e32 v117, v80
	v_mov_b32_e32 v115, v88
	v_mov_b32_e32 v88, v85
	v_pk_mul_f32 v[116:117], v[116:117], v[116:117]
	v_mov_b32_e32 v80, v87
	v_pk_mul_f32 v[120:121], v[88:89], v[88:89]
	v_pk_fma_f32 v[116:117], v[80:81], v[80:81], v[116:117]
	v_mov_b32_e32 v114, v84
	v_pk_fma_f32 v[114:115], v[114:115], v[114:115], v[120:121]
	v_pk_mul_f32 v[120:121], v[78:79], v[78:79]
	v_pk_add_f32 v[114:115], v[114:115], v[116:117]
	v_pk_mul_f32 v[116:117], v[90:91], v[90:91]
	v_pk_add_f32 v[114:115], v[114:115], v[114:115] op_sel_hi:[0,1]
	v_pk_mov_b32 v[122:123], v[116:117], v[120:121] op_sel:[1,0]
	v_mov_b32_e32 v117, v121
	v_pk_add_f32 v[116:117], v[116:117], v[122:123]
	v_mul_f32_e32 v114, v74, v74
	v_pk_add_f32 v[116:117], v[116:117], v[116:117] op_sel_hi:[0,1]
	v_mul_f32_e32 v116, v75, v75
	s_waitcnt lgkmcnt(0)
	v_pk_fma_f32 v[68:69], v[102:103], v[112:113], v[68:69]
	v_pk_fma_f32 v[94:95], v[94:95], v[110:111], v[106:107]
	v_and_b32_sdwa v102, v69, v130 dst_sel:DWORD dst_unused:UNUSED_PAD src0_sel:WORD_1 src1_sel:DWORD
	v_and_b32_sdwa v103, v95, v130 dst_sel:DWORD dst_unused:UNUSED_PAD src0_sel:WORD_1 src1_sel:DWORD
	v_and_b32_sdwa v80, v68, v130 dst_sel:DWORD dst_unused:UNUSED_PAD src0_sel:WORD_1 src1_sel:DWORD
	v_and_b32_sdwa v88, v94, v130 dst_sel:DWORD dst_unused:UNUSED_PAD src0_sel:WORD_1 src1_sel:DWORD
	v_add3_u32 v102, v69, v102, s11
	v_add3_u32 v103, v95, v103, s11
	v_add3_u32 v88, v94, v88, s11
	v_add3_u32 v80, v68, v80, s11
	v_and_b32_e32 v102, 0xffff0000, v102
	v_and_b32_e32 v106, 0xffff0000, v103
	v_or_b32_sdwa v103, v102, v80 dst_sel:DWORD dst_unused:UNUSED_PAD src0_sel:DWORD src1_sel:WORD_1
	v_or_b32_sdwa v102, v106, v88 dst_sel:DWORD dst_unused:UNUSED_PAD src0_sel:DWORD src1_sel:WORD_1
	global_store_dwordx2 v[104:105], v[102:103], off offset:3584
	s_nop 0
	ds_read_b128 v[110:113], v141 offset:8192
	v_mul_f32_e32 v80, v92, v92
	v_mul_f32_e32 v88, v76, v76
	v_pk_fma_f32 v[102:103], v[92:93], v[92:93], v[80:81] op_sel_hi:[1,1,0]
	v_pk_fma_f32 v[104:105], v[76:77], v[76:77], v[88:89] op_sel_hi:[1,1,0]
	v_mul_f32_e32 v102, v96, v96
	v_mul_f32_e32 v104, v97, v97
	v_pk_add_f32 v[102:103], v[102:103], v[104:105]
	v_pk_add_f32 v[104:105], v[116:117], v[114:115]
	v_pk_mul_f32 v[106:107], v[72:73], v[72:73]
	v_pk_add_f32 v[102:103], v[102:103], v[104:105]
	v_pk_mul_f32 v[104:105], v[98:99], v[98:99]
	v_mul_f32_e32 v80, v100, v100
	v_pk_mov_b32 v[114:115], v[104:105], v[106:107] op_sel:[1,0]
	v_mov_b32_e32 v105, v107
	v_pk_add_f32 v[104:105], v[104:105], v[114:115]
	v_mul_f32_e32 v88, v70, v70
	v_pk_add_f32 v[102:103], v[102:103], v[102:103] op_sel_hi:[0,1]
	v_pk_add_f32 v[104:105], v[104:105], v[104:105] op_sel_hi:[0,1]
	v_pk_fma_f32 v[106:107], v[100:101], v[100:101], v[80:81] op_sel_hi:[1,1,0]
	v_pk_fma_f32 v[114:115], v[70:71], v[70:71], v[88:89] op_sel_hi:[1,1,0]
	v_mul_f32_e32 v106, v94, v94
	v_mul_f32_e32 v114, v95, v95
	v_mul_f32_e32 v102, v68, v68
	v_mul_f32_e32 v104, v69, v69
	v_pk_add_f32 v[106:107], v[106:107], v[114:115]
	v_pk_add_f32 v[102:103], v[104:105], v[102:103]
	s_nop 0
	v_pk_add_f32 v[102:103], v[106:107], v[102:103]
	v_mov_b32_e32 v106, v94
	v_add_f32_e32 v80, v102, v103
	ds_bpermute_b32 v88, v109, v80
	v_add_co_u32_e32 v102, vcc, s20, v82
	v_mov_b32_e32 v82, v84
	s_nop 0
	v_addc_co_u32_e32 v103, vcc, 0, v83, vcc
	s_waitcnt lgkmcnt(0)
; DI unsigned pk2(float lo, float hi) { return f2bf(lo) | (f2bf(hi) << 16); }
; template <int MODE, bool FIRST, bool LAST>
; DI void phase_rowpass(const float* xin, const bf16_t* M, const float* gpost, float* outf, bf16_t* HB, bf16_t* XN, const float* gnext, int gw, int NGW, int lane) {
;     ...
;         if (MODE == 1) { const float r2 = rsqrtf(wave_sum(s2) * (1.f / D_) + EPS); u32x2* o = (u32x2*)(XN + (size_t)row * D_) + lane;
; #pragma unroll
;             for (int j = 0; j < 8; ++j) { const f32x4 gv = ((const f32x4*)gnext)[lane + 64 * j]; u32x2 w; w.x = pk2(hv[j][0] * r2 * gv[0], hv[j][1] * r2 * gv[1]); w.y = pk2(hv[j][2] * r2 * gv[2], hv[j][3] * r2 * gv[3]); o[64 * j] = w; } }
	v_add_f32_e32 v80, v80, v88
	ds_bpermute_b32 v88, v124, v80
	v_mov_b32_e32 v107, v68
	v_mov_b32_e32 v68, v95
	s_waitcnt lgkmcnt(0)
	v_add_f32_e32 v80, v80, v88
	ds_bpermute_b32 v88, v125, v80
	s_waitcnt lgkmcnt(0)
	v_add_f32_e32 v80, v80, v88
	ds_bpermute_b32 v88, v126, v80
	s_waitcnt lgkmcnt(0)
	v_add_f32_e32 v80, v80, v88
	ds_bpermute_b32 v88, v127, v80
	s_waitcnt lgkmcnt(0)
	v_add_f32_e32 v80, v80, v88
	ds_bpermute_b32 v88, v128, v80
	s_waitcnt lgkmcnt(0)
	v_add_f32_e32 v80, v80, v88
	v_fmamk_f32 v80, v80, 0x3a000000, v129
	v_mul_f32_e32 v83, 0x4b800000, v80
	v_cmp_gt_f32_e32 vcc, s9, v80
	s_nop 1
	v_cndmask_b32_e32 v80, v80, v83, vcc
	v_rsq_f32_e32 v80, v80
	v_mov_b32_e32 v83, v86
	v_mov_b32_e32 v86, v85
	v_mul_f32_e32 v84, 0x45800000, v80
	v_cndmask_b32_e32 v104, v80, v84, vcc
	v_pk_mul_f32 v[82:83], v[82:83], v[104:105] op_sel_hi:[1,0]
	v_pk_mul_f32 v[84:85], v[86:87], v[104:105] op_sel_hi:[1,0]
	s_waitcnt lgkmcnt(0)
	v_mov_b32_e32 v86, v110
	v_mov_b32_e32 v87, v112
	v_mov_b32_e32 v112, v111
	v_pk_mul_f32 v[82:83], v[86:87], v[82:83]
	v_pk_mul_f32 v[84:85], v[112:113], v[84:85]
	v_and_b32_sdwa v80, v83, v130 dst_sel:DWORD dst_unused:UNUSED_PAD src0_sel:WORD_1 src1_sel:DWORD
	v_and_b32_sdwa v87, v85, v130 dst_sel:DWORD dst_unused:UNUSED_PAD src0_sel:WORD_1 src1_sel:DWORD
	v_and_b32_sdwa v88, v84, v130 dst_sel:DWORD dst_unused:UNUSED_PAD src0_sel:WORD_1 src1_sel:DWORD
	v_and_b32_sdwa v86, v82, v130 dst_sel:DWORD dst_unused:UNUSED_PAD src0_sel:WORD_1 src1_sel:DWORD
	v_add3_u32 v80, v83, v80, s11
	v_add3_u32 v83, v85, v87, s11
	v_add3_u32 v84, v84, v88, s11
	v_add3_u32 v82, v82, v86, s11
	v_and_b32_e32 v83, 0xffff0000, v83
	v_and_b32_e32 v84, 0xffff0000, v84
	v_or_b32_sdwa v83, v83, v80 dst_sel:DWORD dst_unused:UNUSED_PAD src0_sel:DWORD src1_sel:WORD_1
	v_or_b32_sdwa v82, v84, v82 dst_sel:DWORD dst_unused:UNUSED_PAD src0_sel:DWORD src1_sel:WORD_1
	global_store_dwordx2 v[102:103], v[82:83], off
	s_nop 0
	ds_read_b128 v[82:85], v141 offset:9216
	v_mov_b32_e32 v80, v89
	v_pk_mul_f32 v[80:81], v[80:81], v[104:105] op_sel_hi:[1,0]
	v_pk_mul_f32 v[86:87], v[118:119], v[104:105] op_sel_hi:[1,0]
	v_pk_mul_f32 v[94:95], v[106:107], v[104:105] op_sel_hi:[1,0]
	v_pk_mul_f32 v[68:69], v[68:69], v[104:105] op_sel_hi:[1,0]
	s_andn2_b64 vcc, exec, s[18:19]
	s_waitcnt lgkmcnt(0)
	v_mov_b32_e32 v89, v84
	v_mov_b32_e32 v84, v83
	v_mov_b32_e32 v88, v82
	v_pk_mul_f32 v[80:81], v[84:85], v[80:81]
	v_pk_mul_f32 v[82:83], v[88:89], v[86:87]
	v_and_b32_sdwa v86, v81, v130 dst_sel:DWORD dst_unused:UNUSED_PAD src0_sel:WORD_1 src1_sel:DWORD
	v_and_b32_sdwa v87, v80, v130 dst_sel:DWORD dst_unused:UNUSED_PAD src0_sel:WORD_1 src1_sel:DWORD
	v_and_b32_sdwa v84, v83, v130 dst_sel:DWORD dst_unused:UNUSED_PAD src0_sel:WORD_1 src1_sel:DWORD
	v_and_b32_sdwa v85, v82, v130 dst_sel:DWORD dst_unused:UNUSED_PAD src0_sel:WORD_1 src1_sel:DWORD
	v_add3_u32 v81, v81, v86, s11
	v_add3_u32 v80, v80, v87, s11
	v_add3_u32 v82, v82, v85, s11
	v_add3_u32 v83, v83, v84, s11
	v_and_b32_e32 v81, 0xffff0000, v81
	v_and_b32_e32 v80, 0xffff0000, v80
	v_or_b32_sdwa v81, v81, v83 dst_sel:DWORD dst_unused:UNUSED_PAD src0_sel:DWORD src1_sel:WORD_1
	v_or_b32_sdwa v80, v80, v82 dst_sel:DWORD dst_unused:UNUSED_PAD src0_sel:DWORD src1_sel:WORD_1
	global_store_dwordx2 v[102:103], v[80:81], off offset:512
	s_nop 0
	ds_read_b128 v[80:83], v141 offset:10240
	v_mov_b32_e32 v85, v78
	v_mov_b32_e32 v78, v91
	v_mov_b32_e32 v84, v90
	v_pk_mul_f32 v[78:79], v[78:79], v[104:105] op_sel_hi:[1,0]
	v_pk_mul_f32 v[84:85], v[84:85], v[104:105] op_sel_hi:[1,0]
	v_mov_b64_e32 v[88:89], v[62:63]
	v_mov_b64_e32 v[90:91], v[64:65]
	s_waitcnt lgkmcnt(0)
	v_mov_b32_e32 v87, v82
	v_mov_b32_e32 v82, v81
	v_mov_b32_e32 v86, v80
	v_pk_mul_f32 v[78:79], v[82:83], v[78:79]
	v_pk_mul_f32 v[80:81], v[86:87], v[84:85]
	v_and_b32_sdwa v84, v79, v130 dst_sel:DWORD dst_unused:UNUSED_PAD src0_sel:WORD_1 src1_sel:DWORD
	v_and_b32_sdwa v85, v78, v130 dst_sel:DWORD dst_unused:UNUSED_PAD src0_sel:WORD_1 src1_sel:DWORD
	v_and_b32_sdwa v82, v81, v130 dst_sel:DWORD dst_unused:UNUSED_PAD src0_sel:WORD_1 src1_sel:DWORD
	v_and_b32_sdwa v83, v80, v130 dst_sel:DWORD dst_unused:UNUSED_PAD src0_sel:WORD_1 src1_sel:DWORD
	v_add3_u32 v79, v79, v84, s11
	v_add3_u32 v78, v78, v85, s11
	v_add3_u32 v80, v80, v83, s11
	v_add3_u32 v81, v81, v82, s11
	v_and_b32_e32 v79, 0xffff0000, v79
	v_and_b32_e32 v78, 0xffff0000, v78
	v_or_b32_sdwa v79, v79, v81 dst_sel:DWORD dst_unused:UNUSED_PAD src0_sel:DWORD src1_sel:WORD_1
	v_or_b32_sdwa v78, v78, v80 dst_sel:DWORD dst_unused:UNUSED_PAD src0_sel:DWORD src1_sel:WORD_1
	global_store_dwordx2 v[102:103], v[78:79], off offset:1024
	s_nop 0
	ds_read_b128 v[78:81], v141 offset:11264
	v_mov_b32_e32 v83, v76
	v_mov_b32_e32 v76, v93
	v_mov_b32_e32 v82, v92
	v_pk_mul_f32 v[76:77], v[76:77], v[104:105] op_sel_hi:[1,0]
	v_pk_mul_f32 v[82:83], v[82:83], v[104:105] op_sel_hi:[1,0]
	v_mov_b64_e32 v[86:87], v[60:61]
	v_mov_b64_e32 v[92:93], v[52:53]
	s_waitcnt lgkmcnt(0)
	v_mov_b32_e32 v85, v80
	v_mov_b32_e32 v80, v79
	v_mov_b32_e32 v84, v78
	v_pk_mul_f32 v[76:77], v[80:81], v[76:77]
	v_pk_mul_f32 v[78:79], v[84:85], v[82:83]
	v_and_b32_sdwa v82, v77, v130 dst_sel:DWORD dst_unused:UNUSED_PAD src0_sel:WORD_1 src1_sel:DWORD
	v_and_b32_sdwa v83, v76, v130 dst_sel:DWORD dst_unused:UNUSED_PAD src0_sel:WORD_1 src1_sel:DWORD
	v_and_b32_sdwa v80, v79, v130 dst_sel:DWORD dst_unused:UNUSED_PAD src0_sel:WORD_1 src1_sel:DWORD
	v_and_b32_sdwa v81, v78, v130 dst_sel:DWORD dst_unused:UNUSED_PAD src0_sel:WORD_1 src1_sel:DWORD
	v_add3_u32 v77, v77, v82, s11
	v_add3_u32 v76, v76, v83, s11
	v_add3_u32 v78, v78, v81, s11
	v_add3_u32 v79, v79, v80, s11
	v_and_b32_e32 v77, 0xffff0000, v77
	v_and_b32_e32 v76, 0xffff0000, v76
	v_or_b32_sdwa v77, v77, v79 dst_sel:DWORD dst_unused:UNUSED_PAD src0_sel:DWORD src1_sel:WORD_1
	v_or_b32_sdwa v76, v76, v78 dst_sel:DWORD dst_unused:UNUSED_PAD src0_sel:DWORD src1_sel:WORD_1
	global_store_dwordx2 v[102:103], v[76:77], off offset:1536
	s_nop 0
	ds_read_b128 v[76:79], v141 offset:12288
	v_mov_b32_e32 v81, v74
	v_mov_b32_e32 v74, v97
	v_mov_b32_e32 v80, v96
	v_pk_mul_f32 v[74:75], v[74:75], v[104:105] op_sel_hi:[1,0]
	v_pk_mul_f32 v[80:81], v[80:81], v[104:105] op_sel_hi:[1,0]
	v_mov_b64_e32 v[84:85], v[66:67]
	v_mov_b64_e32 v[96:97], v[54:55]
	s_waitcnt lgkmcnt(0)
; DI unsigned pk2(float lo, float hi) { return f2bf(lo) | (f2bf(hi) << 16); }
; template <int MODE, bool FIRST, bool LAST>
; DI void phase_rowpass(const float* xin, const bf16_t* M, const float* gpost, float* outf, bf16_t* HB, bf16_t* XN, const float* gnext, int gw, int NGW, int lane) {
;     ...
;             for (int j = 0; j < 8; ++j) { const f32x4 gv = ((const f32x4*)gnext)[lane + 64 * j]; u32x2 w; w.x = pk2(hv[j][0] * r2 * gv[0], hv[j][1] * r2 * gv[1]); w.y = pk2(hv[j][2] * r2 * gv[2], hv[j][3] * r2 * gv[3]); o[64 * j] = w; } }
;         if (MODE == 2) { u32x2* o = (u32x2*)(XN + (size_t)row * D_) + lane;
; #pragma unroll
;             for (int j = 0; j < 8; ++j) { u32x2 w; w.x = pk2(hv[j][0], hv[j][1]); w.y = pk2(hv[j][2], hv[j][3]); o[64 * j] = w; } }
;         if (!has) break;
; #pragma unroll
;         for (int j = 0; j < 8; ++j) { hc.f[j] = hn.f[j]; mw[j] = mn[j]; }
;         row = nrow;
	v_mov_b32_e32 v83, v78
	v_mov_b32_e32 v78, v77
	v_mov_b32_e32 v82, v76
	v_pk_mul_f32 v[74:75], v[78:79], v[74:75]
	v_pk_mul_f32 v[76:77], v[82:83], v[80:81]
	v_and_b32_sdwa v80, v75, v130 dst_sel:DWORD dst_unused:UNUSED_PAD src0_sel:WORD_1 src1_sel:DWORD
	v_and_b32_sdwa v81, v74, v130 dst_sel:DWORD dst_unused:UNUSED_PAD src0_sel:WORD_1 src1_sel:DWORD
	v_and_b32_sdwa v78, v77, v130 dst_sel:DWORD dst_unused:UNUSED_PAD src0_sel:WORD_1 src1_sel:DWORD
	v_and_b32_sdwa v79, v76, v130 dst_sel:DWORD dst_unused:UNUSED_PAD src0_sel:WORD_1 src1_sel:DWORD
	v_add3_u32 v75, v75, v80, s11
	v_add3_u32 v74, v74, v81, s11
	v_add3_u32 v76, v76, v79, s11
	v_add3_u32 v77, v77, v78, s11
	v_and_b32_e32 v75, 0xffff0000, v75
	v_and_b32_e32 v74, 0xffff0000, v74
	v_or_b32_sdwa v75, v75, v77 dst_sel:DWORD dst_unused:UNUSED_PAD src0_sel:DWORD src1_sel:WORD_1
	v_or_b32_sdwa v74, v74, v76 dst_sel:DWORD dst_unused:UNUSED_PAD src0_sel:DWORD src1_sel:WORD_1
	global_store_dwordx2 v[102:103], v[74:75], off offset:2048
	s_nop 0
	ds_read_b128 v[74:77], v141 offset:13312
	v_mov_b32_e32 v79, v72
	v_mov_b32_e32 v72, v99
	v_mov_b32_e32 v78, v98
	v_pk_mul_f32 v[72:73], v[72:73], v[104:105] op_sel_hi:[1,0]
	v_pk_mul_f32 v[78:79], v[78:79], v[104:105] op_sel_hi:[1,0]
	v_mov_b64_e32 v[98:99], v[56:57]
	v_mov_b64_e32 v[82:83], v[36:37]
	s_waitcnt lgkmcnt(0)
	v_mov_b32_e32 v81, v76
	v_mov_b32_e32 v76, v75
	v_mov_b32_e32 v80, v74
	v_pk_mul_f32 v[72:73], v[76:77], v[72:73]
	v_pk_mul_f32 v[74:75], v[80:81], v[78:79]
	v_and_b32_sdwa v78, v73, v130 dst_sel:DWORD dst_unused:UNUSED_PAD src0_sel:WORD_1 src1_sel:DWORD
	v_and_b32_sdwa v79, v72, v130 dst_sel:DWORD dst_unused:UNUSED_PAD src0_sel:WORD_1 src1_sel:DWORD
	v_and_b32_sdwa v76, v75, v130 dst_sel:DWORD dst_unused:UNUSED_PAD src0_sel:WORD_1 src1_sel:DWORD
	v_and_b32_sdwa v77, v74, v130 dst_sel:DWORD dst_unused:UNUSED_PAD src0_sel:WORD_1 src1_sel:DWORD
	v_add3_u32 v73, v73, v78, s11
	v_add3_u32 v72, v72, v79, s11
	v_add3_u32 v74, v74, v77, s11
	v_add3_u32 v75, v75, v76, s11
	v_and_b32_e32 v73, 0xffff0000, v73
	v_and_b32_e32 v72, 0xffff0000, v72
	v_or_b32_sdwa v73, v73, v75 dst_sel:DWORD dst_unused:UNUSED_PAD src0_sel:DWORD src1_sel:WORD_1
	v_or_b32_sdwa v72, v72, v74 dst_sel:DWORD dst_unused:UNUSED_PAD src0_sel:DWORD src1_sel:WORD_1
	global_store_dwordx2 v[102:103], v[72:73], off offset:2560
	s_nop 0
	ds_read_b128 v[72:75], v141 offset:14336
	v_mov_b32_e32 v77, v70
	v_mov_b32_e32 v70, v101
	v_mov_b32_e32 v76, v100
	v_pk_mul_f32 v[70:71], v[70:71], v[104:105] op_sel_hi:[1,0]
	v_pk_mul_f32 v[76:77], v[76:77], v[104:105] op_sel_hi:[1,0]
	v_mov_b64_e32 v[100:101], v[58:59]
	v_mov_b64_e32 v[80:81], v[38:39]
	s_waitcnt lgkmcnt(0)
	v_mov_b32_e32 v79, v74
	v_mov_b32_e32 v74, v73
	v_mov_b32_e32 v78, v72
	v_pk_mul_f32 v[70:71], v[74:75], v[70:71]
	v_pk_mul_f32 v[72:73], v[78:79], v[76:77]
	v_and_b32_sdwa v76, v71, v130 dst_sel:DWORD dst_unused:UNUSED_PAD src0_sel:WORD_1 src1_sel:DWORD
	v_and_b32_sdwa v77, v70, v130 dst_sel:DWORD dst_unused:UNUSED_PAD src0_sel:WORD_1 src1_sel:DWORD
	v_and_b32_sdwa v74, v73, v130 dst_sel:DWORD dst_unused:UNUSED_PAD src0_sel:WORD_1 src1_sel:DWORD
	v_and_b32_sdwa v75, v72, v130 dst_sel:DWORD dst_unused:UNUSED_PAD src0_sel:WORD_1 src1_sel:DWORD
	v_add3_u32 v71, v71, v76, s11
	v_add3_u32 v70, v70, v77, s11
	v_add3_u32 v72, v72, v75, s11
	v_add3_u32 v73, v73, v74, s11
	v_and_b32_e32 v71, 0xffff0000, v71
	v_and_b32_e32 v70, 0xffff0000, v70
	v_or_b32_sdwa v71, v71, v73 dst_sel:DWORD dst_unused:UNUSED_PAD src0_sel:DWORD src1_sel:WORD_1
	v_or_b32_sdwa v70, v70, v72 dst_sel:DWORD dst_unused:UNUSED_PAD src0_sel:DWORD src1_sel:WORD_1
	global_store_dwordx2 v[102:103], v[70:71], off offset:3072
	s_nop 0
	ds_read_b128 v[110:113], v141 offset:15360
	v_mov_b64_e32 v[78:79], v[40:41]
	v_mov_b64_e32 v[76:77], v[42:43]
	v_mov_b64_e32 v[74:75], v[44:45]
	v_mov_b64_e32 v[72:73], v[46:47]
	v_mov_b64_e32 v[70:71], v[48:49]
	s_waitcnt vmcnt(0) lgkmcnt(0)
	v_mov_b32_e32 v105, v112
	v_mov_b32_e32 v112, v111
	v_mov_b32_e32 v104, v110
	v_pk_mul_f32 v[68:69], v[112:113], v[68:69]
	v_pk_mul_f32 v[94:95], v[104:105], v[94:95]
	v_and_b32_sdwa v106, v69, v130 dst_sel:DWORD dst_unused:UNUSED_PAD src0_sel:WORD_1 src1_sel:DWORD
	v_and_b32_sdwa v107, v68, v130 dst_sel:DWORD dst_unused:UNUSED_PAD src0_sel:WORD_1 src1_sel:DWORD
	v_and_b32_sdwa v104, v95, v130 dst_sel:DWORD dst_unused:UNUSED_PAD src0_sel:WORD_1 src1_sel:DWORD
	v_and_b32_sdwa v105, v94, v130 dst_sel:DWORD dst_unused:UNUSED_PAD src0_sel:WORD_1 src1_sel:DWORD
	v_add3_u32 v69, v69, v106, s11
	v_add3_u32 v68, v68, v107, s11
	v_add3_u32 v94, v94, v105, s11
	v_add3_u32 v95, v95, v104, s11
	v_and_b32_e32 v69, 0xffff0000, v69
	v_and_b32_e32 v68, 0xffff0000, v68
	v_or_b32_sdwa v69, v69, v95 dst_sel:DWORD dst_unused:UNUSED_PAD src0_sel:DWORD src1_sel:WORD_1
	v_or_b32_sdwa v68, v68, v94 dst_sel:DWORD dst_unused:UNUSED_PAD src0_sel:DWORD src1_sel:WORD_1
	global_store_dwordx2 v[102:103], v[68:69], off offset:3584
	v_mov_b64_e32 v[68:69], v[50:51]
	s_cbranch_vccz .LBB0_1135

; template <int MODE, bool FIRST, bool LAST>
; DI void phase_rowpass(const float* xin, const bf16_t* M, const float* gpost, float* outf, bf16_t* HB, bf16_t* XN, const float* gnext, int gw, int NGW, int lane) {
;     int row = gw; if (row >= T_) return;
;     HRow<FIRST> hc; u32x2 mw[8];
;     { const u32x2* mr = (const u32x2*)(M + (size_t)row * D_) + lane;
; #pragma unroll
;       for (int j = 0; j < 8; ++j) { if constexpr (FIRST) hc.f[j] = ((const f32x4*)(xin + (size_t)row * D_) + lane)[64 * j]; else hc.f[j] = ((const u32x2*)(HB + (size_t)row * D_) + lane)[64 * j]; mw[j] = mr[64 * j]; } }
;     ...
;         for (int j = 0; j < 8; ++j) { const f32x4 gv = ((const f32x4*)gpost)[lane + 64 * j]; hv[j] = hv[j] + mv[j] * rs * gv;
.LBB0_1361:
	s_cmp_lt_i32 s62, 19
	s_cselect_b64 s[8:9], -1, 0
	s_and_b64 s[6:7], s[8:9], s[6:7]
	s_andn2_b64 vcc, exec, s[6:7]
	s_cbranch_vccnz .LBB0_1367
	v_mov_b32_e32 v2, v1
	s_lshl_b32 s3, s2, 3
	v_readfirstlane_b32 s8, v2
	s_ashr_i32 s8, s8, 6
	s_add_i32 s8, s8, s3
	s_mov_b64 s[12:13], s[0:1]
	s_cmpk_gt_i32 s8, 0x3fff
	s_cbranch_scc1 .LBB0_1367
	s_waitcnt lgkmcnt(0)
	s_load_dwordx2 s[16:17], s[12:13], 0xc8
	s_load_dwordx2 s[14:15], s[12:13], 0x28
	s_ashr_i32 s9, s8, 31
	s_lshl_b32 s10, s74, 3
	s_lshl_b64 s[12:13], s[8:9], 12
	v_and_b32_e32 v12, 63, v2
	s_waitcnt lgkmcnt(0)
	s_add_u32 s12, s16, s12
	v_lshlrev_b32_e32 v2, 3, v12
	v_mov_b32_e32 v3, 0
	s_addc_u32 s13, s17, s13
	v_lshl_add_u64 v[4:5], s[12:13], 0, v[2:3]
	s_mov_b32 s3, 0xc000
	s_mov_b64 s[18:19], 0x14dcc000
	v_add_co_u32_e32 v10, vcc, s3, v4
	v_lshl_add_u64 v[6:7], v[4:5], 0, s[18:19]
	s_mov_b64 s[18:19], 0xc000
	v_addc_co_u32_e32 v11, vcc, 0, v5, vcc
	s_mov_b32 s9, 0x14dcc000
	v_lshl_add_u64 v[8:9], v[4:5], 0, s[18:19]
	v_add_co_u32_e32 v4, vcc, s9, v4
	s_add_i32 s18, s8, s10
	s_nop 0
	v_addc_co_u32_e32 v5, vcc, 0, v5, vcc
	global_load_dwordx2 v[82:83], v[6:7], off offset:512
	global_load_dwordx2 v[80:81], v[6:7], off offset:1024
	global_load_dwordx2 v[76:77], v[6:7], off offset:1536
	global_load_dwordx2 v[74:75], v[6:7], off offset:2048
	global_load_dwordx2 v[56:57], v[8:9], off offset:1024
	global_load_dwordx2 v[54:55], v[8:9], off offset:1536
	global_load_dwordx2 v[52:53], v[8:9], off offset:2048
	global_load_dwordx2 v[50:51], v[8:9], off offset:2560
	global_load_dwordx2 v[60:61], v[10:11], off
	global_load_dwordx2 v[84:85], v[4:5], off
	global_load_dwordx2 v[32:33], v[8:9], off offset:3072
	global_load_dwordx2 v[16:17], v[8:9], off offset:3584
	global_load_dwordx2 v[58:59], v[8:9], off offset:512
	global_load_dwordx2 v[70:71], v[6:7], off offset:2560
	global_load_dwordx2 v[64:65], v[6:7], off offset:3072
	global_load_dwordx2 v[62:63], v[6:7], off offset:3584
	v_mbcnt_lo_u32_b32 v4, -1, 0
	v_mbcnt_hi_u32_b32 v4, -1, v4
	v_and_b32_e32 v5, 64, v4
	v_add_u32_e32 v5, 64, v5
	v_xor_b32_e32 v6, 1, v4
	v_cmp_lt_i32_e32 vcc, v6, v5
	s_ashr_i32 s11, s10, 31
	s_ashr_i32 s19, s18, 31
	v_cndmask_b32_e32 v6, v4, v6, vcc
	v_lshlrev_b32_e32 v73, 2, v6
	v_xor_b32_e32 v6, 2, v4
	v_cmp_lt_i32_e32 vcc, v6, v5
	s_lshl_b64 s[18:19], s[18:19], 12
	s_mov_b32 s9, 0xffff0000
	v_cndmask_b32_e32 v6, v4, v6, vcc
	v_lshlrev_b32_e32 v94, 2, v6
	v_xor_b32_e32 v6, 4, v4
	v_cmp_lt_i32_e32 vcc, v6, v5
	v_mov_b32_e32 v99, 0x358637bd
	s_movk_i32 s20, 0x7fff
	v_cndmask_b32_e32 v6, v4, v6, vcc
	v_lshlrev_b32_e32 v95, 2, v6
	v_xor_b32_e32 v6, 8, v4
	v_cmp_lt_i32_e32 vcc, v6, v5
	s_nop 1
	v_cndmask_b32_e32 v6, v4, v6, vcc
	s_waitcnt vmcnt(0)
	v_lshlrev_b32_e32 v96, 2, v6
	v_xor_b32_e32 v6, 16, v4
	v_cmp_lt_i32_e32 vcc, v6, v5
	s_nop 1
	v_cndmask_b32_e32 v6, v4, v6, vcc
	v_lshlrev_b32_e32 v97, 2, v6
	v_xor_b32_e32 v6, 32, v4
	v_cmp_lt_i32_e32 vcc, v6, v5
	v_mov_b32_e32 v5, v3
	s_nop 0
	v_cndmask_b32_e32 v4, v4, v6, vcc
	v_lshlrev_b32_e32 v98, 2, v4
	v_lshlrev_b32_e32 v4, 4, v12
	v_lshl_add_u64 v[12:13], s[14:15], 0, v[4:5]
	s_mov_b64 s[14:15], 0x2000
	v_lshl_add_u64 v[4:5], v[12:13], 0, s[14:15]
	s_mov_b64 s[14:15], 0x3000
	v_lshl_add_u64 v[6:7], v[12:13], 0, s[14:15]
	s_mov_b64 s[14:15], 0x3400
	v_lshl_add_u64 v[8:9], v[12:13], 0, s[14:15]
	s_mov_b64 s[14:15], 0x3800
	v_lshl_add_u64 v[10:11], v[12:13], 0, s[14:15]
	s_mov_b64 s[14:15], 0x3c00
	v_lshl_add_u64 v[12:13], v[12:13], 0, s[14:15]
	s_lshl_b64 s[14:15], s[10:11], 12
	s_add_u32 s16, s16, s18
	s_addc_u32 s17, s17, s19
	s_mov_b32 s11, 0x800000
	v_and_b32_e32 v118, 63, v1
	v_lshlrev_b32_e32 v118, 4, v118
	global_load_dwordx4 v[120:123], v[4:5], off
	global_load_dwordx4 v[124:127], v[4:5], off offset:1024
	global_load_dwordx4 v[128:131], v[4:5], off offset:2048
	global_load_dwordx4 v[132:135], v[4:5], off offset:3072
	global_load_dwordx4 v[136:139], v[6:7], off
	global_load_dwordx4 v[140:143], v[8:9], off
	global_load_dwordx4 v[144:147], v[10:11], off
	global_load_dwordx4 v[148:151], v[12:13], off
	s_waitcnt vmcnt(0)
	ds_write_b128 v118, v[120:123] offset:0
	ds_write_b128 v118, v[124:127] offset:1024
	ds_write_b128 v118, v[128:131] offset:2048
	ds_write_b128 v118, v[132:135] offset:3072
	ds_write_b128 v118, v[136:139] offset:4096
	ds_write_b128 v118, v[140:143] offset:5120
	ds_write_b128 v118, v[144:147] offset:6144
	ds_write_b128 v118, v[148:151] offset:7168
	s_waitcnt lgkmcnt(0)
	s_branch .LBB0_1365
; DI unsigned pk2(float lo, float hi) { return f2bf(lo) | (f2bf(hi) << 16); }
; DI float lo_f(unsigned w) { return __uint_as_float(w << 16); }
; DI float hi_f(unsigned w) { return __uint_as_float(w & 0xffff0000u); }
; template <int MODE, bool FIRST, bool LAST>
; DI void phase_rowpass(const float* xin, const bf16_t* M, const float* gpost, float* outf, bf16_t* HB, bf16_t* XN, const float* gnext, int gw, int NGW, int lane) {
;     ...
;         f32x4 hv[8], mv[8]; float ss = 0.f;
; #pragma unroll
;         for (int j = 0; j < 8; ++j) { const u32x2 w = mw[j]; mv[j] = (f32x4){lo_f(w.x), hi_f(w.x), lo_f(w.y), hi_f(w.y)};
;             if constexpr (FIRST) hv[j] = hc.f[j]; else { const u32x2 hw = hc.f[j]; hv[j] = (f32x4){lo_f(hw.x), hi_f(hw.x), lo_f(hw.y), hi_f(hw.y)}; }
;             ss += (mv[j][0] * mv[j][0] + mv[j][1] * mv[j][1]) + (mv[j][2] * mv[j][2] + mv[j][3] * mv[j][3]); }
;         const float rs = rsqrtf(wave_sum(ss) * (1.f / D_) + EPS);
;         float s2 = 0.f;
; #pragma unroll
;         for (int j = 0; j < 8; ++j) { const f32x4 gv = ((const f32x4*)gpost)[lane + 64 * j]; hv[j] = hv[j] + mv[j] * rs * gv;
;             if constexpr (LAST) ((f32x4*)(outf + (size_t)row * D_) + lane)[64 * j] = hv[j];
;             else { u32x2 w; w.x = pk2(hv[j][0], hv[j][1]); w.y = pk2(hv[j][2], hv[j][3]); ((u32x2*)(HB + (size_t)row * D_) + lane)[64 * j] = w; }
.LBB0_1364:
	ds_read_b128 v[100:103], v118 offset:0
	v_and_b32_e32 v105, 0xffff0000, v84
	v_and_b32_e32 v104, 0xffff0000, v82
	v_and_b32_e32 v109, 0xffff0000, v85
	v_and_b32_e32 v108, 0xffff0000, v83
	v_lshlrev_b32_e32 v93, 16, v84
	v_lshlrev_b32_e32 v92, 16, v82
	v_lshlrev_b32_e32 v107, 16, v85
	v_lshlrev_b32_e32 v106, 16, v83
	v_pk_mul_f32 v[66:67], v[104:105], v[104:105]
	v_pk_mul_f32 v[68:69], v[108:109], v[108:109]
	v_pk_fma_f32 v[66:67], v[92:93], v[92:93], v[66:67]
	v_pk_fma_f32 v[68:69], v[106:107], v[106:107], v[68:69]
	v_and_b32_e32 v91, 0xffff0000, v81
	v_pk_add_f32 v[66:67], v[66:67], v[68:69]
	v_and_b32_e32 v90, 0xffff0000, v80
	v_pk_add_f32 v[66:67], v[66:67], v[66:67] op_sel_hi:[0,1]
	v_lshlrev_b32_e32 v89, 16, v81
	v_lshlrev_b32_e32 v88, 16, v80
	v_pk_mul_f32 v[68:69], v[90:91], v[90:91]
	v_lshlrev_b32_e32 v82, 16, v76
	v_and_b32_e32 v83, 0xffff0000, v76
	v_lshlrev_b32_e32 v84, 16, v77
	v_lshlrev_b32_e32 v80, 16, v74
	v_pk_fma_f32 v[68:69], v[88:89], v[88:89], v[68:69]
	v_mul_f32_e32 v81, v82, v82
	v_mul_f32_e32 v79, v83, v83
	v_and_b32_e32 v85, 0xffff0000, v77
	v_mul_f32_e32 v66, v84, v84
	v_mov_b32_e32 v78, v80
	v_pk_add_f32 v[68:69], v[68:69], v[68:69] op_sel_hi:[0,1]
	v_pk_fma_f32 v[86:87], v[84:85], v[84:85], v[66:67] op_sel_hi:[1,1,0]
	v_and_b32_e32 v116, 0xffff0000, v74
	v_lshlrev_b32_e32 v76, 16, v75
	v_and_b32_e32 v77, 0xffff0000, v75
	v_pk_add_f32 v[78:79], v[80:81], v[78:79]
	v_mul_f32_e32 v86, v116, v116
	v_mul_f32_e32 v68, v76, v76
	v_mul_f32_e32 v66, v77, v77
	v_mul_f32_e32 v74, v80, v80
	v_mov_b32_e32 v75, v79
	v_pk_add_f32 v[74:75], v[74:75], v[86:87]
	v_pk_add_f32 v[66:67], v[68:69], v[66:67]
	v_lshlrev_b32_e32 v86, 16, v64
	v_pk_add_f32 v[66:67], v[74:75], v[66:67]
	v_lshlrev_b32_e32 v75, 16, v71
	v_lshlrev_b32_e32 v74, 16, v70
	v_and_b32_e32 v71, 0xffff0000, v71
	v_and_b32_e32 v70, 0xffff0000, v70
	v_pk_add_f32 v[78:79], v[66:67], v[66:67] op_sel_hi:[0,1]
	v_pk_mul_f32 v[66:67], v[70:71], v[70:71]
	v_and_b32_e32 v87, 0xffff0000, v64
	v_pk_fma_f32 v[66:67], v[74:75], v[74:75], v[66:67]
	v_lshlrev_b32_e32 v64, 16, v65
	v_pk_add_f32 v[110:111], v[66:67], v[66:67] op_sel_hi:[0,1]
	v_mul_f32_e32 v67, v86, v86
	v_and_b32_e32 v65, 0xffff0000, v65
	v_mul_f32_e32 v66, v64, v64
	v_pk_fma_f32 v[114:115], v[64:65], v[64:65], v[66:67] op_sel_hi:[1,1,0]
	v_lshlrev_b32_e32 v66, 16, v62
	v_mul_f32_e32 v113, v87, v87
	v_mov_b32_e32 v112, v66
	v_and_b32_e32 v117, 0xffff0000, v62
	v_lshlrev_b32_e32 v68, 16, v63
	v_and_b32_e32 v69, 0xffff0000, v63
	v_pk_add_f32 v[112:113], v[66:67], v[112:113]
	v_mul_f32_e32 v114, v117, v117
	v_mul_f32_e32 v110, v68, v68
	v_mul_f32_e32 v78, v69, v69
	v_mul_f32_e32 v62, v66, v66
	v_mov_b32_e32 v63, v113
	v_pk_add_f32 v[62:63], v[62:63], v[114:115]
	v_pk_add_f32 v[78:79], v[110:111], v[78:79]
	v_mov_b32_e32 v110, v93
	v_pk_add_f32 v[62:63], v[62:63], v[78:79]
	v_mov_b32_e32 v111, v105
	v_add_f32_e32 v62, v62, v63
	ds_bpermute_b32 v63, v73, v62
	v_mov_b32_e32 v112, v107
	v_mov_b32_e32 v113, v109
	v_lshl_add_u64 v[78:79], s[12:13], 0, v[2:3]
	v_mov_b32_e32 v93, v104
	s_waitcnt lgkmcnt(0)
	v_add_f32_e32 v62, v62, v63
	ds_bpermute_b32 v63, v94, v62
	v_mov_b32_e32 v107, v108
	s_add_u32 s12, s12, s14
	s_addc_u32 s13, s13, s15
	s_add_u32 s16, s16, s14
	s_waitcnt lgkmcnt(0)
	v_add_f32_e32 v62, v62, v63
	ds_bpermute_b32 v63, v95, v62
	s_addc_u32 s17, s17, s15
	s_waitcnt lgkmcnt(0)
	v_add_f32_e32 v62, v62, v63
	ds_bpermute_b32 v63, v96, v62
	s_waitcnt lgkmcnt(0)
	v_add_f32_e32 v62, v62, v63
	ds_bpermute_b32 v63, v97, v62
	s_waitcnt lgkmcnt(0)
	v_add_f32_e32 v63, v62, v63
	ds_bpermute_b32 v67, v98, v63
	v_lshlrev_b32_e32 v62, 16, v60
	s_waitcnt lgkmcnt(0)
	v_add_f32_e32 v63, v63, v67
	v_fmamk_f32 v63, v63, 0x3a000000, v99
	v_mul_f32_e32 v67, 0x4b800000, v63
	v_cmp_gt_f32_e32 vcc, s11, v63
	s_nop 1
	v_cndmask_b32_e32 v63, v63, v67, vcc
	v_rsq_f32_e32 v67, v63
	v_and_b32_e32 v63, 0xffff0000, v60
	v_lshlrev_b32_e32 v60, 16, v61
	v_and_b32_e32 v61, 0xffff0000, v61
	v_mul_f32_e32 v72, 0x45800000, v67
	v_cndmask_b32_e32 v72, v67, v72, vcc
	v_pk_mul_f32 v[110:111], v[110:111], v[72:73] op_sel_hi:[1,0]
	v_pk_mul_f32 v[112:113], v[112:113], v[72:73] op_sel_hi:[1,0]
	s_waitcnt vmcnt(0) lgkmcnt(0)
	v_pk_fma_f32 v[62:63], v[100:101], v[110:111], v[62:63]
	v_pk_fma_f32 v[60:61], v[102:103], v[112:113], v[60:61]
	v_bfe_u32 v67, v62, 16, 1
	v_add3_u32 v62, v62, v67, s20
	v_bfe_u32 v67, v63, 16, 1
	v_lshrrev_b32_e32 v62, 16, v62
	v_add3_u32 v63, v63, v67, s20
	v_and_or_b32 v62, v63, s9, v62
	v_bfe_u32 v63, v60, 16, 1
	v_add3_u32 v60, v60, v63, s20
	v_bfe_u32 v63, v61, 16, 1
	v_lshrrev_b32_e32 v60, 16, v60
	v_add3_u32 v61, v61, v63, s20
	v_add_co_u32_e32 v78, vcc, s3, v78
	v_and_or_b32 v63, v61, s9, v60
	s_nop 0
	v_addc_co_u32_e32 v79, vcc, 0, v79, vcc
	global_store_dwordx2 v[78:79], v[62:63], off
	s_nop 0
	ds_read_b128 v[60:63], v118 offset:1024
	v_lshlrev_b32_e32 v100, 16, v58
	v_and_b32_e32 v101, 0xffff0000, v58
	v_lshlrev_b32_e32 v58, 16, v59
	v_and_b32_e32 v59, 0xffff0000, v59
	v_pk_mul_f32 v[92:93], v[92:93], v[72:73] op_sel_hi:[1,0]
	v_pk_mul_f32 v[102:103], v[106:107], v[72:73] op_sel_hi:[1,0]
	v_pk_mul_f32 v[68:69], v[68:69], v[72:73] op_sel_hi:[1,0]
	s_andn2_b64 vcc, exec, s[18:19]
	s_waitcnt lgkmcnt(0)
; DI unsigned pk2(float lo, float hi) { return f2bf(lo) | (f2bf(hi) << 16); }
; template <int MODE, bool FIRST, bool LAST>
; DI void phase_rowpass(const float* xin, const bf16_t* M, const float* gpost, float* outf, bf16_t* HB, bf16_t* XN, const float* gnext, int gw, int NGW, int lane) {
;     ...
;         for (int j = 0; j < 8; ++j) { const f32x4 gv = ((const f32x4*)gpost)[lane + 64 * j]; hv[j] = hv[j] + mv[j] * rs * gv;
;             if constexpr (LAST) ((f32x4*)(outf + (size_t)row * D_) + lane)[64 * j] = hv[j];
;             else { u32x2 w; w.x = pk2(hv[j][0], hv[j][1]); w.y = pk2(hv[j][2], hv[j][3]); ((u32x2*)(HB + (size_t)row * D_) + lane)[64 * j] = w; }
;             s2 += (hv[j][0] * hv[j][0] + hv[j][1] * hv[j][1]) + (hv[j][2] * hv[j][2] + hv[j][3] * hv[j][3]); }
;         if (MODE == 1) { const float r2 = rsqrtf(wave_sum(s2) * (1.f / D_) + EPS); u32x2* o = (u32x2*)(XN + (size_t)row * D_) + lane;
; #pragma unroll
;             for (int j = 0; j < 8; ++j) { const f32x4 gv = ((const f32x4*)gnext)[lane + 64 * j]; u32x2 w; w.x = pk2(hv[j][0] * r2 * gv[0], hv[j][1] * r2 * gv[1]); w.y = pk2(hv[j][2] * r2 * gv[2], hv[j][3] * r2 * gv[3]); o[64 * j] = w; } }
;         if (MODE == 2) { u32x2* o = (u32x2*)(XN + (size_t)row * D_) + lane;
; #pragma unroll
;             for (int j = 0; j < 8; ++j) { u32x2 w; w.x = pk2(hv[j][0], hv[j][1]); w.y = pk2(hv[j][2], hv[j][3]); o[64 * j] = w; } }
;         if (!has) break;
; #pragma unroll
;         for (int j = 0; j < 8; ++j) { hc.f[j] = hn.f[j]; mw[j] = mn[j]; }
;         row = nrow;
	v_pk_fma_f32 v[58:59], v[62:63], v[102:103], v[58:59]
	v_pk_fma_f32 v[60:61], v[60:61], v[92:93], v[100:101]
	v_bfe_u32 v67, v58, 16, 1
	v_bfe_u32 v62, v60, 16, 1
	v_bfe_u32 v63, v61, 16, 1
	v_bfe_u32 v81, v59, 16, 1
	v_add3_u32 v60, v60, v62, s20
	v_add3_u32 v58, v58, v67, s20
	v_add3_u32 v61, v61, v63, s20
	v_add3_u32 v59, v59, v81, s20
	v_lshrrev_b32_e32 v60, 16, v60
	v_lshrrev_b32_e32 v62, 16, v58
	v_and_or_b32 v58, v61, s9, v60
	v_and_or_b32 v59, v59, s9, v62
	global_store_dwordx2 v[78:79], v[58:59], off offset:512
	s_nop 0
	ds_read_b128 v[58:61], v118 offset:2048
	v_mov_b32_e32 v92, v88
	v_mov_b32_e32 v93, v90
	v_mov_b32_e32 v90, v89
	v_lshlrev_b32_e32 v62, 16, v56
	v_and_b32_e32 v63, 0xffff0000, v56
	v_lshlrev_b32_e32 v56, 16, v57
	v_and_b32_e32 v57, 0xffff0000, v57
	v_pk_mul_f32 v[88:89], v[72:73], v[92:93] op_sel_hi:[0,1]
	v_pk_mul_f32 v[90:91], v[72:73], v[90:91] op_sel_hi:[0,1]
	v_mov_b32_e32 v81, v116
	v_mov_b32_e32 v67, v117
	v_pk_mul_f32 v[66:67], v[66:67], v[72:73] op_sel_hi:[1,0]
	s_waitcnt lgkmcnt(0)
	v_pk_fma_f32 v[56:57], v[60:61], v[90:91], v[56:57]
	v_pk_fma_f32 v[58:59], v[58:59], v[88:89], v[62:63]
	v_bfe_u32 v62, v56, 16, 1
	v_bfe_u32 v60, v58, 16, 1
	v_bfe_u32 v61, v59, 16, 1
	v_bfe_u32 v63, v57, 16, 1
	v_add3_u32 v58, v58, v60, s20
	v_add3_u32 v56, v56, v62, s20
	v_add3_u32 v59, v59, v61, s20
	v_add3_u32 v57, v57, v63, s20
	v_lshrrev_b32_e32 v58, 16, v58
	v_lshrrev_b32_e32 v60, 16, v56
	v_and_or_b32 v56, v59, s9, v58
	v_and_or_b32 v57, v57, s9, v60
	global_store_dwordx2 v[78:79], v[56:57], off offset:1024
	s_nop 0
	ds_read_b128 v[56:59], v118 offset:3072
	v_lshlrev_b32_e32 v60, 16, v54
	v_and_b32_e32 v61, 0xffff0000, v54
	v_lshlrev_b32_e32 v54, 16, v55
	v_and_b32_e32 v55, 0xffff0000, v55
	v_pk_mul_f32 v[62:63], v[82:83], v[72:73] op_sel_hi:[1,0]
	v_pk_mul_f32 v[82:83], v[84:85], v[72:73] op_sel_hi:[1,0]
	v_lshlrev_b32_e32 v90, 16, v16
	v_and_b32_e32 v91, 0xffff0000, v16
	v_lshlrev_b32_e32 v16, 16, v17
	v_and_b32_e32 v17, 0xffff0000, v17
	v_mov_b64_e32 v[84:85], v[40:41]
	s_waitcnt lgkmcnt(0)
	v_pk_fma_f32 v[54:55], v[58:59], v[82:83], v[54:55]
	v_pk_fma_f32 v[56:57], v[56:57], v[62:63], v[60:61]
	v_bfe_u32 v60, v54, 16, 1
	v_bfe_u32 v58, v56, 16, 1
	v_bfe_u32 v59, v57, 16, 1
	v_bfe_u32 v61, v55, 16, 1
	v_add3_u32 v56, v56, v58, s20
	v_add3_u32 v54, v54, v60, s20
	v_add3_u32 v57, v57, v59, s20
	v_add3_u32 v55, v55, v61, s20
	v_lshrrev_b32_e32 v56, 16, v56
	v_lshrrev_b32_e32 v58, 16, v54
	v_and_or_b32 v54, v57, s9, v56
	v_and_or_b32 v55, v55, s9, v58
	global_store_dwordx2 v[78:79], v[54:55], off offset:1536
	s_nop 0
	ds_read_b128 v[54:57], v118 offset:4096
	v_lshlrev_b32_e32 v58, 16, v52
	v_and_b32_e32 v59, 0xffff0000, v52
	v_lshlrev_b32_e32 v52, 16, v53
	v_and_b32_e32 v53, 0xffff0000, v53
	v_pk_mul_f32 v[60:61], v[80:81], v[72:73] op_sel_hi:[1,0]
	v_pk_mul_f32 v[62:63], v[76:77], v[72:73] op_sel_hi:[1,0]
	v_mov_b64_e32 v[76:77], v[34:35]
	v_mov_b64_e32 v[80:81], v[36:37]
	v_mov_b64_e32 v[82:83], v[38:39]
	s_waitcnt lgkmcnt(0)
	v_pk_fma_f32 v[52:53], v[56:57], v[62:63], v[52:53]
	v_pk_fma_f32 v[54:55], v[54:55], v[60:61], v[58:59]
	v_bfe_u32 v58, v52, 16, 1
	v_bfe_u32 v56, v54, 16, 1
	v_bfe_u32 v57, v55, 16, 1
	v_bfe_u32 v59, v53, 16, 1
	v_add3_u32 v54, v54, v56, s20
	v_add3_u32 v52, v52, v58, s20
	v_add3_u32 v55, v55, v57, s20
	v_add3_u32 v53, v53, v59, s20
	v_lshrrev_b32_e32 v54, 16, v54
	v_lshrrev_b32_e32 v56, 16, v52
	v_and_or_b32 v52, v55, s9, v54
	v_and_or_b32 v53, v53, s9, v56
	global_store_dwordx2 v[78:79], v[52:53], off offset:2048
	s_nop 0
	ds_read_b128 v[52:55], v118 offset:5120
	v_mov_b32_e32 v58, v74
	v_mov_b32_e32 v59, v70
	v_mov_b32_e32 v70, v75
	v_lshlrev_b32_e32 v56, 16, v50
	v_and_b32_e32 v57, 0xffff0000, v50
	v_lshlrev_b32_e32 v50, 16, v51
	v_and_b32_e32 v51, 0xffff0000, v51
	v_pk_mul_f32 v[58:59], v[72:73], v[58:59] op_sel_hi:[0,1]
	v_pk_mul_f32 v[60:61], v[72:73], v[70:71] op_sel_hi:[0,1]
	v_mov_b64_e32 v[62:63], v[48:49]
	v_mov_b64_e32 v[70:71], v[44:45]
	v_mov_b64_e32 v[74:75], v[46:47]
	s_waitcnt lgkmcnt(0)
	v_pk_fma_f32 v[50:51], v[54:55], v[60:61], v[50:51]
	v_pk_fma_f32 v[52:53], v[52:53], v[58:59], v[56:57]
	v_bfe_u32 v56, v50, 16, 1
	v_bfe_u32 v54, v52, 16, 1
	v_bfe_u32 v55, v53, 16, 1
	v_bfe_u32 v57, v51, 16, 1
	v_add3_u32 v52, v52, v54, s20
	v_add3_u32 v50, v50, v56, s20
	v_add3_u32 v53, v53, v55, s20
	v_add3_u32 v51, v51, v57, s20
	v_lshrrev_b32_e32 v52, 16, v52
	v_lshrrev_b32_e32 v54, 16, v50
	v_and_or_b32 v50, v53, s9, v52
	v_and_or_b32 v51, v51, s9, v54
	global_store_dwordx2 v[78:79], v[50:51], off offset:2560
	s_nop 0
	ds_read_b128 v[50:53], v118 offset:6144
	v_lshlrev_b32_e32 v54, 16, v32
	v_and_b32_e32 v55, 0xffff0000, v32
	v_lshlrev_b32_e32 v32, 16, v33
	v_and_b32_e32 v33, 0xffff0000, v33
	v_pk_mul_f32 v[56:57], v[86:87], v[72:73] op_sel_hi:[1,0]
	v_pk_mul_f32 v[58:59], v[64:65], v[72:73] op_sel_hi:[1,0]
	v_mov_b64_e32 v[64:65], v[42:43]
	v_mov_b64_e32 v[60:61], v[14:15]
	s_waitcnt lgkmcnt(0)
	v_pk_fma_f32 v[32:33], v[58:59], v[52:53], v[32:33]
	v_pk_fma_f32 v[50:51], v[56:57], v[50:51], v[54:55]
	v_bfe_u32 v54, v32, 16, 1
	v_bfe_u32 v52, v50, 16, 1
	v_bfe_u32 v53, v51, 16, 1
	v_bfe_u32 v55, v33, 16, 1
	v_add3_u32 v50, v50, v52, s20
	v_add3_u32 v32, v32, v54, s20
	v_add3_u32 v51, v51, v53, s20
	v_add3_u32 v33, v33, v55, s20
	v_lshrrev_b32_e32 v50, 16, v50
	v_lshrrev_b32_e32 v52, 16, v32
	v_and_or_b32 v32, v51, s9, v50
	v_and_or_b32 v33, v33, s9, v52
	global_store_dwordx2 v[78:79], v[32:33], off offset:3072
	s_nop 0
	ds_read_b128 v[86:89], v118 offset:7168
	v_mov_b64_e32 v[58:59], v[18:19]
	v_mov_b64_e32 v[56:57], v[20:21]
	v_mov_b64_e32 v[54:55], v[22:23]
	v_mov_b64_e32 v[52:53], v[24:25]
	v_mov_b64_e32 v[50:51], v[26:27]
	v_mov_b64_e32 v[32:33], v[28:29]
	s_waitcnt vmcnt(0) lgkmcnt(0)
	v_pk_fma_f32 v[16:17], v[68:69], v[88:89], v[16:17]
	v_pk_fma_f32 v[66:67], v[66:67], v[86:87], v[90:91]
	v_bfe_u32 v72, v16, 16, 1
	v_bfe_u32 v68, v66, 16, 1
	v_bfe_u32 v69, v67, 16, 1
	v_bfe_u32 v86, v17, 16, 1
	v_add3_u32 v66, v66, v68, s20
	v_add3_u32 v16, v16, v72, s20
	v_add3_u32 v67, v67, v69, s20
	v_add3_u32 v17, v17, v86, s20
	v_lshrrev_b32_e32 v66, 16, v66
	v_lshrrev_b32_e32 v68, 16, v16
	v_and_or_b32 v16, v67, s9, v66
	v_and_or_b32 v17, v17, s9, v68
	global_store_dwordx2 v[78:79], v[16:17], off offset:3584
	v_mov_b64_e32 v[16:17], v[30:31]
	s_cbranch_vccz .LBB0_1367

; template <int MODE, bool FIRST, bool LAST>
; DI void phase_rowpass(const float* xin, const bf16_t* M, const float* gpost, float* outf, bf16_t* HB, bf16_t* XN, const float* gnext, int gw, int NGW, int lane) {
;     int row = gw; if (row >= T_) return;
;     HRow<FIRST> hc; u32x2 mw[8];
;     { const u32x2* mr = (const u32x2*)(M + (size_t)row * D_) + lane;
; #pragma unroll
;       for (int j = 0; j < 8; ++j) { if constexpr (FIRST) hc.f[j] = ((const f32x4*)(xin + (size_t)row * D_) + lane)[64 * j]; else hc.f[j] = ((const u32x2*)(HB + (size_t)row * D_) + lane)[64 * j]; mw[j] = mr[64 * j]; } }
;     ...
;         for (int j = 0; j < 8; ++j) { const f32x4 gv = ((const f32x4*)gpost)[lane + 64 * j]; hv[j] = hv[j] + mv[j] * rs * gv;
;             if constexpr (LAST) ((f32x4*)(outf + (size_t)row * D_) + lane)[64 * j] = hv[j];
.LBB0_1456:
	s_cmp_lt_i32 s62, 21
	s_cselect_b64 s[4:5], -1, 0
	s_and_b64 s[4:5], s[4:5], s[6:7]
	s_andn2_b64 vcc, exec, s[4:5]
	s_cbranch_vccnz .LBB0_1462
	v_mov_b32_e32 v2, v1
	s_lshl_b32 s2, s2, 3
	v_readfirstlane_b32 s3, v2
	s_ashr_i32 s3, s3, 6
	s_add_i32 s2, s3, s2
	s_cmpk_gt_i32 s2, 0x3fff
	s_cbranch_scc1 .LBB0_1462
	s_load_dwordx4 s[4:7], s[0:1], 0xc0
	s_load_dwordx2 s[12:13], s[0:1], 0x30
	s_ashr_i32 s3, s2, 31
	s_lshl_b32 s8, s74, 3
	s_lshl_b64 s[0:1], s[2:3], 12
	v_and_b32_e32 v10, 63, v2
	s_waitcnt lgkmcnt(0)
	s_add_u32 s0, s6, s0
	v_lshlrev_b32_e32 v16, 3, v10
	v_mov_b32_e32 v17, 0
	s_addc_u32 s1, s7, s1
	v_lshl_add_u64 v[2:3], s[0:1], 0, v[16:17]
	s_mov_b64 s[0:1], 0xc000
	v_lshl_add_u64 v[6:7], v[2:3], 0, s[0:1]
	s_mov_b32 s0, 0xc000
	v_add_co_u32_e32 v8, vcc, s0, v2
	s_mov_b64 s[10:11], 0x14dcc000
	s_nop 0
	v_addc_co_u32_e32 v9, vcc, 0, v3, vcc
	s_mov_b32 s0, 0x14dcc000
	v_lshl_add_u64 v[4:5], v[2:3], 0, s[10:11]
	v_add_co_u32_e32 v2, vcc, s0, v2
	v_lshlrev_b32_e32 v12, 4, v10
	s_nop 0
	v_addc_co_u32_e32 v3, vcc, 0, v3, vcc
	global_load_dwordx2 v[76:77], v[4:5], off offset:512
	global_load_dwordx2 v[74:75], v[4:5], off offset:1024
	global_load_dwordx2 v[72:73], v[4:5], off offset:1536
	global_load_dwordx2 v[70:71], v[4:5], off offset:2048
	global_load_dwordx2 v[58:59], v[6:7], off offset:1024
	global_load_dwordx2 v[56:57], v[6:7], off offset:1536
	global_load_dwordx2 v[38:39], v[6:7], off offset:2048
	global_load_dwordx2 v[20:21], v[6:7], off offset:2560
	global_load_dwordx2 v[62:63], v[8:9], off
	global_load_dwordx2 v[78:79], v[2:3], off
	global_load_dwordx2 v[18:19], v[6:7], off offset:3072
	global_load_dwordx2 v[14:15], v[6:7], off offset:3584
	global_load_dwordx2 v[60:61], v[6:7], off offset:512
	global_load_dwordx2 v[68:69], v[4:5], off offset:2560
	global_load_dwordx2 v[66:67], v[4:5], off offset:3072
	global_load_dwordx2 v[64:65], v[4:5], off offset:3584
	v_mbcnt_lo_u32_b32 v2, -1, 0
	v_mbcnt_hi_u32_b32 v2, -1, v2
	v_and_b32_e32 v3, 64, v2
	v_add_u32_e32 v3, 64, v3
	v_xor_b32_e32 v4, 1, v2
	v_cmp_lt_i32_e32 vcc, v4, v3
	v_mov_b32_e32 v13, v17
	v_lshl_add_u64 v[10:11], s[12:13], 0, v[12:13]
	v_cndmask_b32_e32 v4, v2, v4, vcc
	v_lshlrev_b32_e32 v84, 2, v4
	v_xor_b32_e32 v4, 2, v2
	v_cmp_lt_i32_e32 vcc, v4, v3
	s_mov_b64 s[0:1], 0x2000
	v_mov_b32_e32 v90, 0x358637bd
	v_cndmask_b32_e32 v4, v2, v4, vcc
	v_lshlrev_b32_e32 v85, 2, v4
	v_xor_b32_e32 v4, 4, v2
	v_cmp_lt_i32_e32 vcc, v4, v3
	s_nop 1
	v_cndmask_b32_e32 v4, v2, v4, vcc
	v_lshlrev_b32_e32 v86, 2, v4
	v_xor_b32_e32 v4, 8, v2
	v_cmp_lt_i32_e32 vcc, v4, v3
	s_nop 1
	v_cndmask_b32_e32 v4, v2, v4, vcc
	v_lshlrev_b32_e32 v87, 2, v4
	v_xor_b32_e32 v4, 16, v2
	v_cmp_lt_i32_e32 vcc, v4, v3
	s_nop 1
	v_cndmask_b32_e32 v4, v2, v4, vcc
	v_lshlrev_b32_e32 v88, 2, v4
	v_xor_b32_e32 v4, 32, v2
	v_cmp_lt_i32_e32 vcc, v4, v3
	s_nop 1
	v_cndmask_b32_e32 v2, v2, v4, vcc
	v_lshlrev_b32_e32 v89, 2, v2
	v_lshl_add_u64 v[2:3], v[10:11], 0, s[0:1]
	s_mov_b64 s[0:1], 0x3000
	v_lshl_add_u64 v[4:5], v[10:11], 0, s[0:1]
	s_mov_b64 s[0:1], 0x3400
	v_lshl_add_u64 v[6:7], v[10:11], 0, s[0:1]
	s_mov_b64 s[0:1], 0x3800
	v_lshl_add_u64 v[8:9], v[10:11], 0, s[0:1]
	s_mov_b64 s[0:1], 0x3c00
	v_lshl_add_u64 v[10:11], v[10:11], 0, s[0:1]
	s_lshl_b64 s[0:1], s[2:3], 13
	s_add_u32 s0, s4, s0
	s_addc_u32 s1, s5, s1
	s_add_i32 s4, s2, s8
	v_lshl_add_u64 v[12:13], s[0:1], 0, v[12:13]
	s_mov_b64 s[0:1], 0x1000
	s_ashr_i32 s9, s8, 31
	s_ashr_i32 s5, s4, 31
	v_lshl_add_u64 v[12:13], v[12:13], 0, s[0:1]
	s_lshl_b64 s[0:1], s[8:9], 13
	s_lshl_b64 s[4:5], s[4:5], 12
	s_add_u32 s4, s6, s4
	s_addc_u32 s5, s7, s5
	v_lshl_add_u64 v[16:17], s[4:5], 0, v[16:17]
	v_lshl_add_u64 v[16:17], v[16:17], 0, s[10:11]
	s_lshl_b64 s[4:5], s[8:9], 12
	s_mov_b32 s3, 0x800000
	v_and_b32_e32 v119, 63, v1
	v_lshlrev_b32_e32 v119, 4, v119
	global_load_dwordx4 v[120:123], v[2:3], off
	global_load_dwordx4 v[124:127], v[2:3], off offset:1024
	global_load_dwordx4 v[128:131], v[2:3], off offset:2048
	global_load_dwordx4 v[132:135], v[2:3], off offset:3072
	global_load_dwordx4 v[136:139], v[4:5], off
	global_load_dwordx4 v[140:143], v[6:7], off
	global_load_dwordx4 v[144:147], v[8:9], off
	global_load_dwordx4 v[148:151], v[10:11], off
	s_waitcnt vmcnt(0)
	ds_write_b128 v119, v[120:123] offset:0
	ds_write_b128 v119, v[124:127] offset:1024
	ds_write_b128 v119, v[128:131] offset:2048
	ds_write_b128 v119, v[132:135] offset:3072
	ds_write_b128 v119, v[136:139] offset:4096
	ds_write_b128 v119, v[140:143] offset:5120
	ds_write_b128 v119, v[144:147] offset:6144
	ds_write_b128 v119, v[148:151] offset:7168
	s_waitcnt lgkmcnt(0)
	s_branch .LBB0_1460
; DI float lo_f(unsigned w) { return __uint_as_float(w << 16); }
; DI float hi_f(unsigned w) { return __uint_as_float(w & 0xffff0000u); }
; DI float wave_sum(float v) {
; #pragma unroll
;     for (int o = 1; o < 64; o <<= 1) v += __shfl_xor(v, o);
;     return v;
; template <int MODE, bool FIRST, bool LAST>
; DI void phase_rowpass(const float* xin, const bf16_t* M, const float* gpost, float* outf, bf16_t* HB, bf16_t* XN, const float* gnext, int gw, int NGW, int lane) {
;     ...
;         f32x4 hv[8], mv[8]; float ss = 0.f;
; #pragma unroll
;         for (int j = 0; j < 8; ++j) { const u32x2 w = mw[j]; mv[j] = (f32x4){lo_f(w.x), hi_f(w.x), lo_f(w.y), hi_f(w.y)};
;             if constexpr (FIRST) hv[j] = hc.f[j]; else { const u32x2 hw = hc.f[j]; hv[j] = (f32x4){lo_f(hw.x), hi_f(hw.x), lo_f(hw.y), hi_f(hw.y)}; }
;             ss += (mv[j][0] * mv[j][0] + mv[j][1] * mv[j][1]) + (mv[j][2] * mv[j][2] + mv[j][3] * mv[j][3]); }
;         const float rs = rsqrtf(wave_sum(ss) * (1.f / D_) + EPS);
;         float s2 = 0.f;
; #pragma unroll
;         for (int j = 0; j < 8; ++j) { const f32x4 gv = ((const f32x4*)gpost)[lane + 64 * j]; hv[j] = hv[j] + mv[j] * rs * gv;
.LBB0_1459:
	s_waitcnt vmcnt(0)
	v_and_b32_e32 v95, 0xffff0000, v78
	v_and_b32_e32 v94, 0xffff0000, v76
	v_and_b32_e32 v99, 0xffff0000, v79
	v_and_b32_e32 v98, 0xffff0000, v77
	v_and_b32_e32 v103, 0xffff0000, v75
	v_and_b32_e32 v102, 0xffff0000, v74
	v_lshlrev_b32_e32 v93, 16, v78
	v_lshlrev_b32_e32 v92, 16, v76
	v_lshlrev_b32_e32 v97, 16, v79
	v_lshlrev_b32_e32 v96, 16, v77
	v_pk_mul_f32 v[76:77], v[94:95], v[94:95]
	v_pk_mul_f32 v[78:79], v[98:99], v[98:99]
	v_lshlrev_b32_e32 v101, 16, v75
	v_lshlrev_b32_e32 v100, 16, v74
	v_pk_mul_f32 v[74:75], v[102:103], v[102:103]
	v_pk_fma_f32 v[76:77], v[92:93], v[92:93], v[76:77]
	v_pk_fma_f32 v[78:79], v[96:97], v[96:97], v[78:79]
	v_pk_fma_f32 v[74:75], v[100:101], v[100:101], v[74:75]
	v_lshlrev_b32_e32 v104, 16, v72
	v_and_b32_e32 v105, 0xffff0000, v72
	v_lshlrev_b32_e32 v72, 16, v73
	v_pk_add_f32 v[76:77], v[76:77], v[78:79]
	v_pk_add_f32 v[78:79], v[74:75], v[74:75] op_sel_hi:[0,1]
	v_mul_f32_e32 v75, v104, v104
	v_and_b32_e32 v73, 0xffff0000, v73
	v_mul_f32_e32 v74, v72, v72
	v_pk_fma_f32 v[82:83], v[72:73], v[72:73], v[74:75] op_sel_hi:[1,1,0]
	v_lshlrev_b32_e32 v74, 16, v70
	v_mul_f32_e32 v81, v105, v105
	v_mov_b32_e32 v80, v74
	v_pk_add_f32 v[76:77], v[76:77], v[76:77] op_sel_hi:[0,1]
	v_and_b32_e32 v91, 0xffff0000, v70
	v_lshlrev_b32_e32 v70, 16, v71
	v_and_b32_e32 v71, 0xffff0000, v71
	v_pk_add_f32 v[80:81], v[74:75], v[80:81]
	v_mul_f32_e32 v82, v91, v91
	v_mul_f32_e32 v78, v70, v70
	v_mul_f32_e32 v76, v71, v71
	v_mul_f32_e32 v106, v74, v74
	v_mov_b32_e32 v107, v81
	v_pk_add_f32 v[80:81], v[106:107], v[82:83]
	v_pk_add_f32 v[76:77], v[78:79], v[76:77]
	v_lshlrev_b32_e32 v109, 16, v69
	v_pk_add_f32 v[76:77], v[80:81], v[76:77]
	v_lshlrev_b32_e32 v108, 16, v68
	v_pk_add_f32 v[106:107], v[76:77], v[76:77] op_sel_hi:[0,1]
	ds_read_b128 v[76:79], v119 offset:0
	v_and_b32_e32 v69, 0xffff0000, v69
	v_and_b32_e32 v68, 0xffff0000, v68
	v_pk_mul_f32 v[80:81], v[68:69], v[68:69]
	v_lshlrev_b32_e32 v112, 16, v66
	v_pk_fma_f32 v[80:81], v[108:109], v[108:109], v[80:81]
	v_and_b32_e32 v113, 0xffff0000, v66
	v_lshlrev_b32_e32 v66, 16, v67
	v_pk_add_f32 v[110:111], v[80:81], v[80:81] op_sel_hi:[0,1]
	v_mul_f32_e32 v81, v112, v112
	v_and_b32_e32 v67, 0xffff0000, v67
	v_mul_f32_e32 v80, v66, v66
	v_pk_fma_f32 v[116:117], v[66:67], v[66:67], v[80:81] op_sel_hi:[1,1,0]
	v_lshlrev_b32_e32 v80, 16, v64
	v_mul_f32_e32 v115, v113, v113
	v_mov_b32_e32 v114, v80
	v_and_b32_e32 v118, 0xffff0000, v64
	v_lshlrev_b32_e32 v82, 16, v65
	v_and_b32_e32 v83, 0xffff0000, v65
	v_pk_add_f32 v[114:115], v[80:81], v[114:115]
	v_mul_f32_e32 v116, v118, v118
	v_mul_f32_e32 v110, v82, v82
	v_mul_f32_e32 v106, v83, v83
	v_mul_f32_e32 v64, v80, v80
	v_mov_b32_e32 v65, v115
	v_pk_add_f32 v[64:65], v[64:65], v[116:117]
	v_pk_add_f32 v[106:107], v[110:111], v[106:107]
	v_mov_b32_e32 v75, v91
	v_pk_add_f32 v[64:65], v[64:65], v[106:107]
	v_lshlrev_b32_e32 v106, 16, v62
	v_add_f32_e32 v64, v64, v65
	ds_bpermute_b32 v65, v84, v64
	v_and_b32_e32 v107, 0xffff0000, v62
	v_lshlrev_b32_e32 v62, 16, v63
	v_and_b32_e32 v63, 0xffff0000, v63
	v_mov_b32_e32 v81, v118
	s_waitcnt lgkmcnt(0)
	v_add_f32_e32 v64, v64, v65
	ds_bpermute_b32 v65, v85, v64
	v_lshl_add_u64 v[16:17], v[16:17], 0, s[4:5]
	s_waitcnt lgkmcnt(0)
	v_add_f32_e32 v64, v64, v65
	ds_bpermute_b32 v65, v86, v64
	s_waitcnt lgkmcnt(0)
	v_add_f32_e32 v64, v64, v65
	ds_bpermute_b32 v65, v87, v64
	s_waitcnt lgkmcnt(0)
	v_add_f32_e32 v64, v64, v65
	ds_bpermute_b32 v65, v88, v64
	s_waitcnt lgkmcnt(0)
	v_add_f32_e32 v64, v64, v65
	ds_bpermute_b32 v65, v89, v64
	s_waitcnt lgkmcnt(0)
	v_add_f32_e32 v64, v64, v65
	v_fmamk_f32 v64, v64, 0x3a000000, v90
	v_mul_f32_e32 v65, 0x4b800000, v64
	v_cmp_gt_f32_e32 vcc, s3, v64
	s_nop 1
	v_cndmask_b32_e32 v64, v64, v65, vcc
	v_rsq_f32_e32 v64, v64
	s_nop 0
	v_mul_f32_e32 v65, 0x45800000, v64
	v_cndmask_b32_e32 v110, v64, v65, vcc
	v_mov_b32_e32 v64, v93
	v_mov_b32_e32 v65, v95
	v_pk_mul_f32 v[114:115], v[64:65], v[110:111] op_sel_hi:[1,0]
	v_mov_b32_e32 v64, v97
	v_mov_b32_e32 v65, v99
	v_pk_mul_f32 v[64:65], v[64:65], v[110:111] op_sel_hi:[1,0]
	v_mov_b32_e32 v97, v98
	s_waitcnt vmcnt(0) lgkmcnt(0)
; DI unsigned pk2(float lo, float hi) { return f2bf(lo) | (f2bf(hi) << 16); }
; template <int MODE, bool FIRST, bool LAST>
; DI void phase_rowpass(const float* xin, const bf16_t* M, const float* gpost, float* outf, bf16_t* HB, bf16_t* XN, const float* gnext, int gw, int NGW, int lane) {
;     ...
; #pragma unroll
;         for (int j = 0; j < 8; ++j) { const f32x4 gv = ((const f32x4*)gpost)[lane + 64 * j]; hv[j] = hv[j] + mv[j] * rs * gv;
;             if constexpr (LAST) ((f32x4*)(outf + (size_t)row * D_) + lane)[64 * j] = hv[j];
;             else { u32x2 w; w.x = pk2(hv[j][0], hv[j][1]); w.y = pk2(hv[j][2], hv[j][3]); ((u32x2*)(HB + (size_t)row * D_) + lane)[64 * j] = w; }
;             s2 += (hv[j][0] * hv[j][0] + hv[j][1] * hv[j][1]) + (hv[j][2] * hv[j][2] + hv[j][3] * hv[j][3]); }
	v_pk_fma_f32 v[64:65], v[78:79], v[64:65], v[62:63]
	v_pk_fma_f32 v[62:63], v[76:77], v[114:115], v[106:107]
	global_store_dwordx4 v[12:13], v[62:65], off offset:-4096
	s_nop 0
	ds_read_b128 v[62:65], v119 offset:1024
	v_mov_b32_e32 v93, v94
	v_lshlrev_b32_e32 v76, 16, v60
	v_and_b32_e32 v77, 0xffff0000, v60
	v_lshlrev_b32_e32 v78, 16, v61
	v_and_b32_e32 v79, 0xffff0000, v61
	v_pk_mul_f32 v[94:95], v[96:97], v[110:111] op_sel_hi:[1,0]
	v_pk_mul_f32 v[60:61], v[92:93], v[110:111] op_sel_hi:[1,0]
	v_pk_mul_f32 v[72:73], v[72:73], v[110:111] op_sel_hi:[1,0]
	v_lshlrev_b32_e32 v96, 16, v14
	v_and_b32_e32 v97, 0xffff0000, v14
	v_lshlrev_b32_e32 v14, 16, v15
	v_and_b32_e32 v15, 0xffff0000, v15
	v_pk_mul_f32 v[82:83], v[82:83], v[110:111] op_sel_hi:[1,0]
	v_pk_mul_f32 v[80:81], v[80:81], v[110:111] op_sel_hi:[1,0]
	s_andn2_b64 vcc, exec, s[6:7]
	s_waitcnt lgkmcnt(0)
	v_pk_fma_f32 v[60:61], v[62:63], v[60:61], v[76:77]
	v_pk_fma_f32 v[62:63], v[64:65], v[94:95], v[78:79]
	global_store_dwordx4 v[12:13], v[60:63], off offset:-3072
	s_nop 0
	ds_read_b128 v[60:63], v119 offset:2048
	v_lshlrev_b32_e32 v64, 16, v58
	v_and_b32_e32 v65, 0xffff0000, v58
	v_lshlrev_b32_e32 v76, 16, v59
	v_and_b32_e32 v77, 0xffff0000, v59
	v_mov_b32_e32 v58, v101
	v_mov_b32_e32 v59, v103
	v_mov_b32_e32 v101, v102
	v_pk_mul_f32 v[78:79], v[110:111], v[58:59] op_sel_hi:[0,1]
	v_pk_mul_f32 v[58:59], v[110:111], v[100:101] op_sel_hi:[0,1]
	s_waitcnt lgkmcnt(0)
	v_pk_fma_f32 v[58:59], v[60:61], v[58:59], v[64:65]
	v_pk_fma_f32 v[60:61], v[62:63], v[78:79], v[76:77]
	global_store_dwordx4 v[12:13], v[58:61], off offset:-2048
	s_nop 0
	ds_read_b128 v[58:61], v119 offset:3072
	v_lshlrev_b32_e32 v62, 16, v56
	v_and_b32_e32 v63, 0xffff0000, v56
	v_lshlrev_b32_e32 v64, 16, v57
	v_and_b32_e32 v65, 0xffff0000, v57
	v_pk_mul_f32 v[56:57], v[104:105], v[110:111] op_sel_hi:[1,0]
	v_mov_b64_e32 v[76:77], v[44:45]
	v_mov_b64_e32 v[78:79], v[46:47]
	s_waitcnt lgkmcnt(0)
	v_pk_fma_f32 v[56:57], v[58:59], v[56:57], v[62:63]
	v_pk_fma_f32 v[58:59], v[60:61], v[72:73], v[64:65]
	global_store_dwordx4 v[12:13], v[56:59], off offset:-1024
	s_nop 0
	ds_read_b128 v[56:59], v119 offset:4096
	v_lshlrev_b32_e32 v60, 16, v38
	v_and_b32_e32 v61, 0xffff0000, v38
	v_lshlrev_b32_e32 v38, 16, v39
	v_and_b32_e32 v39, 0xffff0000, v39
	v_pk_mul_f32 v[62:63], v[70:71], v[110:111] op_sel_hi:[1,0]
	v_pk_mul_f32 v[64:65], v[74:75], v[110:111] op_sel_hi:[1,0]
	v_mov_b64_e32 v[70:71], v[52:53]
	v_mov_b64_e32 v[72:73], v[40:41]
	v_mov_b64_e32 v[74:75], v[42:43]
	s_waitcnt lgkmcnt(0)
	v_pk_fma_f32 v[56:57], v[56:57], v[64:65], v[60:61]
	v_pk_fma_f32 v[58:59], v[58:59], v[62:63], v[38:39]
	global_store_dwordx4 v[12:13], v[56:59], off
	s_nop 0
	ds_read_b128 v[56:59], v119 offset:5120
	v_mov_b32_e32 v60, v109
	v_mov_b32_e32 v61, v69
	v_mov_b32_e32 v109, v68
	v_lshlrev_b32_e32 v38, 16, v20
	v_and_b32_e32 v39, 0xffff0000, v20
	v_lshlrev_b32_e32 v20, 16, v21
	v_and_b32_e32 v21, 0xffff0000, v21
	v_pk_mul_f32 v[60:61], v[110:111], v[60:61] op_sel_hi:[0,1]
	v_pk_mul_f32 v[62:63], v[110:111], v[108:109] op_sel_hi:[0,1]
	v_mov_b64_e32 v[64:65], v[54:55]
	v_mov_b64_e32 v[68:69], v[50:51]
	s_waitcnt lgkmcnt(0)
	v_pk_fma_f32 v[56:57], v[56:57], v[62:63], v[38:39]
	v_pk_fma_f32 v[58:59], v[58:59], v[60:61], v[20:21]
	global_store_dwordx4 v[12:13], v[56:59], off offset:1024
	s_nop 0
	ds_read_b128 v[56:59], v119 offset:6144
	v_lshlrev_b32_e32 v20, 16, v18
	v_and_b32_e32 v21, 0xffff0000, v18
	v_lshlrev_b32_e32 v38, 16, v19
	v_and_b32_e32 v39, 0xffff0000, v19
	v_pk_mul_f32 v[60:61], v[66:67], v[110:111] op_sel_hi:[1,0]
	v_pk_mul_f32 v[18:19], v[112:113], v[110:111] op_sel_hi:[1,0]
	v_mov_b64_e32 v[66:67], v[48:49]
	v_mov_b64_e32 v[62:63], v[22:23]
	s_waitcnt lgkmcnt(0)
	v_pk_fma_f32 v[18:19], v[18:19], v[56:57], v[20:21]
	v_pk_fma_f32 v[20:21], v[60:61], v[58:59], v[38:39]
	global_store_dwordx4 v[12:13], v[18:21], off offset:2048
	s_nop 0
	ds_read_b128 v[92:95], v119 offset:7168
	v_mov_b64_e32 v[60:61], v[24:25]
	v_mov_b64_e32 v[58:59], v[26:27]
	v_mov_b64_e32 v[56:57], v[28:29]
	v_mov_b64_e32 v[38:39], v[30:31]
	v_mov_b64_e32 v[20:21], v[32:33]
	v_mov_b64_e32 v[18:19], v[34:35]
	s_waitcnt vmcnt(0) lgkmcnt(0)
	v_pk_fma_f32 v[80:81], v[80:81], v[92:93], v[96:97]
	v_pk_fma_f32 v[82:83], v[82:83], v[94:95], v[14:15]
	global_store_dwordx4 v[12:13], v[80:83], off offset:3072
	v_lshl_add_u64 v[12:13], v[12:13], 0, s[0:1]
	v_mov_b64_e32 v[14:15], v[36:37]
	s_cbranch_vccz .LBB0_1462
